# K-loop s_setprio flips deleted, static s_setprio 1 for waves 0-3 (repeat)
# speedup vs baseline: 1.0181x; 1.0002x over previous
; #define LAS __attribute__((address_space(3)))
; __global__ void __launch_bounds__(NTHR, 2) fwd_megakernel(Params P) {
;     extern __shared__ __attribute__((aligned(16))) unsigned char lds_raw[];
;     LAS unsigned char* lds = (LAS unsigned char*)lds_raw;
;     cg::grid_group grid = cg::this_grid();
;     const int G = gridDim.x, bid = blockIdx.x;
;     unsigned char* ws = P.ws;
;     bf16_t* WT = (bf16_t*)(ws + WS_WT); bf16_t* PB = (bf16_t*)(ws + WS_PB); bf16_t* U = (bf16_t*)(ws + WS_U); float* LSE = (float*)(ws + WS_LSE);
;     unsigned char* AR = ws + WS_AR;
;     bf16_t* QKV = (bf16_t*)(AR + AR_QKV); bf16_t* GATES = (bf16_t*)(AR + AR_GATES); bf16_t* MIX = (bf16_t*)(AR + AR_MIX);
;     bf16_t* RAWUP = (bf16_t*)(AR + AR_RAWUP); bf16_t* ACT = (bf16_t*)(AR + AR_ACT); bf16_t* FB = (bf16_t*)(AR + AR_F); bf16_t* EB = (bf16_t*)(AR + AR_E);
;     const float* x = P.in[0]; const float* p = P.in[1];
;     float* H = P.out;
;     volatile LAS unsigned* xb_st = (volatile LAS unsigned*)(lds + LDS_BYTES - 16);
;     if (threadIdx.x == 0) { xb_st[0] = 0u; xb_st[1] = 0u; }
;     __syncthreads();
;     const XcdBarrier xbar = xcd_barrier_post((unsigned*)(ws + WS_BAR), xb_st);
_Z14fwd_megakernel6Params:
	v_readfirstlane_b32 s12, v0
	s_nop 3
	s_lshr_b32 s12, s12, 6
	s_cmp_lt_u32 s12, 4
	s_cbranch_scc0 .Lprio_done
	s_setprio 1
.Lprio_done:
	s_load_dword s12, s[0:1], 0x98
	s_load_dwordx4 s[76:79], s[0:1], 0x80
	s_load_dwordx2 s[80:81], s[0:1], 0x90
	s_mov_b32 s75, s2
	s_add_u32 s2, s0, 0x90
	s_addc_u32 s3, s1, 0
	v_and_b32_e32 v230, 0x3ff, v0
	v_writelane_b32 v250, s2, 0
	v_cmp_eq_u32_e64 s[4:5], 0, v230
	s_nop 0
	v_writelane_b32 v250, s3, 1
	s_mov_b64 s[2:3], exec
	v_writelane_b32 v250, s4, 2
	s_nop 1
	v_writelane_b32 v250, s5, 3
	s_and_b64 s[4:5], s[2:3], s[4:5]
	s_mov_b64 exec, s[4:5]
	s_cbranch_execz .LBB0_2
	s_add_i32 s4, 0, 0x22ff0
	v_mov_b32_e32 v1, 0
	v_mov_b32_e32 v2, s4
	s_add_i32 s4, 0, 0x22ff4
	ds_write_b32 v2, v1
	v_mov_b32_e32 v2, s4
	ds_write_b32 v2, v1

; #define PG8_STAGE(bufoff, gbase, voff) do { _Pragma("unroll") for (int _i = 0; _i < 2; ++_i) \
;         __builtin_amdgcn_global_load_lds((const unsigned*)((const char*)(gbase) + (voff)[_i]), (LAS unsigned*)(lds + (bufoff) + ldsw + _i * 8192), 16, 0, 0); } while (0)
; #define PG8_LDA(dst, b, h) do { _Pragma("unroll") for (int m = 0; m < 4; ++m) _Pragma("unroll") for (int k = 0; k < 2; ++k) dst[m][k] = *(const LAS bf16x8*)(lds + PG8_SA(b, h) + aoff + m * 2048 + k * 1024); } while (0)
; #define PG8_LDB(dst, b, h) do { _Pragma("unroll") for (int n = 0; n < 2; ++n) _Pragma("unroll") for (int k = 0; k < 2; ++k) dst[n][k] = *(const LAS bf16x8*)(lds + PG8_SB(b, h) + boff + n * 2048 + k * 1024); } while (0)
; #define PG8_MMA(ai, bj, At, Bt) do { __builtin_amdgcn_s_setprio(1); _Pragma("unroll") for (int m = 0; m < 4; ++m) _Pragma("unroll") for (int n = 0; n < 2; ++n) _Pragma("unroll") for (int k = 0; k < 2; ++k) \
;         acc[ai][bj][m][n] = __builtin_amdgcn_mfma_f32_16x16x32_bf16(Bt[n][k], At[m][k], acc[ai][bj][m][n], 0, 0, 0); __builtin_amdgcn_s_setprio(0); } while (0)
; #define PG8_WAIT_V(n) asm volatile("s_waitcnt vmcnt(" #n ")" ::: "memory")
; #define PG8_WAIT_L(n) asm volatile("s_waitcnt lgkmcnt(" #n ")" ::: "memory")
; template <class Epi, bool PERMA = false, bool DUAL = false, bool ALIGN_EPI = true, bool SP2 = true>
; __device__ __forceinline__ void gemm_phase(LAS unsigned char* lds, const Gemm g, const StaticOrder& S, const Epi& E) {
;     ...
;         for (int t = 0; t < nt; t += 2) {
;             const bool last = (t == nt - 2);
;             const char* a1 = cA + (size_t)(t + 1) * kstep;
;             const char* a2 = last ? nA : cA + (size_t)(t + 2) * kstep; const char* b2 = last ? nB : cB + (size_t)(t + 2) * kstep;
;             const char* a3 = a2 + kstep; const char* b3 = b2 + kstep;
;             if constexpr (SP2) {
;             PG8_LDB(B0, 0, 0); PG8_LDB(B1, 0, 1); PG8_SCHED; PG8_LDA(At, 0, 0); PG8_STAGE(PG8_SA(1, 1), a1 + hstepA, voffA);
;             PG8_WAIT_V(8); PG8_WAIT_L(0); PG8_BAR; PG8_MMA(0, 0, At, B0); PG8_MMA(0, 1, At, B1); PG8_BAR; PG8_SCHED;
;             PG8_LDA(At, 0, 1); PG8_STAGE(PG8_SB(0, 0), b2, voffB); PG8_STAGE(PG8_SB(0, 1), b2 + hstepB, voffB); PG8_STAGE(PG8_SA(0, 0), a2, voffA);
;             PG8_WAIT_V(8); PG8_WAIT_L(0); PG8_BAR; PG8_MMA(1, 0, At, B0); PG8_MMA(1, 1, At, B1); PG8_BAR; PG8_SCHED;
.LBB0_130:
	s_add_u32 s16, s14, 0xfff80080
	s_addc_u32 s17, s15, -1
	s_add_i32 s38, 0, 0x10000
	s_cmp_eq_u32 s37, 28
	s_cselect_b32 s19, s9, s17
	s_cselect_b32 s18, s33, s16
	s_cselect_b32 s17, s7, s36
	s_cselect_b32 s16, s34, s35
	s_add_i32 s40, 0, 0x14000
	v_add_u32_e32 v156, s38, v141
	v_add_u32_e32 v172, s40, v141
	ds_read_b128 v[144:147], v156
	ds_read_b128 v[148:151], v156 offset:1024
	ds_read_b128 v[152:155], v156 offset:2048
	ds_read_b128 v[156:159], v156 offset:3072
	ds_read_b128 v[160:163], v172
	ds_read_b128 v[164:167], v172 offset:1024
	ds_read_b128 v[168:171], v172 offset:2048
	ds_read_b128 v[172:175], v172 offset:3072
	v_lshl_add_u64 v[222:223], s[14:15], 0, v[136:137]
	s_add_i32 m0, s21, 0xc000
	ds_read_b128 v[176:179], v143
	ds_read_b128 v[180:183], v143 offset:1024
	ds_read_b128 v[184:187], v143 offset:2048
	ds_read_b128 v[188:191], v143 offset:3072
	ds_read_b128 v[206:209], v143 offset:4096
	ds_read_b128 v[210:213], v143 offset:5120
	ds_read_b128 v[214:217], v143 offset:6144
	ds_read_b128 v[218:221], v143 offset:7168
	global_load_lds_dwordx4 v[222:223], off
	v_lshl_add_u64 v[222:223], s[14:15], 0, v[138:139]
	s_add_i32 m0, s21, 0xe000
	s_nop 0
	global_load_lds_dwordx4 v[222:223], off
	s_waitcnt vmcnt(8)
	s_waitcnt lgkmcnt(0)
	s_barrier
	s_waitcnt lgkmcnt(0)
	v_mfma_f32_16x16x32_bf16 v[124:127], v[144:147], v[176:179], v[124:127]
	v_mfma_f32_16x16x32_bf16 v[120:123], v[152:155], v[176:179], v[120:123]
	v_mfma_f32_16x16x32_bf16 v[116:119], v[144:147], v[184:187], v[116:119]
	v_mfma_f32_16x16x32_bf16 v[108:111], v[152:155], v[184:187], v[108:111]
	v_mfma_f32_16x16x32_bf16 v[100:103], v[144:147], v[206:209], v[100:103]
	v_mfma_f32_16x16x32_bf16 v[92:95], v[152:155], v[206:209], v[92:95]
	v_mfma_f32_16x16x32_bf16 v[84:87], v[144:147], v[214:217], v[84:87]
	v_mfma_f32_16x16x32_bf16 v[76:79], v[152:155], v[214:217], v[76:79]
	v_mfma_f32_16x16x32_bf16 v[124:127], v[148:151], v[180:183], v[124:127]
	v_mfma_f32_16x16x32_bf16 v[120:123], v[156:159], v[180:183], v[120:123]
	v_mfma_f32_16x16x32_bf16 v[116:119], v[148:151], v[188:191], v[116:119]
	v_mfma_f32_16x16x32_bf16 v[108:111], v[156:159], v[188:191], v[108:111]
	v_mfma_f32_16x16x32_bf16 v[100:103], v[148:151], v[210:213], v[100:103]
	v_mfma_f32_16x16x32_bf16 v[92:95], v[156:159], v[210:213], v[92:95]
	v_mfma_f32_16x16x32_bf16 v[84:87], v[148:151], v[218:221], v[84:87]
	v_mfma_f32_16x16x32_bf16 v[76:79], v[156:159], v[218:221], v[76:79]
	v_mfma_f32_16x16x32_bf16 v[112:115], v[160:163], v[176:179], v[112:115]
	v_mfma_f32_16x16x32_bf16 v[104:107], v[168:171], v[176:179], v[104:107]
	v_mfma_f32_16x16x32_bf16 v[96:99], v[160:163], v[184:187], v[96:99]
	v_mfma_f32_16x16x32_bf16 v[88:91], v[168:171], v[184:187], v[88:91]
	v_mfma_f32_16x16x32_bf16 v[80:83], v[160:163], v[206:209], v[80:83]
	v_mfma_f32_16x16x32_bf16 v[72:75], v[168:171], v[206:209], v[72:75]
	v_mfma_f32_16x16x32_bf16 v[68:71], v[160:163], v[214:217], v[68:71]
	v_mfma_f32_16x16x32_bf16 v[64:67], v[168:171], v[214:217], v[64:67]
	v_mfma_f32_16x16x32_bf16 v[112:115], v[164:167], v[180:183], v[112:115]
	v_mfma_f32_16x16x32_bf16 v[104:107], v[172:175], v[180:183], v[104:107]
	v_mfma_f32_16x16x32_bf16 v[96:99], v[164:167], v[188:191], v[96:99]
	v_mfma_f32_16x16x32_bf16 v[88:91], v[172:175], v[188:191], v[88:91]
	v_mfma_f32_16x16x32_bf16 v[80:83], v[164:167], v[210:213], v[80:83]
	v_mfma_f32_16x16x32_bf16 v[72:75], v[172:175], v[210:213], v[72:75]
	v_mfma_f32_16x16x32_bf16 v[68:71], v[164:167], v[218:221], v[68:71]
	v_mfma_f32_16x16x32_bf16 v[64:67], v[172:175], v[218:221], v[64:67]
	s_barrier
	s_add_i32 s38, s38, s20
	v_lshl_add_u64 v[222:223], s[16:17], 0, v[132:133]
	s_mov_b32 m0, s38
	ds_read_b128 v[176:179], v143 offset:16384
	ds_read_b128 v[180:183], v143 offset:17408
	ds_read_b128 v[184:187], v143 offset:18432
	ds_read_b128 v[188:191], v143 offset:19456
	ds_read_b128 v[206:209], v143 offset:20480
	ds_read_b128 v[210:213], v143 offset:21504
	ds_read_b128 v[214:217], v143 offset:22528
	ds_read_b128 v[218:221], v143 offset:23552
	global_load_lds_dwordx4 v[222:223], off
	s_add_i32 m0, s38, 0x2000
	s_add_u32 s38, s16, 0x80000
	v_lshl_add_u64 v[224:225], s[16:17], 0, v[128:129]
	s_addc_u32 s39, s17, 0
	s_add_i32 s40, s40, s20
	global_load_lds_dwordx4 v[224:225], off
	v_lshl_add_u64 v[226:227], s[38:39], 0, v[132:133]
	s_mov_b32 m0, s40
	v_lshl_add_u64 v[228:229], s[18:19], 0, v[130:131]
	global_load_lds_dwordx4 v[226:227], off
	v_lshl_add_u64 v[226:227], s[38:39], 0, v[128:129]
	s_add_i32 m0, s40, 0x2000
	s_nop 0
	global_load_lds_dwordx4 v[226:227], off
	v_lshl_add_u64 v[226:227], s[18:19], 0, v[134:135]
	s_mov_b32 m0, s21
	s_nop 0
	global_load_lds_dwordx4 v[226:227], off
	s_mov_b32 m0, s22
	s_nop 0
	global_load_lds_dwordx4 v[228:229], off
	s_waitcnt vmcnt(8)
	s_waitcnt lgkmcnt(0)
	s_barrier
; #define PG8_STAGE(bufoff, gbase, voff) do { _Pragma("unroll") for (int _i = 0; _i < 2; ++_i) \
;         __builtin_amdgcn_global_load_lds((const unsigned*)((const char*)(gbase) + (voff)[_i]), (LAS unsigned*)(lds + (bufoff) + ldsw + _i * 8192), 16, 0, 0); } while (0)
; #define PG8_LDA(dst, b, h) do { _Pragma("unroll") for (int m = 0; m < 4; ++m) _Pragma("unroll") for (int k = 0; k < 2; ++k) dst[m][k] = *(const LAS bf16x8*)(lds + PG8_SA(b, h) + aoff + m * 2048 + k * 1024); } while (0)
; #define PG8_LDB(dst, b, h) do { _Pragma("unroll") for (int n = 0; n < 2; ++n) _Pragma("unroll") for (int k = 0; k < 2; ++k) dst[n][k] = *(const LAS bf16x8*)(lds + PG8_SB(b, h) + boff + n * 2048 + k * 1024); } while (0)
; #define PG8_MMA(ai, bj, At, Bt) do { __builtin_amdgcn_s_setprio(1); _Pragma("unroll") for (int m = 0; m < 4; ++m) _Pragma("unroll") for (int n = 0; n < 2; ++n) _Pragma("unroll") for (int k = 0; k < 2; ++k) \
;         acc[ai][bj][m][n] = __builtin_amdgcn_mfma_f32_16x16x32_bf16(Bt[n][k], At[m][k], acc[ai][bj][m][n], 0, 0, 0); __builtin_amdgcn_s_setprio(0); } while (0)
; #define PG8_WAIT_V(n) asm volatile("s_waitcnt vmcnt(" #n ")" ::: "memory")
; #define PG8_WAIT_L(n) asm volatile("s_waitcnt lgkmcnt(" #n ")" ::: "memory")
; template <class Epi, bool PERMA = false, bool DUAL = false, bool ALIGN_EPI = true, bool SP2 = true>
; __device__ __forceinline__ void gemm_phase(LAS unsigned char* lds, const Gemm g, const StaticOrder& S, const Epi& E) {
;     ...
;             PG8_WAIT_V(8); PG8_WAIT_L(0); PG8_BAR; PG8_MMA(0, 0, At, B0); PG8_MMA(0, 1, At, B1); PG8_BAR; PG8_SCHED;
;             PG8_LDA(At, 0, 1); PG8_STAGE(PG8_SB(0, 0), b2, voffB); PG8_STAGE(PG8_SB(0, 1), b2 + hstepB, voffB); PG8_STAGE(PG8_SA(0, 0), a2, voffA);
;             PG8_WAIT_V(8); PG8_WAIT_L(0); PG8_BAR; PG8_MMA(1, 0, At, B0); PG8_MMA(1, 1, At, B1); PG8_BAR; PG8_SCHED;
;             PG8_LDB(B0, 1, 0); PG8_LDB(B1, 1, 1); PG8_SCHED; PG8_LDA(At, 1, 0); PG8_STAGE(PG8_SA(0, 1), a2 + hstepA, voffA);
;             PG8_WAIT_V(8); PG8_WAIT_L(0); PG8_BAR; PG8_MMA(0, 0, At, B0); PG8_MMA(0, 1, At, B1); PG8_BAR; PG8_SCHED;
;             PG8_LDA(At, 1, 1); PG8_STAGE(PG8_SB(1, 0), b3, voffB); PG8_STAGE(PG8_SB(1, 1), b3 + hstepB, voffB); PG8_STAGE(PG8_SA(1, 0), a3, voffA);
;             PG8_WAIT_V(8); PG8_WAIT_L(0); PG8_BAR; PG8_MMA(1, 0, At, B0); PG8_MMA(1, 1, At, B1); PG8_BAR; PG8_SCHED;
	s_waitcnt lgkmcnt(0)
	v_mfma_f32_16x16x32_bf16 v[60:63], v[144:147], v[176:179], v[60:63]
	v_mfma_f32_16x16x32_bf16 v[56:59], v[152:155], v[176:179], v[56:59]
	v_mfma_f32_16x16x32_bf16 v[52:55], v[144:147], v[184:187], v[52:55]
	v_mfma_f32_16x16x32_bf16 v[44:47], v[152:155], v[184:187], v[44:47]
	v_mfma_f32_16x16x32_bf16 v[36:39], v[144:147], v[206:209], v[36:39]
	v_mfma_f32_16x16x32_bf16 v[28:31], v[152:155], v[206:209], v[28:31]
	v_mfma_f32_16x16x32_bf16 v[20:23], v[144:147], v[214:217], v[20:23]
	v_mfma_f32_16x16x32_bf16 v[12:15], v[152:155], v[214:217], v[12:15]
	v_mfma_f32_16x16x32_bf16 v[60:63], v[148:151], v[180:183], v[60:63]
	v_mfma_f32_16x16x32_bf16 v[56:59], v[156:159], v[180:183], v[56:59]
	v_mfma_f32_16x16x32_bf16 v[52:55], v[148:151], v[188:191], v[52:55]
	v_mfma_f32_16x16x32_bf16 v[44:47], v[156:159], v[188:191], v[44:47]
	v_mfma_f32_16x16x32_bf16 v[36:39], v[148:151], v[210:213], v[36:39]
	v_mfma_f32_16x16x32_bf16 v[28:31], v[156:159], v[210:213], v[28:31]
	v_mfma_f32_16x16x32_bf16 v[20:23], v[148:151], v[218:221], v[20:23]
	v_mfma_f32_16x16x32_bf16 v[12:15], v[156:159], v[218:221], v[12:15]
	v_mfma_f32_16x16x32_bf16 v[48:51], v[160:163], v[176:179], v[48:51]
	v_mfma_f32_16x16x32_bf16 v[40:43], v[168:171], v[176:179], v[40:43]
	v_mfma_f32_16x16x32_bf16 v[32:35], v[160:163], v[184:187], v[32:35]
	v_mfma_f32_16x16x32_bf16 v[24:27], v[168:171], v[184:187], v[24:27]
	v_mfma_f32_16x16x32_bf16 v[16:19], v[160:163], v[206:209], v[16:19]
	v_mfma_f32_16x16x32_bf16 v[8:11], v[168:171], v[206:209], v[8:11]
	v_mfma_f32_16x16x32_bf16 v[4:7], v[160:163], v[214:217], v[4:7]
	v_mfma_f32_16x16x32_bf16 v[0:3], v[168:171], v[214:217], v[0:3]
	v_mfma_f32_16x16x32_bf16 v[48:51], v[164:167], v[180:183], v[48:51]
	v_mfma_f32_16x16x32_bf16 v[40:43], v[172:175], v[180:183], v[40:43]
	v_mfma_f32_16x16x32_bf16 v[32:35], v[164:167], v[188:191], v[32:35]
	v_mfma_f32_16x16x32_bf16 v[24:27], v[172:175], v[188:191], v[24:27]
	v_mfma_f32_16x16x32_bf16 v[16:19], v[164:167], v[210:213], v[16:19]
	v_mfma_f32_16x16x32_bf16 v[8:11], v[172:175], v[210:213], v[8:11]
	v_mfma_f32_16x16x32_bf16 v[4:7], v[164:167], v[218:221], v[4:7]
	v_mfma_f32_16x16x32_bf16 v[0:3], v[172:175], v[218:221], v[0:3]
	s_barrier
	s_add_i32 s38, 0, 0x18000
	s_add_i32 s39, 0, 0x1c000
	v_add_u32_e32 v156, s38, v141
	v_add_u32_e32 v172, s39, v141
	ds_read_b128 v[144:147], v156
	ds_read_b128 v[148:151], v156 offset:1024
	ds_read_b128 v[152:155], v156 offset:2048
	ds_read_b128 v[156:159], v156 offset:3072
	ds_read_b128 v[160:163], v172
	ds_read_b128 v[164:167], v172 offset:1024
	ds_read_b128 v[168:171], v172 offset:2048
	ds_read_b128 v[172:175], v172 offset:3072
	s_add_u32 s18, s18, 0x80000
	s_addc_u32 s19, s19, 0
	s_mov_b32 m0, s23
	v_lshl_add_u64 v[238:239], s[18:19], 0, v[134:135]
	ds_read_b128 v[176:179], v143 offset:32768
	ds_read_b128 v[180:183], v143 offset:33792
	ds_read_b128 v[184:187], v143 offset:34816
	ds_read_b128 v[188:191], v143 offset:35840
	ds_read_b128 v[206:209], v143 offset:36864
	ds_read_b128 v[210:213], v143 offset:37888
	ds_read_b128 v[214:217], v143 offset:38912
	ds_read_b128 v[218:221], v143 offset:39936
	global_load_lds_dwordx4 v[238:239], off
	v_lshl_add_u64 v[238:239], s[18:19], 0, v[130:131]
	s_mov_b32 m0, s24
	s_nop 0
	global_load_lds_dwordx4 v[238:239], off
	s_waitcnt vmcnt(8)
	s_waitcnt lgkmcnt(0)
	s_barrier
	s_waitcnt lgkmcnt(0)
	v_mfma_f32_16x16x32_bf16 v[124:127], v[144:147], v[176:179], v[124:127]
	v_mfma_f32_16x16x32_bf16 v[120:123], v[152:155], v[176:179], v[120:123]
	v_mfma_f32_16x16x32_bf16 v[116:119], v[144:147], v[184:187], v[116:119]
	v_mfma_f32_16x16x32_bf16 v[108:111], v[152:155], v[184:187], v[108:111]
	v_mfma_f32_16x16x32_bf16 v[100:103], v[144:147], v[206:209], v[100:103]
	v_mfma_f32_16x16x32_bf16 v[92:95], v[152:155], v[206:209], v[92:95]
	v_mfma_f32_16x16x32_bf16 v[84:87], v[144:147], v[214:217], v[84:87]
	v_mfma_f32_16x16x32_bf16 v[76:79], v[152:155], v[214:217], v[76:79]
	v_mfma_f32_16x16x32_bf16 v[124:127], v[148:151], v[180:183], v[124:127]
	v_mfma_f32_16x16x32_bf16 v[120:123], v[156:159], v[180:183], v[120:123]
	v_mfma_f32_16x16x32_bf16 v[116:119], v[148:151], v[188:191], v[116:119]
	v_mfma_f32_16x16x32_bf16 v[108:111], v[156:159], v[188:191], v[108:111]
	v_mfma_f32_16x16x32_bf16 v[100:103], v[148:151], v[210:213], v[100:103]
	v_mfma_f32_16x16x32_bf16 v[92:95], v[156:159], v[210:213], v[92:95]
	v_mfma_f32_16x16x32_bf16 v[84:87], v[148:151], v[218:221], v[84:87]
	v_mfma_f32_16x16x32_bf16 v[76:79], v[156:159], v[218:221], v[76:79]
	v_mfma_f32_16x16x32_bf16 v[112:115], v[160:163], v[176:179], v[112:115]
	v_mfma_f32_16x16x32_bf16 v[104:107], v[168:171], v[176:179], v[104:107]
	v_mfma_f32_16x16x32_bf16 v[96:99], v[160:163], v[184:187], v[96:99]
	v_mfma_f32_16x16x32_bf16 v[88:91], v[168:171], v[184:187], v[88:91]
	v_mfma_f32_16x16x32_bf16 v[80:83], v[160:163], v[206:209], v[80:83]
	v_mfma_f32_16x16x32_bf16 v[72:75], v[168:171], v[206:209], v[72:75]
	v_mfma_f32_16x16x32_bf16 v[68:71], v[160:163], v[214:217], v[68:71]
	v_mfma_f32_16x16x32_bf16 v[64:67], v[168:171], v[214:217], v[64:67]
	v_mfma_f32_16x16x32_bf16 v[112:115], v[164:167], v[180:183], v[112:115]
	v_mfma_f32_16x16x32_bf16 v[104:107], v[172:175], v[180:183], v[104:107]
	v_mfma_f32_16x16x32_bf16 v[96:99], v[164:167], v[188:191], v[96:99]
	v_mfma_f32_16x16x32_bf16 v[88:91], v[172:175], v[188:191], v[88:91]
	v_mfma_f32_16x16x32_bf16 v[80:83], v[164:167], v[210:213], v[80:83]
	v_mfma_f32_16x16x32_bf16 v[72:75], v[172:175], v[210:213], v[72:75]
	v_mfma_f32_16x16x32_bf16 v[68:71], v[164:167], v[218:221], v[68:71]
	v_mfma_f32_16x16x32_bf16 v[64:67], v[172:175], v[218:221], v[64:67]
	s_barrier
; #define PG8_STAGE(bufoff, gbase, voff) do { _Pragma("unroll") for (int _i = 0; _i < 2; ++_i) \
;         __builtin_amdgcn_global_load_lds((const unsigned*)((const char*)(gbase) + (voff)[_i]), (LAS unsigned*)(lds + (bufoff) + ldsw + _i * 8192), 16, 0, 0); } while (0)
; #define PG8_LDA(dst, b, h) do { _Pragma("unroll") for (int m = 0; m < 4; ++m) _Pragma("unroll") for (int k = 0; k < 2; ++k) dst[m][k] = *(const LAS bf16x8*)(lds + PG8_SA(b, h) + aoff + m * 2048 + k * 1024); } while (0)
; #define PG8_LDB(dst, b, h) do { _Pragma("unroll") for (int n = 0; n < 2; ++n) _Pragma("unroll") for (int k = 0; k < 2; ++k) dst[n][k] = *(const LAS bf16x8*)(lds + PG8_SB(b, h) + boff + n * 2048 + k * 1024); } while (0)
; #define PG8_MMA(ai, bj, At, Bt) do { __builtin_amdgcn_s_setprio(1); _Pragma("unroll") for (int m = 0; m < 4; ++m) _Pragma("unroll") for (int n = 0; n < 2; ++n) _Pragma("unroll") for (int k = 0; k < 2; ++k) \
;         acc[ai][bj][m][n] = __builtin_amdgcn_mfma_f32_16x16x32_bf16(Bt[n][k], At[m][k], acc[ai][bj][m][n], 0, 0, 0); __builtin_amdgcn_s_setprio(0); } while (0)
; #define PG8_WAIT_V(n) asm volatile("s_waitcnt vmcnt(" #n ")" ::: "memory")
; #define PG8_WAIT_L(n) asm volatile("s_waitcnt lgkmcnt(" #n ")" ::: "memory")
; #define PG8_BAR __builtin_amdgcn_s_barrier()
; #define PG8_SCHED __builtin_amdgcn_sched_barrier(0)
; template <class Epi, bool PERMA = false, bool DUAL = false, bool ALIGN_EPI = true, bool SP2 = true>
; __device__ __forceinline__ void gemm_phase(LAS unsigned char* lds, const Gemm g, const StaticOrder& S, const Epi& E) {
;     ...
;             PG8_LDB(B0, 1, 0); PG8_LDB(B1, 1, 1); PG8_SCHED; PG8_LDA(At, 1, 0); PG8_STAGE(PG8_SA(0, 1), a2 + hstepA, voffA);
;             PG8_WAIT_V(8); PG8_WAIT_L(0); PG8_BAR; PG8_MMA(0, 0, At, B0); PG8_MMA(0, 1, At, B1); PG8_BAR; PG8_SCHED;
;             PG8_LDA(At, 1, 1); PG8_STAGE(PG8_SB(1, 0), b3, voffB); PG8_STAGE(PG8_SB(1, 1), b3 + hstepB, voffB); PG8_STAGE(PG8_SA(1, 0), a3, voffA);
;             PG8_WAIT_V(8); PG8_WAIT_L(0); PG8_BAR; PG8_MMA(1, 0, At, B0); PG8_MMA(1, 1, At, B1); PG8_BAR; PG8_SCHED;
	s_add_i32 s18, s38, s20
	v_lshl_add_u64 v[222:223], v[222:223], 0, s[46:47]
	s_mov_b32 m0, s18
	ds_read_b128 v[176:179], v143 offset:49152
	ds_read_b128 v[180:183], v143 offset:50176
	ds_read_b128 v[184:187], v143 offset:51200
	ds_read_b128 v[188:191], v143 offset:52224
	ds_read_b128 v[206:209], v143 offset:53248
	ds_read_b128 v[210:213], v143 offset:54272
	ds_read_b128 v[214:217], v143 offset:55296
	ds_read_b128 v[218:221], v143 offset:56320
	global_load_lds_dwordx4 v[222:223], off
	s_add_i32 m0, s18, 0x2000
	s_add_u32 s16, s16, 0x80080
	v_lshl_add_u64 v[222:223], v[224:225], 0, s[46:47]
	s_addc_u32 s17, s17, 0
	s_add_i32 s18, s39, s20
	global_load_lds_dwordx4 v[222:223], off
	v_lshl_add_u64 v[222:223], s[16:17], 0, v[132:133]
	s_mov_b32 m0, s18
	s_nop 0
	global_load_lds_dwordx4 v[222:223], off
	v_lshl_add_u64 v[222:223], s[16:17], 0, v[128:129]
	s_add_i32 m0, s18, 0x2000
	s_nop 0
	global_load_lds_dwordx4 v[222:223], off
	v_lshl_add_u64 v[222:223], v[226:227], 0, s[46:47]
	s_mov_b32 m0, s25
	s_nop 0
	global_load_lds_dwordx4 v[222:223], off
	v_lshl_add_u64 v[222:223], v[228:229], 0, s[46:47]
	s_mov_b32 m0, s26
	s_nop 0
	global_load_lds_dwordx4 v[222:223], off
	s_waitcnt vmcnt(8)
	s_waitcnt lgkmcnt(0)
	s_barrier
	s_waitcnt lgkmcnt(0)
	v_mfma_f32_16x16x32_bf16 v[60:63], v[144:147], v[176:179], v[60:63]
	v_mfma_f32_16x16x32_bf16 v[56:59], v[152:155], v[176:179], v[56:59]
	v_mfma_f32_16x16x32_bf16 v[52:55], v[144:147], v[184:187], v[52:55]
	v_mfma_f32_16x16x32_bf16 v[44:47], v[152:155], v[184:187], v[44:47]
	v_mfma_f32_16x16x32_bf16 v[36:39], v[144:147], v[206:209], v[36:39]
	v_mfma_f32_16x16x32_bf16 v[28:31], v[152:155], v[206:209], v[28:31]
	v_mfma_f32_16x16x32_bf16 v[20:23], v[144:147], v[214:217], v[20:23]
	v_mfma_f32_16x16x32_bf16 v[12:15], v[152:155], v[214:217], v[12:15]
	v_mfma_f32_16x16x32_bf16 v[60:63], v[148:151], v[180:183], v[60:63]
	v_mfma_f32_16x16x32_bf16 v[56:59], v[156:159], v[180:183], v[56:59]
	v_mfma_f32_16x16x32_bf16 v[52:55], v[148:151], v[188:191], v[52:55]
	v_mfma_f32_16x16x32_bf16 v[44:47], v[156:159], v[188:191], v[44:47]
	v_mfma_f32_16x16x32_bf16 v[36:39], v[148:151], v[210:213], v[36:39]
	v_mfma_f32_16x16x32_bf16 v[28:31], v[156:159], v[210:213], v[28:31]
	v_mfma_f32_16x16x32_bf16 v[20:23], v[148:151], v[218:221], v[20:23]
	v_mfma_f32_16x16x32_bf16 v[12:15], v[156:159], v[218:221], v[12:15]
	v_mfma_f32_16x16x32_bf16 v[48:51], v[160:163], v[176:179], v[48:51]
	v_mfma_f32_16x16x32_bf16 v[40:43], v[168:171], v[176:179], v[40:43]
	v_mfma_f32_16x16x32_bf16 v[32:35], v[160:163], v[184:187], v[32:35]
	v_mfma_f32_16x16x32_bf16 v[24:27], v[168:171], v[184:187], v[24:27]
	v_mfma_f32_16x16x32_bf16 v[16:19], v[160:163], v[206:209], v[16:19]
	v_mfma_f32_16x16x32_bf16 v[8:11], v[168:171], v[206:209], v[8:11]
	v_mfma_f32_16x16x32_bf16 v[4:7], v[160:163], v[214:217], v[4:7]
	v_mfma_f32_16x16x32_bf16 v[0:3], v[168:171], v[214:217], v[0:3]
	v_mfma_f32_16x16x32_bf16 v[48:51], v[164:167], v[180:183], v[48:51]
	v_mfma_f32_16x16x32_bf16 v[40:43], v[172:175], v[180:183], v[40:43]
	v_mfma_f32_16x16x32_bf16 v[32:35], v[164:167], v[188:191], v[32:35]
	v_mfma_f32_16x16x32_bf16 v[24:27], v[172:175], v[188:191], v[24:27]
	v_mfma_f32_16x16x32_bf16 v[16:19], v[164:167], v[210:213], v[16:19]
	v_mfma_f32_16x16x32_bf16 v[8:11], v[172:175], v[210:213], v[8:11]
	v_mfma_f32_16x16x32_bf16 v[4:7], v[164:167], v[218:221], v[4:7]
	v_mfma_f32_16x16x32_bf16 v[0:3], v[172:175], v[218:221], v[0:3]
	s_barrier
	s_add_i32 s37, s37, 2
	s_add_u32 s14, s14, 0x100
	s_addc_u32 s15, s15, 0
	s_add_u32 s35, s35, 0x100
	s_addc_u32 s36, s36, 0
	s_cmp_gt_u32 s37, 29
	s_cbranch_scc0 .LBB0_130
	s_and_b64 vcc, exec, s[4:5]
	s_cbranch_vccz .LBB0_133
	s_barrier

; #define PG8_STAGE(bufoff, gbase, voff) do { _Pragma("unroll") for (int _i = 0; _i < 2; ++_i) \
;         __builtin_amdgcn_global_load_lds((const unsigned*)((const char*)(gbase) + (voff)[_i]), (LAS unsigned*)(lds + (bufoff) + ldsw + _i * 8192), 16, 0, 0); } while (0)
; #define PG8_LDA(dst, b, h) do { _Pragma("unroll") for (int m = 0; m < 4; ++m) _Pragma("unroll") for (int k = 0; k < 2; ++k) dst[m][k] = *(const LAS bf16x8*)(lds + PG8_SA(b, h) + aoff + m * 2048 + k * 1024); } while (0)
; #define PG8_LDB(dst, b, h) do { _Pragma("unroll") for (int n = 0; n < 2; ++n) _Pragma("unroll") for (int k = 0; k < 2; ++k) dst[n][k] = *(const LAS bf16x8*)(lds + PG8_SB(b, h) + boff + n * 2048 + k * 1024); } while (0)
; #define PG8_MMA(ai, bj, At, Bt) do { __builtin_amdgcn_s_setprio(1); _Pragma("unroll") for (int m = 0; m < 4; ++m) _Pragma("unroll") for (int n = 0; n < 2; ++n) _Pragma("unroll") for (int k = 0; k < 2; ++k) \
;         acc[ai][bj][m][n] = __builtin_amdgcn_mfma_f32_16x16x32_bf16(Bt[n][k], At[m][k], acc[ai][bj][m][n], 0, 0, 0); __builtin_amdgcn_s_setprio(0); } while (0)
; #define PG8_WAIT_V(n) asm volatile("s_waitcnt vmcnt(" #n ")" ::: "memory")
; #define PG8_WAIT_L(n) asm volatile("s_waitcnt lgkmcnt(" #n ")" ::: "memory")
; template <class Epi, bool PERMA = false, bool DUAL = false, bool ALIGN_EPI = true, bool SP2 = true>
; __device__ __forceinline__ void gemm_phase(LAS unsigned char* lds, const Gemm g, const StaticOrder& S, const Epi& E) {
;     ...
;         for (int t = 0; t < nt; t += 2) {
;             const bool last = (t == nt - 2);
;             const char* a1 = cA + (size_t)(t + 1) * kstep;
;             const char* a2 = last ? nA : cA + (size_t)(t + 2) * kstep; const char* b2 = last ? nB : cB + (size_t)(t + 2) * kstep;
;             const char* a3 = a2 + kstep; const char* b3 = b2 + kstep;
;             if constexpr (SP2) {
;             PG8_LDB(B0, 0, 0); PG8_LDB(B1, 0, 1); PG8_SCHED; PG8_LDA(At, 0, 0); PG8_STAGE(PG8_SA(1, 1), a1 + hstepA, voffA);
;             PG8_WAIT_V(8); PG8_WAIT_L(0); PG8_BAR; PG8_MMA(0, 0, At, B0); PG8_MMA(0, 1, At, B1); PG8_BAR; PG8_SCHED;
;             PG8_LDA(At, 0, 1); PG8_STAGE(PG8_SB(0, 0), b2, voffB); PG8_STAGE(PG8_SB(0, 1), b2 + hstepB, voffB); PG8_STAGE(PG8_SA(0, 0), a2, voffA);
;             PG8_WAIT_V(8); PG8_WAIT_L(0); PG8_BAR; PG8_MMA(1, 0, At, B0); PG8_MMA(1, 1, At, B1); PG8_BAR; PG8_SCHED;
.LBB0_329:
	s_add_u32 s0, s12, 0x100
	s_addc_u32 s1, s13, 0
	s_add_i32 s38, 0, 0x10000
	s_cmp_eq_u32 s37, 4
	s_cselect_b32 s17, s9, s1
	s_cselect_b32 s16, s8, s0
	s_cselect_b32 s15, s7, s36
	s_cselect_b32 s14, s34, s35
	s_add_i32 s39, 0, 0x14000
	v_add_u32_e32 v140, s38, v193
	v_add_u32_e32 v156, s39, v193
	ds_read_b128 v[128:131], v140
	ds_read_b128 v[132:135], v140 offset:1024
	ds_read_b128 v[136:139], v140 offset:2048
	ds_read_b128 v[140:143], v140 offset:3072
	ds_read_b128 v[144:147], v156
	ds_read_b128 v[148:151], v156 offset:1024
	ds_read_b128 v[152:155], v156 offset:2048
	ds_read_b128 v[156:159], v156 offset:3072
	v_lshl_add_u64 v[220:221], s[12:13], 0, v[216:217]
	s_add_i32 m0, s19, 0xc000
	ds_read_b128 v[160:163], v238
	ds_read_b128 v[164:167], v238 offset:1024
	ds_read_b128 v[168:171], v238 offset:2048
	ds_read_b128 v[172:175], v238 offset:3072
	ds_read_b128 v[176:179], v238 offset:4096
	ds_read_b128 v[180:183], v238 offset:5120
	ds_read_b128 v[184:187], v238 offset:6144
	ds_read_b128 v[188:191], v238 offset:7168
	global_load_lds_dwordx4 v[220:221], off
	v_lshl_add_u64 v[220:221], s[12:13], 0, v[218:219]
	s_add_i32 m0, s19, 0xe000
	s_nop 0
	global_load_lds_dwordx4 v[220:221], off
	s_waitcnt vmcnt(8)
	s_waitcnt lgkmcnt(0)
	s_barrier
	s_waitcnt lgkmcnt(0)
	v_mfma_f32_16x16x32_bf16 v[124:127], v[128:131], v[160:163], v[124:127]
	v_mfma_f32_16x16x32_bf16 v[120:123], v[136:139], v[160:163], v[120:123]
	v_mfma_f32_16x16x32_bf16 v[108:111], v[128:131], v[168:171], v[108:111]
	v_mfma_f32_16x16x32_bf16 v[104:107], v[136:139], v[168:171], v[104:107]
	v_mfma_f32_16x16x32_bf16 v[92:95], v[128:131], v[176:179], v[92:95]
	v_mfma_f32_16x16x32_bf16 v[88:91], v[136:139], v[176:179], v[88:91]
	v_mfma_f32_16x16x32_bf16 v[76:79], v[128:131], v[184:187], v[76:79]
	v_mfma_f32_16x16x32_bf16 v[72:75], v[136:139], v[184:187], v[72:75]
	v_mfma_f32_16x16x32_bf16 v[124:127], v[132:135], v[164:167], v[124:127]
	v_mfma_f32_16x16x32_bf16 v[120:123], v[140:143], v[164:167], v[120:123]
	v_mfma_f32_16x16x32_bf16 v[108:111], v[132:135], v[172:175], v[108:111]
	v_mfma_f32_16x16x32_bf16 v[104:107], v[140:143], v[172:175], v[104:107]
	v_mfma_f32_16x16x32_bf16 v[92:95], v[132:135], v[180:183], v[92:95]
	v_mfma_f32_16x16x32_bf16 v[88:91], v[140:143], v[180:183], v[88:91]
	v_mfma_f32_16x16x32_bf16 v[76:79], v[132:135], v[188:191], v[76:79]
	v_mfma_f32_16x16x32_bf16 v[72:75], v[140:143], v[188:191], v[72:75]
	v_mfma_f32_16x16x32_bf16 v[116:119], v[144:147], v[160:163], v[116:119]
	v_mfma_f32_16x16x32_bf16 v[112:115], v[152:155], v[160:163], v[112:115]
	v_mfma_f32_16x16x32_bf16 v[100:103], v[144:147], v[168:171], v[100:103]
	v_mfma_f32_16x16x32_bf16 v[96:99], v[152:155], v[168:171], v[96:99]
	v_mfma_f32_16x16x32_bf16 v[84:87], v[144:147], v[176:179], v[84:87]
	v_mfma_f32_16x16x32_bf16 v[80:83], v[152:155], v[176:179], v[80:83]
	v_mfma_f32_16x16x32_bf16 v[68:71], v[144:147], v[184:187], v[68:71]
	v_mfma_f32_16x16x32_bf16 v[64:67], v[152:155], v[184:187], v[64:67]
	v_mfma_f32_16x16x32_bf16 v[116:119], v[148:151], v[164:167], v[116:119]
	v_mfma_f32_16x16x32_bf16 v[112:115], v[156:159], v[164:167], v[112:115]
	v_mfma_f32_16x16x32_bf16 v[100:103], v[148:151], v[172:175], v[100:103]
	v_mfma_f32_16x16x32_bf16 v[96:99], v[156:159], v[172:175], v[96:99]
	v_mfma_f32_16x16x32_bf16 v[84:87], v[148:151], v[180:183], v[84:87]
	v_mfma_f32_16x16x32_bf16 v[80:83], v[156:159], v[180:183], v[80:83]
	v_mfma_f32_16x16x32_bf16 v[68:71], v[148:151], v[188:191], v[68:71]
	v_mfma_f32_16x16x32_bf16 v[64:67], v[156:159], v[188:191], v[64:67]
	s_barrier
	s_add_i32 s12, s38, s18
	v_lshl_add_u64 v[220:221], s[14:15], 0, v[210:211]
	s_mov_b32 m0, s12
	ds_read_b128 v[160:163], v238 offset:16384
	ds_read_b128 v[164:167], v238 offset:17408
	ds_read_b128 v[168:171], v238 offset:18432
	ds_read_b128 v[172:175], v238 offset:19456
	ds_read_b128 v[176:179], v238 offset:20480
	ds_read_b128 v[180:183], v238 offset:21504
	ds_read_b128 v[184:187], v238 offset:22528
	ds_read_b128 v[188:191], v238 offset:23552
	global_load_lds_dwordx4 v[220:221], off
	s_add_i32 m0, s12, 0x2000
	s_add_u32 s12, s14, 0x20000
	v_lshl_add_u64 v[222:223], s[14:15], 0, v[206:207]
	s_addc_u32 s13, s15, 0
	s_add_i32 s38, s39, s18
	global_load_lds_dwordx4 v[222:223], off
	v_lshl_add_u64 v[224:225], s[12:13], 0, v[210:211]
	s_mov_b32 m0, s38
	v_lshl_add_u64 v[226:227], s[16:17], 0, v[208:209]
	global_load_lds_dwordx4 v[224:225], off
	v_lshl_add_u64 v[224:225], s[12:13], 0, v[206:207]
	s_add_i32 m0, s38, 0x2000
	s_nop 0
	global_load_lds_dwordx4 v[224:225], off
	v_lshl_add_u64 v[224:225], s[16:17], 0, v[212:213]
	s_mov_b32 m0, s19
	s_nop 0
	global_load_lds_dwordx4 v[224:225], off
	s_mov_b32 m0, s20
	s_nop 0
	global_load_lds_dwordx4 v[226:227], off
	s_waitcnt vmcnt(8)
	s_waitcnt lgkmcnt(0)
	s_barrier
; #define PG8_STAGE(bufoff, gbase, voff) do { _Pragma("unroll") for (int _i = 0; _i < 2; ++_i) \
;         __builtin_amdgcn_global_load_lds((const unsigned*)((const char*)(gbase) + (voff)[_i]), (LAS unsigned*)(lds + (bufoff) + ldsw + _i * 8192), 16, 0, 0); } while (0)
; #define PG8_LDA(dst, b, h) do { _Pragma("unroll") for (int m = 0; m < 4; ++m) _Pragma("unroll") for (int k = 0; k < 2; ++k) dst[m][k] = *(const LAS bf16x8*)(lds + PG8_SA(b, h) + aoff + m * 2048 + k * 1024); } while (0)
; #define PG8_LDB(dst, b, h) do { _Pragma("unroll") for (int n = 0; n < 2; ++n) _Pragma("unroll") for (int k = 0; k < 2; ++k) dst[n][k] = *(const LAS bf16x8*)(lds + PG8_SB(b, h) + boff + n * 2048 + k * 1024); } while (0)
; #define PG8_MMA(ai, bj, At, Bt) do { __builtin_amdgcn_s_setprio(1); _Pragma("unroll") for (int m = 0; m < 4; ++m) _Pragma("unroll") for (int n = 0; n < 2; ++n) _Pragma("unroll") for (int k = 0; k < 2; ++k) \
;         acc[ai][bj][m][n] = __builtin_amdgcn_mfma_f32_16x16x32_bf16(Bt[n][k], At[m][k], acc[ai][bj][m][n], 0, 0, 0); __builtin_amdgcn_s_setprio(0); } while (0)
; #define PG8_WAIT_V(n) asm volatile("s_waitcnt vmcnt(" #n ")" ::: "memory")
; #define PG8_WAIT_L(n) asm volatile("s_waitcnt lgkmcnt(" #n ")" ::: "memory")
; template <class Epi, bool PERMA = false, bool DUAL = false, bool ALIGN_EPI = true, bool SP2 = true>
; __device__ __forceinline__ void gemm_phase(LAS unsigned char* lds, const Gemm g, const StaticOrder& S, const Epi& E) {
;     ...
;             PG8_WAIT_V(8); PG8_WAIT_L(0); PG8_BAR; PG8_MMA(0, 0, At, B0); PG8_MMA(0, 1, At, B1); PG8_BAR; PG8_SCHED;
;             PG8_LDA(At, 0, 1); PG8_STAGE(PG8_SB(0, 0), b2, voffB); PG8_STAGE(PG8_SB(0, 1), b2 + hstepB, voffB); PG8_STAGE(PG8_SA(0, 0), a2, voffA);
;             PG8_WAIT_V(8); PG8_WAIT_L(0); PG8_BAR; PG8_MMA(1, 0, At, B0); PG8_MMA(1, 1, At, B1); PG8_BAR; PG8_SCHED;
;             PG8_LDB(B0, 1, 0); PG8_LDB(B1, 1, 1); PG8_SCHED; PG8_LDA(At, 1, 0); PG8_STAGE(PG8_SA(0, 1), a2 + hstepA, voffA);
;             PG8_WAIT_V(8); PG8_WAIT_L(0); PG8_BAR; PG8_MMA(0, 0, At, B0); PG8_MMA(0, 1, At, B1); PG8_BAR; PG8_SCHED;
;             PG8_LDA(At, 1, 1); PG8_STAGE(PG8_SB(1, 0), b3, voffB); PG8_STAGE(PG8_SB(1, 1), b3 + hstepB, voffB); PG8_STAGE(PG8_SA(1, 0), a3, voffA);
;             PG8_WAIT_V(8); PG8_WAIT_L(0); PG8_BAR; PG8_MMA(1, 0, At, B0); PG8_MMA(1, 1, At, B1); PG8_BAR; PG8_SCHED;
	s_waitcnt lgkmcnt(0)
	v_mfma_f32_16x16x32_bf16 v[60:63], v[128:131], v[160:163], v[60:63]
	v_mfma_f32_16x16x32_bf16 v[56:59], v[136:139], v[160:163], v[56:59]
	v_mfma_f32_16x16x32_bf16 v[44:47], v[128:131], v[168:171], v[44:47]
	v_mfma_f32_16x16x32_bf16 v[40:43], v[136:139], v[168:171], v[40:43]
	v_mfma_f32_16x16x32_bf16 v[28:31], v[128:131], v[176:179], v[28:31]
	v_mfma_f32_16x16x32_bf16 v[24:27], v[136:139], v[176:179], v[24:27]
	v_mfma_f32_16x16x32_bf16 v[12:15], v[128:131], v[184:187], v[12:15]
	v_mfma_f32_16x16x32_bf16 v[8:11], v[136:139], v[184:187], v[8:11]
	v_mfma_f32_16x16x32_bf16 v[60:63], v[132:135], v[164:167], v[60:63]
	v_mfma_f32_16x16x32_bf16 v[56:59], v[140:143], v[164:167], v[56:59]
	v_mfma_f32_16x16x32_bf16 v[44:47], v[132:135], v[172:175], v[44:47]
	v_mfma_f32_16x16x32_bf16 v[40:43], v[140:143], v[172:175], v[40:43]
	v_mfma_f32_16x16x32_bf16 v[28:31], v[132:135], v[180:183], v[28:31]
	v_mfma_f32_16x16x32_bf16 v[24:27], v[140:143], v[180:183], v[24:27]
	v_mfma_f32_16x16x32_bf16 v[12:15], v[132:135], v[188:191], v[12:15]
	v_mfma_f32_16x16x32_bf16 v[8:11], v[140:143], v[188:191], v[8:11]
	v_mfma_f32_16x16x32_bf16 v[52:55], v[144:147], v[160:163], v[52:55]
	v_mfma_f32_16x16x32_bf16 v[48:51], v[152:155], v[160:163], v[48:51]
	v_mfma_f32_16x16x32_bf16 v[36:39], v[144:147], v[168:171], v[36:39]
	v_mfma_f32_16x16x32_bf16 v[32:35], v[152:155], v[168:171], v[32:35]
	v_mfma_f32_16x16x32_bf16 v[20:23], v[144:147], v[176:179], v[20:23]
	v_mfma_f32_16x16x32_bf16 v[16:19], v[152:155], v[176:179], v[16:19]
	v_mfma_f32_16x16x32_bf16 v[4:7], v[144:147], v[184:187], v[4:7]
	v_mfma_f32_16x16x32_bf16 v[0:3], v[152:155], v[184:187], v[0:3]
	v_mfma_f32_16x16x32_bf16 v[52:55], v[148:151], v[164:167], v[52:55]
	v_mfma_f32_16x16x32_bf16 v[48:51], v[156:159], v[164:167], v[48:51]
	v_mfma_f32_16x16x32_bf16 v[36:39], v[148:151], v[172:175], v[36:39]
	v_mfma_f32_16x16x32_bf16 v[32:35], v[156:159], v[172:175], v[32:35]
	v_mfma_f32_16x16x32_bf16 v[20:23], v[148:151], v[180:183], v[20:23]
	v_mfma_f32_16x16x32_bf16 v[16:19], v[156:159], v[180:183], v[16:19]
	v_mfma_f32_16x16x32_bf16 v[4:7], v[148:151], v[188:191], v[4:7]
	v_mfma_f32_16x16x32_bf16 v[0:3], v[156:159], v[188:191], v[0:3]
	s_barrier
	s_add_i32 s38, 0, 0x18000
	s_add_i32 s39, 0, 0x1c000
	v_add_u32_e32 v140, s38, v193
	v_add_u32_e32 v156, s39, v193
	ds_read_b128 v[128:131], v140
	ds_read_b128 v[132:135], v140 offset:1024
	ds_read_b128 v[136:139], v140 offset:2048
	ds_read_b128 v[140:143], v140 offset:3072
	ds_read_b128 v[144:147], v156
	ds_read_b128 v[148:151], v156 offset:1024
	ds_read_b128 v[152:155], v156 offset:2048
	ds_read_b128 v[156:159], v156 offset:3072
	s_add_u32 s12, s16, 0x180000
	s_addc_u32 s13, s17, 0
	s_mov_b32 m0, s21
	v_lshl_add_u64 v[228:229], s[12:13], 0, v[212:213]
	ds_read_b128 v[160:163], v238 offset:32768
	ds_read_b128 v[164:167], v238 offset:33792
	ds_read_b128 v[168:171], v238 offset:34816
	ds_read_b128 v[172:175], v238 offset:35840
	ds_read_b128 v[176:179], v238 offset:36864
	ds_read_b128 v[180:183], v238 offset:37888
	ds_read_b128 v[184:187], v238 offset:38912
	ds_read_b128 v[188:191], v238 offset:39936
	global_load_lds_dwordx4 v[228:229], off
	v_lshl_add_u64 v[228:229], s[12:13], 0, v[208:209]
	s_mov_b32 m0, s22
	s_nop 0
	global_load_lds_dwordx4 v[228:229], off
	s_waitcnt vmcnt(8)
	s_waitcnt lgkmcnt(0)
	s_barrier
	s_waitcnt lgkmcnt(0)
	v_mfma_f32_16x16x32_bf16 v[124:127], v[128:131], v[160:163], v[124:127]
	v_mfma_f32_16x16x32_bf16 v[120:123], v[136:139], v[160:163], v[120:123]
	v_mfma_f32_16x16x32_bf16 v[108:111], v[128:131], v[168:171], v[108:111]
	v_mfma_f32_16x16x32_bf16 v[104:107], v[136:139], v[168:171], v[104:107]
	v_mfma_f32_16x16x32_bf16 v[92:95], v[128:131], v[176:179], v[92:95]
	v_mfma_f32_16x16x32_bf16 v[88:91], v[136:139], v[176:179], v[88:91]
	v_mfma_f32_16x16x32_bf16 v[76:79], v[128:131], v[184:187], v[76:79]
	v_mfma_f32_16x16x32_bf16 v[72:75], v[136:139], v[184:187], v[72:75]
	v_mfma_f32_16x16x32_bf16 v[124:127], v[132:135], v[164:167], v[124:127]
	v_mfma_f32_16x16x32_bf16 v[120:123], v[140:143], v[164:167], v[120:123]
	v_mfma_f32_16x16x32_bf16 v[108:111], v[132:135], v[172:175], v[108:111]
	v_mfma_f32_16x16x32_bf16 v[104:107], v[140:143], v[172:175], v[104:107]
	v_mfma_f32_16x16x32_bf16 v[92:95], v[132:135], v[180:183], v[92:95]
	v_mfma_f32_16x16x32_bf16 v[88:91], v[140:143], v[180:183], v[88:91]
	v_mfma_f32_16x16x32_bf16 v[76:79], v[132:135], v[188:191], v[76:79]
	v_mfma_f32_16x16x32_bf16 v[72:75], v[140:143], v[188:191], v[72:75]
	v_mfma_f32_16x16x32_bf16 v[116:119], v[144:147], v[160:163], v[116:119]
	v_mfma_f32_16x16x32_bf16 v[112:115], v[152:155], v[160:163], v[112:115]
	v_mfma_f32_16x16x32_bf16 v[100:103], v[144:147], v[168:171], v[100:103]
	v_mfma_f32_16x16x32_bf16 v[96:99], v[152:155], v[168:171], v[96:99]
	v_mfma_f32_16x16x32_bf16 v[84:87], v[144:147], v[176:179], v[84:87]
	v_mfma_f32_16x16x32_bf16 v[80:83], v[152:155], v[176:179], v[80:83]
	v_mfma_f32_16x16x32_bf16 v[68:71], v[144:147], v[184:187], v[68:71]
	v_mfma_f32_16x16x32_bf16 v[64:67], v[152:155], v[184:187], v[64:67]
	v_mfma_f32_16x16x32_bf16 v[116:119], v[148:151], v[164:167], v[116:119]
	v_mfma_f32_16x16x32_bf16 v[112:115], v[156:159], v[164:167], v[112:115]
	v_mfma_f32_16x16x32_bf16 v[100:103], v[148:151], v[172:175], v[100:103]
	v_mfma_f32_16x16x32_bf16 v[96:99], v[156:159], v[172:175], v[96:99]
	v_mfma_f32_16x16x32_bf16 v[84:87], v[148:151], v[180:183], v[84:87]
	v_mfma_f32_16x16x32_bf16 v[80:83], v[156:159], v[180:183], v[80:83]
	v_mfma_f32_16x16x32_bf16 v[68:71], v[148:151], v[188:191], v[68:71]
	v_mfma_f32_16x16x32_bf16 v[64:67], v[156:159], v[188:191], v[64:67]
	s_barrier
; #define PG8_STAGE(bufoff, gbase, voff) do { _Pragma("unroll") for (int _i = 0; _i < 2; ++_i) \
;         __builtin_amdgcn_global_load_lds((const unsigned*)((const char*)(gbase) + (voff)[_i]), (LAS unsigned*)(lds + (bufoff) + ldsw + _i * 8192), 16, 0, 0); } while (0)
; #define PG8_LDA(dst, b, h) do { _Pragma("unroll") for (int m = 0; m < 4; ++m) _Pragma("unroll") for (int k = 0; k < 2; ++k) dst[m][k] = *(const LAS bf16x8*)(lds + PG8_SA(b, h) + aoff + m * 2048 + k * 1024); } while (0)
; #define PG8_LDB(dst, b, h) do { _Pragma("unroll") for (int n = 0; n < 2; ++n) _Pragma("unroll") for (int k = 0; k < 2; ++k) dst[n][k] = *(const LAS bf16x8*)(lds + PG8_SB(b, h) + boff + n * 2048 + k * 1024); } while (0)
; #define PG8_MMA(ai, bj, At, Bt) do { __builtin_amdgcn_s_setprio(1); _Pragma("unroll") for (int m = 0; m < 4; ++m) _Pragma("unroll") for (int n = 0; n < 2; ++n) _Pragma("unroll") for (int k = 0; k < 2; ++k) \
;         acc[ai][bj][m][n] = __builtin_amdgcn_mfma_f32_16x16x32_bf16(Bt[n][k], At[m][k], acc[ai][bj][m][n], 0, 0, 0); __builtin_amdgcn_s_setprio(0); } while (0)
; #define PG8_WAIT_V(n) asm volatile("s_waitcnt vmcnt(" #n ")" ::: "memory")
; #define PG8_WAIT_L(n) asm volatile("s_waitcnt lgkmcnt(" #n ")" ::: "memory")
; #define PG8_BAR __builtin_amdgcn_s_barrier()
; #define PG8_SCHED __builtin_amdgcn_sched_barrier(0)
; template <class Epi, bool PERMA = false, bool DUAL = false, bool ALIGN_EPI = true, bool SP2 = true>
; __device__ __forceinline__ void gemm_phase(LAS unsigned char* lds, const Gemm g, const StaticOrder& S, const Epi& E) {
;     ...
;             PG8_LDB(B0, 1, 0); PG8_LDB(B1, 1, 1); PG8_SCHED; PG8_LDA(At, 1, 0); PG8_STAGE(PG8_SA(0, 1), a2 + hstepA, voffA);
;             PG8_WAIT_V(8); PG8_WAIT_L(0); PG8_BAR; PG8_MMA(0, 0, At, B0); PG8_MMA(0, 1, At, B1); PG8_BAR; PG8_SCHED;
;             PG8_LDA(At, 1, 1); PG8_STAGE(PG8_SB(1, 0), b3, voffB); PG8_STAGE(PG8_SB(1, 1), b3 + hstepB, voffB); PG8_STAGE(PG8_SA(1, 0), a3, voffA);
;             PG8_WAIT_V(8); PG8_WAIT_L(0); PG8_BAR; PG8_MMA(1, 0, At, B0); PG8_MMA(1, 1, At, B1); PG8_BAR; PG8_SCHED;
	s_add_i32 s12, s38, s18
	v_lshl_add_u64 v[220:221], v[220:221], 0, s[46:47]
	s_mov_b32 m0, s12
	ds_read_b128 v[160:163], v238 offset:49152
	ds_read_b128 v[164:167], v238 offset:50176
	ds_read_b128 v[168:171], v238 offset:51200
	ds_read_b128 v[172:175], v238 offset:52224
	ds_read_b128 v[176:179], v238 offset:53248
	ds_read_b128 v[180:183], v238 offset:54272
	ds_read_b128 v[184:187], v238 offset:55296
	ds_read_b128 v[188:191], v238 offset:56320
	global_load_lds_dwordx4 v[220:221], off
	s_add_i32 m0, s12, 0x2000
	s_add_u32 s12, s14, 0x20080
	v_lshl_add_u64 v[220:221], v[222:223], 0, s[46:47]
	s_addc_u32 s13, s15, 0
	s_add_i32 s14, s39, s18
	global_load_lds_dwordx4 v[220:221], off
	v_lshl_add_u64 v[220:221], s[12:13], 0, v[210:211]
	s_mov_b32 m0, s14
	s_nop 0
	global_load_lds_dwordx4 v[220:221], off
	v_lshl_add_u64 v[220:221], s[12:13], 0, v[206:207]
	s_add_i32 m0, s14, 0x2000
	s_nop 0
	global_load_lds_dwordx4 v[220:221], off
	v_lshl_add_u64 v[220:221], v[224:225], 0, s[46:47]
	s_mov_b32 m0, s25
	s_nop 0
	global_load_lds_dwordx4 v[220:221], off
	v_lshl_add_u64 v[220:221], v[226:227], 0, s[46:47]
	s_mov_b32 m0, s26
	s_nop 0
	global_load_lds_dwordx4 v[220:221], off
	s_waitcnt vmcnt(8)
	s_waitcnt lgkmcnt(0)
	s_barrier
	s_waitcnt lgkmcnt(0)
	v_mfma_f32_16x16x32_bf16 v[60:63], v[128:131], v[160:163], v[60:63]
	v_mfma_f32_16x16x32_bf16 v[56:59], v[136:139], v[160:163], v[56:59]
	v_mfma_f32_16x16x32_bf16 v[44:47], v[128:131], v[168:171], v[44:47]
	v_mfma_f32_16x16x32_bf16 v[40:43], v[136:139], v[168:171], v[40:43]
	v_mfma_f32_16x16x32_bf16 v[28:31], v[128:131], v[176:179], v[28:31]
	v_mfma_f32_16x16x32_bf16 v[24:27], v[136:139], v[176:179], v[24:27]
	v_mfma_f32_16x16x32_bf16 v[12:15], v[128:131], v[184:187], v[12:15]
	v_mfma_f32_16x16x32_bf16 v[8:11], v[136:139], v[184:187], v[8:11]
	v_mfma_f32_16x16x32_bf16 v[60:63], v[132:135], v[164:167], v[60:63]
	v_mfma_f32_16x16x32_bf16 v[56:59], v[140:143], v[164:167], v[56:59]
	v_mfma_f32_16x16x32_bf16 v[44:47], v[132:135], v[172:175], v[44:47]
	v_mfma_f32_16x16x32_bf16 v[40:43], v[140:143], v[172:175], v[40:43]
	v_mfma_f32_16x16x32_bf16 v[28:31], v[132:135], v[180:183], v[28:31]
	v_mfma_f32_16x16x32_bf16 v[24:27], v[140:143], v[180:183], v[24:27]
	v_mfma_f32_16x16x32_bf16 v[12:15], v[132:135], v[188:191], v[12:15]
	v_mfma_f32_16x16x32_bf16 v[8:11], v[140:143], v[188:191], v[8:11]
	v_mfma_f32_16x16x32_bf16 v[52:55], v[144:147], v[160:163], v[52:55]
	v_mfma_f32_16x16x32_bf16 v[48:51], v[152:155], v[160:163], v[48:51]
	v_mfma_f32_16x16x32_bf16 v[36:39], v[144:147], v[168:171], v[36:39]
	v_mfma_f32_16x16x32_bf16 v[32:35], v[152:155], v[168:171], v[32:35]
	v_mfma_f32_16x16x32_bf16 v[20:23], v[144:147], v[176:179], v[20:23]
	v_mfma_f32_16x16x32_bf16 v[16:19], v[152:155], v[176:179], v[16:19]
	v_mfma_f32_16x16x32_bf16 v[4:7], v[144:147], v[184:187], v[4:7]
	v_mfma_f32_16x16x32_bf16 v[0:3], v[152:155], v[184:187], v[0:3]
	v_mfma_f32_16x16x32_bf16 v[52:55], v[148:151], v[164:167], v[52:55]
	v_mfma_f32_16x16x32_bf16 v[48:51], v[156:159], v[164:167], v[48:51]
	v_mfma_f32_16x16x32_bf16 v[36:39], v[148:151], v[172:175], v[36:39]
	v_mfma_f32_16x16x32_bf16 v[32:35], v[156:159], v[172:175], v[32:35]
	v_mfma_f32_16x16x32_bf16 v[20:23], v[148:151], v[180:183], v[20:23]
	v_mfma_f32_16x16x32_bf16 v[16:19], v[156:159], v[180:183], v[16:19]
	v_mfma_f32_16x16x32_bf16 v[4:7], v[148:151], v[188:191], v[4:7]
	v_mfma_f32_16x16x32_bf16 v[0:3], v[156:159], v[188:191], v[0:3]
	s_barrier
	s_add_i32 s37, s37, 2
	s_add_u32 s35, s35, 0x100
	s_addc_u32 s36, s36, 0
	s_cmp_gt_u32 s37, 5
	s_mov_b64 s[12:13], s[0:1]
	s_cbranch_scc0 .LBB0_329
	s_and_b64 vcc, exec, s[4:5]
	s_cbranch_vccz .LBB0_332
	s_barrier

; #define PG8_STAGE(bufoff, gbase, voff) do { _Pragma("unroll") for (int _i = 0; _i < 2; ++_i) \
;         __builtin_amdgcn_global_load_lds((const unsigned*)((const char*)(gbase) + (voff)[_i]), (LAS unsigned*)(lds + (bufoff) + ldsw + _i * 8192), 16, 0, 0); } while (0)
; #define PG8_LDA(dst, b, h) do { _Pragma("unroll") for (int m = 0; m < 4; ++m) _Pragma("unroll") for (int k = 0; k < 2; ++k) dst[m][k] = *(const LAS bf16x8*)(lds + PG8_SA(b, h) + aoff + m * 2048 + k * 1024); } while (0)
; #define PG8_LDB(dst, b, h) do { _Pragma("unroll") for (int n = 0; n < 2; ++n) _Pragma("unroll") for (int k = 0; k < 2; ++k) dst[n][k] = *(const LAS bf16x8*)(lds + PG8_SB(b, h) + boff + n * 2048 + k * 1024); } while (0)
; #define PG8_MMA(ai, bj, At, Bt) do { __builtin_amdgcn_s_setprio(1); _Pragma("unroll") for (int m = 0; m < 4; ++m) _Pragma("unroll") for (int n = 0; n < 2; ++n) _Pragma("unroll") for (int k = 0; k < 2; ++k) \
;         acc[ai][bj][m][n] = __builtin_amdgcn_mfma_f32_16x16x32_bf16(Bt[n][k], At[m][k], acc[ai][bj][m][n], 0, 0, 0); __builtin_amdgcn_s_setprio(0); } while (0)
; #define PG8_WAIT_V(n) asm volatile("s_waitcnt vmcnt(" #n ")" ::: "memory")
; #define PG8_WAIT_L(n) asm volatile("s_waitcnt lgkmcnt(" #n ")" ::: "memory")
; template <class Epi, bool PERMA = false, bool DUAL = false, bool ALIGN_EPI = true, bool SP2 = true>
; __device__ __forceinline__ void gemm_phase(LAS unsigned char* lds, const Gemm g, const StaticOrder& S, const Epi& E) {
;     ...
;         for (int t = 0; t < nt; t += 2) {
;             const bool last = (t == nt - 2);
;             const char* a1 = cA + (size_t)(t + 1) * kstep;
;             const char* a2 = last ? nA : cA + (size_t)(t + 2) * kstep; const char* b2 = last ? nB : cB + (size_t)(t + 2) * kstep;
;             const char* a3 = a2 + kstep; const char* b3 = b2 + kstep;
;             if constexpr (SP2) {
;             PG8_LDB(B0, 0, 0); PG8_LDB(B1, 0, 1); PG8_SCHED; PG8_LDA(At, 0, 0); PG8_STAGE(PG8_SA(1, 1), a1 + hstepA, voffA);
;             PG8_WAIT_V(8); PG8_WAIT_L(0); PG8_BAR; PG8_MMA(0, 0, At, B0); PG8_MMA(0, 1, At, B1); PG8_BAR; PG8_SCHED;
;             PG8_LDA(At, 0, 1); PG8_STAGE(PG8_SB(0, 0), b2, voffB); PG8_STAGE(PG8_SB(0, 1), b2 + hstepB, voffB); PG8_STAGE(PG8_SA(0, 0), a2, voffA);
;             PG8_WAIT_V(8); PG8_WAIT_L(0); PG8_BAR; PG8_MMA(1, 0, At, B0); PG8_MMA(1, 1, At, B1); PG8_BAR; PG8_SCHED;
.LBB0_405:
	s_add_u32 s16, s14, 0xfff00080
	s_addc_u32 s17, s15, -1
	s_add_i32 s38, 0, 0x10000
	s_cmp_eq_u32 s37, 28
	s_cselect_b32 s19, s9, s17
	s_cselect_b32 s18, s33, s16
	v_add_u32_e32 v142, s38, v144
	s_cselect_b32 s17, s7, s36
	s_cselect_b32 s16, s34, s35
	s_add_i32 s40, 0, 0x14000
	ds_read_b128 v[146:149], v142
	ds_read_b128 v[150:153], v142 offset:1024
	ds_read_b128 v[154:157], v142 offset:2048
	ds_read_b128 v[158:161], v142 offset:3072
	v_add_u32_e32 v142, s40, v144
	ds_read_b128 v[162:165], v142
	ds_read_b128 v[166:169], v142 offset:1024
	ds_read_b128 v[170:173], v142 offset:2048
	ds_read_b128 v[174:177], v142 offset:3072
	v_lshl_add_u64 v[142:143], s[14:15], 0, v[138:139]
	s_add_i32 m0, s21, 0xc000
	ds_read_b128 v[178:181], v145
	ds_read_b128 v[182:185], v145 offset:1024
	ds_read_b128 v[186:189], v145 offset:2048
	ds_read_b128 v[206:209], v145 offset:3072
	ds_read_b128 v[210:213], v145 offset:4096
	ds_read_b128 v[214:217], v145 offset:5120
	ds_read_b128 v[218:221], v145 offset:6144
	ds_read_b128 v[222:225], v145 offset:7168
	global_load_lds_dwordx4 v[142:143], off
	v_lshl_add_u64 v[142:143], s[14:15], 0, v[140:141]
	s_add_i32 m0, s21, 0xe000
	s_nop 0
	global_load_lds_dwordx4 v[142:143], off
	s_waitcnt vmcnt(8)
	s_waitcnt lgkmcnt(0)
	s_barrier
	s_waitcnt lgkmcnt(0)
	v_mfma_f32_16x16x32_bf16 v[124:127], v[146:149], v[178:181], v[124:127]
	v_mfma_f32_16x16x32_bf16 v[120:123], v[154:157], v[178:181], v[120:123]
	v_mfma_f32_16x16x32_bf16 v[116:119], v[146:149], v[186:189], v[116:119]
	v_mfma_f32_16x16x32_bf16 v[108:111], v[154:157], v[186:189], v[108:111]
	v_mfma_f32_16x16x32_bf16 v[100:103], v[146:149], v[210:213], v[100:103]
	v_mfma_f32_16x16x32_bf16 v[92:95], v[154:157], v[210:213], v[92:95]
	v_mfma_f32_16x16x32_bf16 v[84:87], v[146:149], v[218:221], v[84:87]
	v_mfma_f32_16x16x32_bf16 v[76:79], v[154:157], v[218:221], v[76:79]
	v_mfma_f32_16x16x32_bf16 v[124:127], v[150:153], v[182:185], v[124:127]
	v_mfma_f32_16x16x32_bf16 v[120:123], v[158:161], v[182:185], v[120:123]
	v_mfma_f32_16x16x32_bf16 v[116:119], v[150:153], v[206:209], v[116:119]
	v_mfma_f32_16x16x32_bf16 v[108:111], v[158:161], v[206:209], v[108:111]
	v_mfma_f32_16x16x32_bf16 v[100:103], v[150:153], v[214:217], v[100:103]
	v_mfma_f32_16x16x32_bf16 v[92:95], v[158:161], v[214:217], v[92:95]
	v_mfma_f32_16x16x32_bf16 v[84:87], v[150:153], v[222:225], v[84:87]
	v_mfma_f32_16x16x32_bf16 v[76:79], v[158:161], v[222:225], v[76:79]
	v_mfma_f32_16x16x32_bf16 v[112:115], v[162:165], v[178:181], v[112:115]
	v_mfma_f32_16x16x32_bf16 v[104:107], v[170:173], v[178:181], v[104:107]
	v_mfma_f32_16x16x32_bf16 v[96:99], v[162:165], v[186:189], v[96:99]
	v_mfma_f32_16x16x32_bf16 v[88:91], v[170:173], v[186:189], v[88:91]
	v_mfma_f32_16x16x32_bf16 v[80:83], v[162:165], v[210:213], v[80:83]
	v_mfma_f32_16x16x32_bf16 v[72:75], v[170:173], v[210:213], v[72:75]
	v_mfma_f32_16x16x32_bf16 v[68:71], v[162:165], v[218:221], v[68:71]
	v_mfma_f32_16x16x32_bf16 v[64:67], v[170:173], v[218:221], v[64:67]
	v_mfma_f32_16x16x32_bf16 v[112:115], v[166:169], v[182:185], v[112:115]
	v_mfma_f32_16x16x32_bf16 v[104:107], v[174:177], v[182:185], v[104:107]
	v_mfma_f32_16x16x32_bf16 v[96:99], v[166:169], v[206:209], v[96:99]
	v_mfma_f32_16x16x32_bf16 v[88:91], v[174:177], v[206:209], v[88:91]
	v_mfma_f32_16x16x32_bf16 v[80:83], v[166:169], v[214:217], v[80:83]
	v_mfma_f32_16x16x32_bf16 v[72:75], v[174:177], v[214:217], v[72:75]
	v_mfma_f32_16x16x32_bf16 v[68:71], v[166:169], v[222:225], v[68:71]
	v_mfma_f32_16x16x32_bf16 v[64:67], v[174:177], v[222:225], v[64:67]
	s_barrier
	s_add_i32 s38, s38, s20
	v_lshl_add_u64 v[142:143], s[16:17], 0, v[132:133]
	s_mov_b32 m0, s38
	ds_read_b128 v[178:181], v145 offset:16384
	ds_read_b128 v[182:185], v145 offset:17408
	ds_read_b128 v[186:189], v145 offset:18432
	ds_read_b128 v[206:209], v145 offset:19456
	ds_read_b128 v[210:213], v145 offset:20480
	ds_read_b128 v[214:217], v145 offset:21504
	ds_read_b128 v[218:221], v145 offset:22528
	ds_read_b128 v[222:225], v145 offset:23552
	global_load_lds_dwordx4 v[142:143], off
	s_add_i32 m0, s38, 0x2000
	s_add_u32 s38, s16, 0x80000
	v_lshl_add_u64 v[190:191], s[16:17], 0, v[128:129]
	s_addc_u32 s39, s17, 0
	s_add_i32 s40, s40, s20
	global_load_lds_dwordx4 v[190:191], off
	v_lshl_add_u64 v[226:227], s[38:39], 0, v[132:133]
	s_mov_b32 m0, s40
	v_lshl_add_u64 v[228:229], s[18:19], 0, v[130:131]
	global_load_lds_dwordx4 v[226:227], off
	v_lshl_add_u64 v[226:227], s[38:39], 0, v[128:129]
	s_add_i32 m0, s40, 0x2000
	s_nop 0
	global_load_lds_dwordx4 v[226:227], off
	v_lshl_add_u64 v[226:227], s[18:19], 0, v[134:135]
	s_mov_b32 m0, s21
	s_nop 0
	global_load_lds_dwordx4 v[226:227], off
	s_mov_b32 m0, s22
	s_nop 0
	global_load_lds_dwordx4 v[228:229], off
	s_waitcnt vmcnt(8)
	s_waitcnt lgkmcnt(0)
	s_barrier
; #define PG8_STAGE(bufoff, gbase, voff) do { _Pragma("unroll") for (int _i = 0; _i < 2; ++_i) \
;         __builtin_amdgcn_global_load_lds((const unsigned*)((const char*)(gbase) + (voff)[_i]), (LAS unsigned*)(lds + (bufoff) + ldsw + _i * 8192), 16, 0, 0); } while (0)
; #define PG8_LDA(dst, b, h) do { _Pragma("unroll") for (int m = 0; m < 4; ++m) _Pragma("unroll") for (int k = 0; k < 2; ++k) dst[m][k] = *(const LAS bf16x8*)(lds + PG8_SA(b, h) + aoff + m * 2048 + k * 1024); } while (0)
; #define PG8_LDB(dst, b, h) do { _Pragma("unroll") for (int n = 0; n < 2; ++n) _Pragma("unroll") for (int k = 0; k < 2; ++k) dst[n][k] = *(const LAS bf16x8*)(lds + PG8_SB(b, h) + boff + n * 2048 + k * 1024); } while (0)
; #define PG8_MMA(ai, bj, At, Bt) do { __builtin_amdgcn_s_setprio(1); _Pragma("unroll") for (int m = 0; m < 4; ++m) _Pragma("unroll") for (int n = 0; n < 2; ++n) _Pragma("unroll") for (int k = 0; k < 2; ++k) \
;         acc[ai][bj][m][n] = __builtin_amdgcn_mfma_f32_16x16x32_bf16(Bt[n][k], At[m][k], acc[ai][bj][m][n], 0, 0, 0); __builtin_amdgcn_s_setprio(0); } while (0)
; #define PG8_WAIT_V(n) asm volatile("s_waitcnt vmcnt(" #n ")" ::: "memory")
; #define PG8_WAIT_L(n) asm volatile("s_waitcnt lgkmcnt(" #n ")" ::: "memory")
; template <class Epi, bool PERMA = false, bool DUAL = false, bool ALIGN_EPI = true, bool SP2 = true>
; __device__ __forceinline__ void gemm_phase(LAS unsigned char* lds, const Gemm g, const StaticOrder& S, const Epi& E) {
;     ...
;             PG8_WAIT_V(8); PG8_WAIT_L(0); PG8_BAR; PG8_MMA(0, 0, At, B0); PG8_MMA(0, 1, At, B1); PG8_BAR; PG8_SCHED;
;             PG8_LDA(At, 0, 1); PG8_STAGE(PG8_SB(0, 0), b2, voffB); PG8_STAGE(PG8_SB(0, 1), b2 + hstepB, voffB); PG8_STAGE(PG8_SA(0, 0), a2, voffA);
;             PG8_WAIT_V(8); PG8_WAIT_L(0); PG8_BAR; PG8_MMA(1, 0, At, B0); PG8_MMA(1, 1, At, B1); PG8_BAR; PG8_SCHED;
;             PG8_LDB(B0, 1, 0); PG8_LDB(B1, 1, 1); PG8_SCHED; PG8_LDA(At, 1, 0); PG8_STAGE(PG8_SA(0, 1), a2 + hstepA, voffA);
;             PG8_WAIT_V(8); PG8_WAIT_L(0); PG8_BAR; PG8_MMA(0, 0, At, B0); PG8_MMA(0, 1, At, B1); PG8_BAR; PG8_SCHED;
;             PG8_LDA(At, 1, 1); PG8_STAGE(PG8_SB(1, 0), b3, voffB); PG8_STAGE(PG8_SB(1, 1), b3 + hstepB, voffB); PG8_STAGE(PG8_SA(1, 0), a3, voffA);
;             PG8_WAIT_V(8); PG8_WAIT_L(0); PG8_BAR; PG8_MMA(1, 0, At, B0); PG8_MMA(1, 1, At, B1); PG8_BAR; PG8_SCHED;
	s_waitcnt lgkmcnt(0)
	v_mfma_f32_16x16x32_bf16 v[60:63], v[146:149], v[178:181], v[60:63]
	v_mfma_f32_16x16x32_bf16 v[56:59], v[154:157], v[178:181], v[56:59]
	v_mfma_f32_16x16x32_bf16 v[52:55], v[146:149], v[186:189], v[52:55]
	v_mfma_f32_16x16x32_bf16 v[44:47], v[154:157], v[186:189], v[44:47]
	v_mfma_f32_16x16x32_bf16 v[36:39], v[146:149], v[210:213], v[36:39]
	v_mfma_f32_16x16x32_bf16 v[28:31], v[154:157], v[210:213], v[28:31]
	v_mfma_f32_16x16x32_bf16 v[20:23], v[146:149], v[218:221], v[20:23]
	v_mfma_f32_16x16x32_bf16 v[12:15], v[154:157], v[218:221], v[12:15]
	v_mfma_f32_16x16x32_bf16 v[60:63], v[150:153], v[182:185], v[60:63]
	v_mfma_f32_16x16x32_bf16 v[56:59], v[158:161], v[182:185], v[56:59]
	v_mfma_f32_16x16x32_bf16 v[52:55], v[150:153], v[206:209], v[52:55]
	v_mfma_f32_16x16x32_bf16 v[44:47], v[158:161], v[206:209], v[44:47]
	v_mfma_f32_16x16x32_bf16 v[36:39], v[150:153], v[214:217], v[36:39]
	v_mfma_f32_16x16x32_bf16 v[28:31], v[158:161], v[214:217], v[28:31]
	v_mfma_f32_16x16x32_bf16 v[20:23], v[150:153], v[222:225], v[20:23]
	v_mfma_f32_16x16x32_bf16 v[12:15], v[158:161], v[222:225], v[12:15]
	v_mfma_f32_16x16x32_bf16 v[48:51], v[162:165], v[178:181], v[48:51]
	v_mfma_f32_16x16x32_bf16 v[40:43], v[170:173], v[178:181], v[40:43]
	v_mfma_f32_16x16x32_bf16 v[32:35], v[162:165], v[186:189], v[32:35]
	v_mfma_f32_16x16x32_bf16 v[24:27], v[170:173], v[186:189], v[24:27]
	v_mfma_f32_16x16x32_bf16 v[16:19], v[162:165], v[210:213], v[16:19]
	v_mfma_f32_16x16x32_bf16 v[8:11], v[170:173], v[210:213], v[8:11]
	v_mfma_f32_16x16x32_bf16 v[4:7], v[162:165], v[218:221], v[4:7]
	v_mfma_f32_16x16x32_bf16 v[0:3], v[170:173], v[218:221], v[0:3]
	v_mfma_f32_16x16x32_bf16 v[48:51], v[166:169], v[182:185], v[48:51]
	v_mfma_f32_16x16x32_bf16 v[40:43], v[174:177], v[182:185], v[40:43]
	v_mfma_f32_16x16x32_bf16 v[32:35], v[166:169], v[206:209], v[32:35]
	v_mfma_f32_16x16x32_bf16 v[24:27], v[174:177], v[206:209], v[24:27]
	v_mfma_f32_16x16x32_bf16 v[16:19], v[166:169], v[214:217], v[16:19]
	v_mfma_f32_16x16x32_bf16 v[8:11], v[174:177], v[214:217], v[8:11]
	v_mfma_f32_16x16x32_bf16 v[4:7], v[166:169], v[222:225], v[4:7]
	v_mfma_f32_16x16x32_bf16 v[0:3], v[174:177], v[222:225], v[0:3]
	s_barrier
	s_add_i32 s38, 0, 0x18000
	s_add_i32 s39, 0, 0x1c000
	v_add_u32_e32 v158, s38, v144
	v_add_u32_e32 v174, s39, v144
	ds_read_b128 v[146:149], v158
	ds_read_b128 v[150:153], v158 offset:1024
	ds_read_b128 v[154:157], v158 offset:2048
	ds_read_b128 v[158:161], v158 offset:3072
	ds_read_b128 v[162:165], v174
	ds_read_b128 v[166:169], v174 offset:1024
	ds_read_b128 v[170:173], v174 offset:2048
	ds_read_b128 v[174:177], v174 offset:3072
	s_add_u32 s18, s18, 0x100000
	s_addc_u32 s19, s19, 0
	s_mov_b32 m0, s23
	v_lshl_add_u64 v[238:239], s[18:19], 0, v[134:135]
	ds_read_b128 v[178:181], v145 offset:32768
	ds_read_b128 v[182:185], v145 offset:33792
	ds_read_b128 v[186:189], v145 offset:34816
	ds_read_b128 v[206:209], v145 offset:35840
	ds_read_b128 v[210:213], v145 offset:36864
	ds_read_b128 v[214:217], v145 offset:37888
	ds_read_b128 v[218:221], v145 offset:38912
	ds_read_b128 v[222:225], v145 offset:39936
	global_load_lds_dwordx4 v[238:239], off
	v_lshl_add_u64 v[238:239], s[18:19], 0, v[130:131]
	s_mov_b32 m0, s24
	s_nop 0
	global_load_lds_dwordx4 v[238:239], off
	s_waitcnt vmcnt(8)
	s_waitcnt lgkmcnt(0)
	s_barrier
	s_waitcnt lgkmcnt(0)
	v_mfma_f32_16x16x32_bf16 v[124:127], v[146:149], v[178:181], v[124:127]
	v_mfma_f32_16x16x32_bf16 v[120:123], v[154:157], v[178:181], v[120:123]
	v_mfma_f32_16x16x32_bf16 v[116:119], v[146:149], v[186:189], v[116:119]
	v_mfma_f32_16x16x32_bf16 v[108:111], v[154:157], v[186:189], v[108:111]
	v_mfma_f32_16x16x32_bf16 v[100:103], v[146:149], v[210:213], v[100:103]
	v_mfma_f32_16x16x32_bf16 v[92:95], v[154:157], v[210:213], v[92:95]
	v_mfma_f32_16x16x32_bf16 v[84:87], v[146:149], v[218:221], v[84:87]
	v_mfma_f32_16x16x32_bf16 v[76:79], v[154:157], v[218:221], v[76:79]
	v_mfma_f32_16x16x32_bf16 v[124:127], v[150:153], v[182:185], v[124:127]
	v_mfma_f32_16x16x32_bf16 v[120:123], v[158:161], v[182:185], v[120:123]
	v_mfma_f32_16x16x32_bf16 v[116:119], v[150:153], v[206:209], v[116:119]
	v_mfma_f32_16x16x32_bf16 v[108:111], v[158:161], v[206:209], v[108:111]
	v_mfma_f32_16x16x32_bf16 v[100:103], v[150:153], v[214:217], v[100:103]
	v_mfma_f32_16x16x32_bf16 v[92:95], v[158:161], v[214:217], v[92:95]
	v_mfma_f32_16x16x32_bf16 v[84:87], v[150:153], v[222:225], v[84:87]
	v_mfma_f32_16x16x32_bf16 v[76:79], v[158:161], v[222:225], v[76:79]
	v_mfma_f32_16x16x32_bf16 v[112:115], v[162:165], v[178:181], v[112:115]
	v_mfma_f32_16x16x32_bf16 v[104:107], v[170:173], v[178:181], v[104:107]
	v_mfma_f32_16x16x32_bf16 v[96:99], v[162:165], v[186:189], v[96:99]
	v_mfma_f32_16x16x32_bf16 v[88:91], v[170:173], v[186:189], v[88:91]
	v_mfma_f32_16x16x32_bf16 v[80:83], v[162:165], v[210:213], v[80:83]
	v_mfma_f32_16x16x32_bf16 v[72:75], v[170:173], v[210:213], v[72:75]
	v_mfma_f32_16x16x32_bf16 v[68:71], v[162:165], v[218:221], v[68:71]
	v_mfma_f32_16x16x32_bf16 v[64:67], v[170:173], v[218:221], v[64:67]
	v_mfma_f32_16x16x32_bf16 v[112:115], v[166:169], v[182:185], v[112:115]
	v_mfma_f32_16x16x32_bf16 v[104:107], v[174:177], v[182:185], v[104:107]
	v_mfma_f32_16x16x32_bf16 v[96:99], v[166:169], v[206:209], v[96:99]
	v_mfma_f32_16x16x32_bf16 v[88:91], v[174:177], v[206:209], v[88:91]
	v_mfma_f32_16x16x32_bf16 v[80:83], v[166:169], v[214:217], v[80:83]
	v_mfma_f32_16x16x32_bf16 v[72:75], v[174:177], v[214:217], v[72:75]
	v_mfma_f32_16x16x32_bf16 v[68:71], v[166:169], v[222:225], v[68:71]
	v_mfma_f32_16x16x32_bf16 v[64:67], v[174:177], v[222:225], v[64:67]
	s_barrier
; #define PG8_STAGE(bufoff, gbase, voff) do { _Pragma("unroll") for (int _i = 0; _i < 2; ++_i) \
;         __builtin_amdgcn_global_load_lds((const unsigned*)((const char*)(gbase) + (voff)[_i]), (LAS unsigned*)(lds + (bufoff) + ldsw + _i * 8192), 16, 0, 0); } while (0)
; #define PG8_LDA(dst, b, h) do { _Pragma("unroll") for (int m = 0; m < 4; ++m) _Pragma("unroll") for (int k = 0; k < 2; ++k) dst[m][k] = *(const LAS bf16x8*)(lds + PG8_SA(b, h) + aoff + m * 2048 + k * 1024); } while (0)
; #define PG8_LDB(dst, b, h) do { _Pragma("unroll") for (int n = 0; n < 2; ++n) _Pragma("unroll") for (int k = 0; k < 2; ++k) dst[n][k] = *(const LAS bf16x8*)(lds + PG8_SB(b, h) + boff + n * 2048 + k * 1024); } while (0)
; #define PG8_MMA(ai, bj, At, Bt) do { __builtin_amdgcn_s_setprio(1); _Pragma("unroll") for (int m = 0; m < 4; ++m) _Pragma("unroll") for (int n = 0; n < 2; ++n) _Pragma("unroll") for (int k = 0; k < 2; ++k) \
;         acc[ai][bj][m][n] = __builtin_amdgcn_mfma_f32_16x16x32_bf16(Bt[n][k], At[m][k], acc[ai][bj][m][n], 0, 0, 0); __builtin_amdgcn_s_setprio(0); } while (0)
; #define PG8_WAIT_V(n) asm volatile("s_waitcnt vmcnt(" #n ")" ::: "memory")
; #define PG8_WAIT_L(n) asm volatile("s_waitcnt lgkmcnt(" #n ")" ::: "memory")
; #define PG8_BAR __builtin_amdgcn_s_barrier()
; #define PG8_SCHED __builtin_amdgcn_sched_barrier(0)
; template <class Epi, bool PERMA = false, bool DUAL = false, bool ALIGN_EPI = true, bool SP2 = true>
; __device__ __forceinline__ void gemm_phase(LAS unsigned char* lds, const Gemm g, const StaticOrder& S, const Epi& E) {
;     ...
;             PG8_LDB(B0, 1, 0); PG8_LDB(B1, 1, 1); PG8_SCHED; PG8_LDA(At, 1, 0); PG8_STAGE(PG8_SA(0, 1), a2 + hstepA, voffA);
;             PG8_WAIT_V(8); PG8_WAIT_L(0); PG8_BAR; PG8_MMA(0, 0, At, B0); PG8_MMA(0, 1, At, B1); PG8_BAR; PG8_SCHED;
;             PG8_LDA(At, 1, 1); PG8_STAGE(PG8_SB(1, 0), b3, voffB); PG8_STAGE(PG8_SB(1, 1), b3 + hstepB, voffB); PG8_STAGE(PG8_SA(1, 0), a3, voffA);
;             PG8_WAIT_V(8); PG8_WAIT_L(0); PG8_BAR; PG8_MMA(1, 0, At, B0); PG8_MMA(1, 1, At, B1); PG8_BAR; PG8_SCHED;
	s_add_i32 s18, s38, s20
	v_lshl_add_u64 v[142:143], v[142:143], 0, s[46:47]
	s_mov_b32 m0, s18
	ds_read_b128 v[178:181], v145 offset:49152
	ds_read_b128 v[182:185], v145 offset:50176
	ds_read_b128 v[186:189], v145 offset:51200
	ds_read_b128 v[206:209], v145 offset:52224
	ds_read_b128 v[210:213], v145 offset:53248
	ds_read_b128 v[214:217], v145 offset:54272
	ds_read_b128 v[218:221], v145 offset:55296
	ds_read_b128 v[222:225], v145 offset:56320
	global_load_lds_dwordx4 v[142:143], off
	s_add_i32 m0, s18, 0x2000
	s_add_u32 s16, s16, 0x80080
	v_lshl_add_u64 v[142:143], v[190:191], 0, s[46:47]
	s_addc_u32 s17, s17, 0
	s_add_i32 s18, s39, s20
	global_load_lds_dwordx4 v[142:143], off
	v_lshl_add_u64 v[142:143], s[16:17], 0, v[132:133]
	s_mov_b32 m0, s18
	s_nop 0
	global_load_lds_dwordx4 v[142:143], off
	v_lshl_add_u64 v[142:143], s[16:17], 0, v[128:129]
	s_add_i32 m0, s18, 0x2000
	s_nop 0
	global_load_lds_dwordx4 v[142:143], off
	v_lshl_add_u64 v[142:143], v[226:227], 0, s[46:47]
	s_mov_b32 m0, s27
	s_nop 0
	global_load_lds_dwordx4 v[142:143], off
	v_lshl_add_u64 v[142:143], v[228:229], 0, s[46:47]
	s_mov_b32 m0, s28
	s_nop 0
	global_load_lds_dwordx4 v[142:143], off
	s_waitcnt vmcnt(8)
	s_waitcnt lgkmcnt(0)
	s_barrier
	s_waitcnt lgkmcnt(0)
	v_mfma_f32_16x16x32_bf16 v[60:63], v[146:149], v[178:181], v[60:63]
	v_mfma_f32_16x16x32_bf16 v[56:59], v[154:157], v[178:181], v[56:59]
	v_mfma_f32_16x16x32_bf16 v[52:55], v[146:149], v[186:189], v[52:55]
	v_mfma_f32_16x16x32_bf16 v[44:47], v[154:157], v[186:189], v[44:47]
	v_mfma_f32_16x16x32_bf16 v[36:39], v[146:149], v[210:213], v[36:39]
	v_mfma_f32_16x16x32_bf16 v[28:31], v[154:157], v[210:213], v[28:31]
	v_mfma_f32_16x16x32_bf16 v[20:23], v[146:149], v[218:221], v[20:23]
	v_mfma_f32_16x16x32_bf16 v[12:15], v[154:157], v[218:221], v[12:15]
	v_mfma_f32_16x16x32_bf16 v[60:63], v[150:153], v[182:185], v[60:63]
	v_mfma_f32_16x16x32_bf16 v[56:59], v[158:161], v[182:185], v[56:59]
	v_mfma_f32_16x16x32_bf16 v[52:55], v[150:153], v[206:209], v[52:55]
	v_mfma_f32_16x16x32_bf16 v[44:47], v[158:161], v[206:209], v[44:47]
	v_mfma_f32_16x16x32_bf16 v[36:39], v[150:153], v[214:217], v[36:39]
	v_mfma_f32_16x16x32_bf16 v[28:31], v[158:161], v[214:217], v[28:31]
	v_mfma_f32_16x16x32_bf16 v[20:23], v[150:153], v[222:225], v[20:23]
	v_mfma_f32_16x16x32_bf16 v[12:15], v[158:161], v[222:225], v[12:15]
	v_mfma_f32_16x16x32_bf16 v[48:51], v[162:165], v[178:181], v[48:51]
	v_mfma_f32_16x16x32_bf16 v[40:43], v[170:173], v[178:181], v[40:43]
	v_mfma_f32_16x16x32_bf16 v[32:35], v[162:165], v[186:189], v[32:35]
	v_mfma_f32_16x16x32_bf16 v[24:27], v[170:173], v[186:189], v[24:27]
	v_mfma_f32_16x16x32_bf16 v[16:19], v[162:165], v[210:213], v[16:19]
	v_mfma_f32_16x16x32_bf16 v[8:11], v[170:173], v[210:213], v[8:11]
	v_mfma_f32_16x16x32_bf16 v[4:7], v[162:165], v[218:221], v[4:7]
	v_mfma_f32_16x16x32_bf16 v[0:3], v[170:173], v[218:221], v[0:3]
	v_mfma_f32_16x16x32_bf16 v[48:51], v[166:169], v[182:185], v[48:51]
	v_mfma_f32_16x16x32_bf16 v[40:43], v[174:177], v[182:185], v[40:43]
	v_mfma_f32_16x16x32_bf16 v[32:35], v[166:169], v[206:209], v[32:35]
	v_mfma_f32_16x16x32_bf16 v[24:27], v[174:177], v[206:209], v[24:27]
	v_mfma_f32_16x16x32_bf16 v[16:19], v[166:169], v[214:217], v[16:19]
	v_mfma_f32_16x16x32_bf16 v[8:11], v[174:177], v[214:217], v[8:11]
	v_mfma_f32_16x16x32_bf16 v[4:7], v[166:169], v[222:225], v[4:7]
	v_mfma_f32_16x16x32_bf16 v[0:3], v[174:177], v[222:225], v[0:3]
	s_barrier
	s_add_i32 s37, s37, 2
	s_add_u32 s14, s14, 0x100
	s_addc_u32 s15, s15, 0
	s_add_u32 s35, s35, 0x100
	s_addc_u32 s36, s36, 0
	s_cmp_gt_u32 s37, 29
	s_cbranch_scc0 .LBB0_405
	s_and_b64 vcc, exec, s[4:5]
	s_cbranch_vccz .LBB0_408
	s_barrier

; #define PG8_STAGE(bufoff, gbase, voff) do { _Pragma("unroll") for (int _i = 0; _i < 2; ++_i) \
;         __builtin_amdgcn_global_load_lds((const unsigned*)((const char*)(gbase) + (voff)[_i]), (LAS unsigned*)(lds + (bufoff) + ldsw + _i * 8192), 16, 0, 0); } while (0)
; #define PG8_LDA(dst, b, h) do { _Pragma("unroll") for (int m = 0; m < 4; ++m) _Pragma("unroll") for (int k = 0; k < 2; ++k) dst[m][k] = *(const LAS bf16x8*)(lds + PG8_SA(b, h) + aoff + m * 2048 + k * 1024); } while (0)
; #define PG8_LDB(dst, b, h) do { _Pragma("unroll") for (int n = 0; n < 2; ++n) _Pragma("unroll") for (int k = 0; k < 2; ++k) dst[n][k] = *(const LAS bf16x8*)(lds + PG8_SB(b, h) + boff + n * 2048 + k * 1024); } while (0)
; #define PG8_MMA(ai, bj, At, Bt) do { __builtin_amdgcn_s_setprio(1); _Pragma("unroll") for (int m = 0; m < 4; ++m) _Pragma("unroll") for (int n = 0; n < 2; ++n) _Pragma("unroll") for (int k = 0; k < 2; ++k) \
;         acc[ai][bj][m][n] = __builtin_amdgcn_mfma_f32_16x16x32_bf16(Bt[n][k], At[m][k], acc[ai][bj][m][n], 0, 0, 0); __builtin_amdgcn_s_setprio(0); } while (0)
; #define PG8_WAIT_V(n) asm volatile("s_waitcnt vmcnt(" #n ")" ::: "memory")
; #define PG8_WAIT_L(n) asm volatile("s_waitcnt lgkmcnt(" #n ")" ::: "memory")
; template <class Epi, bool PERMA = false, bool DUAL = false, bool ALIGN_EPI = true, bool SP2 = true>
; __device__ __forceinline__ void gemm_phase(LAS unsigned char* lds, const Gemm g, const StaticOrder& S, const Epi& E) {
;     ...
;         for (int t = 0; t < nt; t += 2) {
;             const bool last = (t == nt - 2);
;             const char* a1 = cA + (size_t)(t + 1) * kstep;
;             const char* a2 = last ? nA : cA + (size_t)(t + 2) * kstep; const char* b2 = last ? nB : cB + (size_t)(t + 2) * kstep;
;             const char* a3 = a2 + kstep; const char* b3 = b2 + kstep;
;             if constexpr (SP2) {
;             PG8_LDB(B0, 0, 0); PG8_LDB(B1, 0, 1); PG8_SCHED; PG8_LDA(At, 0, 0); PG8_STAGE(PG8_SA(1, 1), a1 + hstepA, voffA);
;             PG8_WAIT_V(8); PG8_WAIT_L(0); PG8_BAR; PG8_MMA(0, 0, At, B0); PG8_MMA(0, 1, At, B1); PG8_BAR; PG8_SCHED;
;             PG8_LDA(At, 0, 1); PG8_STAGE(PG8_SB(0, 0), b2, voffB); PG8_STAGE(PG8_SB(0, 1), b2 + hstepB, voffB); PG8_STAGE(PG8_SA(0, 0), a2, voffA);
;             PG8_WAIT_V(8); PG8_WAIT_L(0); PG8_BAR; PG8_MMA(1, 0, At, B0); PG8_MMA(1, 1, At, B1); PG8_BAR; PG8_SCHED;
.LBB0_528:
	s_add_u32 s22, s20, 0x100
	s_addc_u32 s23, s21, 0
	s_add_i32 s52, 0, 0x10000
	s_cmp_eq_u32 s51, 28
	s_cselect_b32 s27, s15, s23
	s_cselect_b32 s26, s39, s22
	s_cselect_b32 s25, s13, s50
	s_cselect_b32 s24, s48, s49
	s_add_i32 s53, 0, 0x14000
	v_add_u32_e32 v108, s52, v193
	v_add_u32_e32 v124, s53, v193
	ds_read_b128 v[96:99], v108
	ds_read_b128 v[100:103], v108 offset:1024
	ds_read_b128 v[104:107], v108 offset:2048
	ds_read_b128 v[108:111], v108 offset:3072
	ds_read_b128 v[112:115], v124
	ds_read_b128 v[116:119], v124 offset:1024
	ds_read_b128 v[120:123], v124 offset:2048
	ds_read_b128 v[124:127], v124 offset:3072
	v_lshl_add_u64 v[220:221], s[20:21], 0, v[216:217]
	s_add_i32 m0, s29, 0xc000
	ds_read_b128 v[128:131], v224
	ds_read_b128 v[132:135], v224 offset:1024
	ds_read_b128 v[136:139], v224 offset:2048
	ds_read_b128 v[144:147], v224 offset:3072
	ds_read_b128 v[152:155], v224 offset:4096
	ds_read_b128 v[160:163], v224 offset:5120
	ds_read_b128 v[168:171], v224 offset:6144
	ds_read_b128 v[188:191], v224 offset:7168
	global_load_lds_dwordx4 v[220:221], off
	v_lshl_add_u64 v[220:221], s[20:21], 0, v[218:219]
	s_add_i32 m0, s29, 0xe000
	s_nop 0
	global_load_lds_dwordx4 v[220:221], off
	s_waitcnt vmcnt(8)
	s_waitcnt lgkmcnt(0)
	s_barrier
	s_waitcnt lgkmcnt(0)
	v_mfma_f32_16x16x32_bf16 v[184:187], v[96:99], v[128:131], v[184:187]
	v_mfma_f32_16x16x32_bf16 v[92:95], v[104:107], v[128:131], v[92:95]
	v_mfma_f32_16x16x32_bf16 v[180:183], v[96:99], v[136:139], v[180:183]
	v_mfma_f32_16x16x32_bf16 v[88:91], v[104:107], v[136:139], v[88:91]
	v_mfma_f32_16x16x32_bf16 v[176:179], v[96:99], v[152:155], v[176:179]
	v_mfma_f32_16x16x32_bf16 v[84:87], v[104:107], v[152:155], v[84:87]
	v_mfma_f32_16x16x32_bf16 v[172:175], v[96:99], v[168:171], v[172:175]
	v_mfma_f32_16x16x32_bf16 v[80:83], v[104:107], v[168:171], v[80:83]
	v_mfma_f32_16x16x32_bf16 v[184:187], v[100:103], v[132:135], v[184:187]
	v_mfma_f32_16x16x32_bf16 v[92:95], v[108:111], v[132:135], v[92:95]
	v_mfma_f32_16x16x32_bf16 v[180:183], v[100:103], v[144:147], v[180:183]
	v_mfma_f32_16x16x32_bf16 v[88:91], v[108:111], v[144:147], v[88:91]
	v_mfma_f32_16x16x32_bf16 v[176:179], v[100:103], v[160:163], v[176:179]
	v_mfma_f32_16x16x32_bf16 v[84:87], v[108:111], v[160:163], v[84:87]
	v_mfma_f32_16x16x32_bf16 v[172:175], v[100:103], v[188:191], v[172:175]
	v_mfma_f32_16x16x32_bf16 v[80:83], v[108:111], v[188:191], v[80:83]
	v_mfma_f32_16x16x32_bf16 v[164:167], v[112:115], v[128:131], v[164:167]
	v_mfma_f32_16x16x32_bf16 v[76:79], v[120:123], v[128:131], v[76:79]
	v_mfma_f32_16x16x32_bf16 v[72:75], v[120:123], v[136:139], v[72:75]
	v_mfma_f32_16x16x32_bf16 v[68:71], v[120:123], v[152:155], v[68:71]
	v_mfma_f32_16x16x32_bf16 v[64:67], v[120:123], v[168:171], v[64:67]
	v_mfma_f32_16x16x32_bf16 v[164:167], v[116:119], v[132:135], v[164:167]
	v_mfma_f32_16x16x32_bf16 v[76:79], v[124:127], v[132:135], v[76:79]
	v_mfma_f32_16x16x32_bf16 v[128:131], v[112:115], v[136:139], v[156:159]
	v_mfma_f32_16x16x32_bf16 v[72:75], v[124:127], v[144:147], v[72:75]
	v_mfma_f32_16x16x32_bf16 v[132:135], v[112:115], v[152:155], v[148:151]
	v_mfma_f32_16x16x32_bf16 v[68:71], v[124:127], v[160:163], v[68:71]
	v_mfma_f32_16x16x32_bf16 v[136:139], v[112:115], v[168:171], v[140:143]
	v_mfma_f32_16x16x32_bf16 v[64:67], v[124:127], v[188:191], v[64:67]
	v_mfma_f32_16x16x32_bf16 v[128:131], v[116:119], v[144:147], v[128:131]
	v_mfma_f32_16x16x32_bf16 v[132:135], v[116:119], v[160:163], v[132:135]
	v_mfma_f32_16x16x32_bf16 v[136:139], v[116:119], v[188:191], v[136:139]
	s_barrier
	s_add_i32 s20, s52, s28
	v_lshl_add_u64 v[220:221], s[24:25], 0, v[210:211]
	s_mov_b32 m0, s20
	ds_read_b128 v[140:143], v224 offset:16384
	ds_read_b128 v[144:147], v224 offset:17408
	ds_read_b128 v[148:151], v224 offset:18432
	ds_read_b128 v[152:155], v224 offset:19456
	ds_read_b128 v[156:159], v224 offset:20480
	ds_read_b128 v[160:163], v224 offset:21504
	ds_read_b128 v[168:171], v224 offset:22528
	ds_read_b128 v[188:191], v224 offset:23552
	global_load_lds_dwordx4 v[220:221], off
	s_add_i32 m0, s20, 0x2000
	s_add_u32 s20, s24, 0x80000
	v_lshl_add_u64 v[238:239], s[24:25], 0, v[206:207]
	s_addc_u32 s21, s25, 0
	s_add_i32 s52, s53, s28
	global_load_lds_dwordx4 v[238:239], off
	v_lshl_add_u64 v[226:227], s[20:21], 0, v[210:211]
	s_mov_b32 m0, s52
	v_lshl_add_u64 v[240:241], s[26:27], 0, v[212:213]
	global_load_lds_dwordx4 v[226:227], off
	v_lshl_add_u64 v[226:227], s[20:21], 0, v[206:207]
	s_add_i32 m0, s52, 0x2000
	v_lshl_add_u64 v[242:243], s[26:27], 0, v[208:209]
	global_load_lds_dwordx4 v[226:227], off
	s_mov_b32 m0, s29
	s_nop 0
	global_load_lds_dwordx4 v[240:241], off
	s_mov_b32 m0, s30
	s_nop 0
	global_load_lds_dwordx4 v[242:243], off
	s_waitcnt vmcnt(8)
	s_waitcnt lgkmcnt(0)
	s_barrier
; #define PG8_STAGE(bufoff, gbase, voff) do { _Pragma("unroll") for (int _i = 0; _i < 2; ++_i) \
;         __builtin_amdgcn_global_load_lds((const unsigned*)((const char*)(gbase) + (voff)[_i]), (LAS unsigned*)(lds + (bufoff) + ldsw + _i * 8192), 16, 0, 0); } while (0)
; #define PG8_LDA(dst, b, h) do { _Pragma("unroll") for (int m = 0; m < 4; ++m) _Pragma("unroll") for (int k = 0; k < 2; ++k) dst[m][k] = *(const LAS bf16x8*)(lds + PG8_SA(b, h) + aoff + m * 2048 + k * 1024); } while (0)
; #define PG8_LDB(dst, b, h) do { _Pragma("unroll") for (int n = 0; n < 2; ++n) _Pragma("unroll") for (int k = 0; k < 2; ++k) dst[n][k] = *(const LAS bf16x8*)(lds + PG8_SB(b, h) + boff + n * 2048 + k * 1024); } while (0)
; #define PG8_MMA(ai, bj, At, Bt) do { __builtin_amdgcn_s_setprio(1); _Pragma("unroll") for (int m = 0; m < 4; ++m) _Pragma("unroll") for (int n = 0; n < 2; ++n) _Pragma("unroll") for (int k = 0; k < 2; ++k) \
;         acc[ai][bj][m][n] = __builtin_amdgcn_mfma_f32_16x16x32_bf16(Bt[n][k], At[m][k], acc[ai][bj][m][n], 0, 0, 0); __builtin_amdgcn_s_setprio(0); } while (0)
; #define PG8_WAIT_V(n) asm volatile("s_waitcnt vmcnt(" #n ")" ::: "memory")
; #define PG8_WAIT_L(n) asm volatile("s_waitcnt lgkmcnt(" #n ")" ::: "memory")
; template <class Epi, bool PERMA = false, bool DUAL = false, bool ALIGN_EPI = true, bool SP2 = true>
; __device__ __forceinline__ void gemm_phase(LAS unsigned char* lds, const Gemm g, const StaticOrder& S, const Epi& E) {
;     ...
;             PG8_WAIT_V(8); PG8_WAIT_L(0); PG8_BAR; PG8_MMA(0, 0, At, B0); PG8_MMA(0, 1, At, B1); PG8_BAR; PG8_SCHED;
;             PG8_LDA(At, 0, 1); PG8_STAGE(PG8_SB(0, 0), b2, voffB); PG8_STAGE(PG8_SB(0, 1), b2 + hstepB, voffB); PG8_STAGE(PG8_SA(0, 0), a2, voffA);
;             PG8_WAIT_V(8); PG8_WAIT_L(0); PG8_BAR; PG8_MMA(1, 0, At, B0); PG8_MMA(1, 1, At, B1); PG8_BAR; PG8_SCHED;
;             PG8_LDB(B0, 1, 0); PG8_LDB(B1, 1, 1); PG8_SCHED; PG8_LDA(At, 1, 0); PG8_STAGE(PG8_SA(0, 1), a2 + hstepA, voffA);
;             PG8_WAIT_V(8); PG8_WAIT_L(0); PG8_BAR; PG8_MMA(0, 0, At, B0); PG8_MMA(0, 1, At, B1); PG8_BAR; PG8_SCHED;
;             PG8_LDA(At, 1, 1); PG8_STAGE(PG8_SB(1, 0), b3, voffB); PG8_STAGE(PG8_SB(1, 1), b3 + hstepB, voffB); PG8_STAGE(PG8_SA(1, 0), a3, voffA);
;             PG8_WAIT_V(8); PG8_WAIT_L(0); PG8_BAR; PG8_MMA(1, 0, At, B0); PG8_MMA(1, 1, At, B1); PG8_BAR; PG8_SCHED;
	s_waitcnt lgkmcnt(0)
	v_mfma_f32_16x16x32_bf16 v[60:63], v[96:99], v[140:143], v[60:63]
	v_mfma_f32_16x16x32_bf16 v[28:31], v[104:107], v[140:143], v[28:31]
	v_mfma_f32_16x16x32_bf16 v[56:59], v[96:99], v[148:151], v[56:59]
	v_mfma_f32_16x16x32_bf16 v[24:27], v[104:107], v[148:151], v[24:27]
	v_mfma_f32_16x16x32_bf16 v[52:55], v[96:99], v[156:159], v[52:55]
	v_mfma_f32_16x16x32_bf16 v[20:23], v[104:107], v[156:159], v[20:23]
	v_mfma_f32_16x16x32_bf16 v[48:51], v[96:99], v[168:171], v[48:51]
	v_mfma_f32_16x16x32_bf16 v[16:19], v[104:107], v[168:171], v[16:19]
	v_mfma_f32_16x16x32_bf16 v[60:63], v[100:103], v[144:147], v[60:63]
	v_mfma_f32_16x16x32_bf16 v[28:31], v[108:111], v[144:147], v[28:31]
	v_mfma_f32_16x16x32_bf16 v[56:59], v[100:103], v[152:155], v[56:59]
	v_mfma_f32_16x16x32_bf16 v[24:27], v[108:111], v[152:155], v[24:27]
	v_mfma_f32_16x16x32_bf16 v[52:55], v[100:103], v[160:163], v[52:55]
	v_mfma_f32_16x16x32_bf16 v[20:23], v[108:111], v[160:163], v[20:23]
	v_mfma_f32_16x16x32_bf16 v[48:51], v[100:103], v[188:191], v[48:51]
	v_mfma_f32_16x16x32_bf16 v[16:19], v[108:111], v[188:191], v[16:19]
	v_mfma_f32_16x16x32_bf16 v[44:47], v[112:115], v[140:143], v[44:47]
	v_mfma_f32_16x16x32_bf16 v[12:15], v[120:123], v[140:143], v[12:15]
	v_mfma_f32_16x16x32_bf16 v[40:43], v[112:115], v[148:151], v[40:43]
	v_mfma_f32_16x16x32_bf16 v[8:11], v[120:123], v[148:151], v[8:11]
	v_mfma_f32_16x16x32_bf16 v[36:39], v[112:115], v[156:159], v[36:39]
	v_mfma_f32_16x16x32_bf16 v[4:7], v[120:123], v[156:159], v[4:7]
	v_mfma_f32_16x16x32_bf16 v[32:35], v[112:115], v[168:171], v[32:35]
	v_mfma_f32_16x16x32_bf16 v[0:3], v[120:123], v[168:171], v[0:3]
	v_mfma_f32_16x16x32_bf16 v[44:47], v[116:119], v[144:147], v[44:47]
	v_mfma_f32_16x16x32_bf16 v[12:15], v[124:127], v[144:147], v[12:15]
	v_mfma_f32_16x16x32_bf16 v[40:43], v[116:119], v[152:155], v[40:43]
	v_mfma_f32_16x16x32_bf16 v[8:11], v[124:127], v[152:155], v[8:11]
	v_mfma_f32_16x16x32_bf16 v[36:39], v[116:119], v[160:163], v[36:39]
	v_mfma_f32_16x16x32_bf16 v[4:7], v[124:127], v[160:163], v[4:7]
	v_mfma_f32_16x16x32_bf16 v[32:35], v[116:119], v[188:191], v[32:35]
	v_mfma_f32_16x16x32_bf16 v[0:3], v[124:127], v[188:191], v[0:3]
	s_barrier
	s_add_i32 s52, 0, 0x18000
	s_add_i32 s53, 0, 0x1c000
	v_add_u32_e32 v108, s52, v193
	v_add_u32_e32 v124, s53, v193
	ds_read_b128 v[96:99], v108
	ds_read_b128 v[100:103], v108 offset:1024
	ds_read_b128 v[104:107], v108 offset:2048
	ds_read_b128 v[108:111], v108 offset:3072
	ds_read_b128 v[112:115], v124
	ds_read_b128 v[116:119], v124 offset:1024
	ds_read_b128 v[120:123], v124 offset:2048
	ds_read_b128 v[124:127], v124 offset:3072
	s_add_u32 s20, s26, 0x80000
	s_addc_u32 s21, s27, 0
	s_mov_b32 m0, s31
	v_lshl_add_u64 v[156:157], s[20:21], 0, v[212:213]
	ds_read_b128 v[140:143], v224 offset:32768
	ds_read_b128 v[144:147], v224 offset:33792
	ds_read_b128 v[148:151], v224 offset:34816
	ds_read_b128 v[152:155], v224 offset:35840
	ds_read_b128 v[160:163], v224 offset:36864
	ds_read_b128 v[168:171], v224 offset:37888
	ds_read_b128 v[188:191], v224 offset:38912
	ds_read_b128 v[226:229], v224 offset:39936
	global_load_lds_dwordx4 v[156:157], off
	v_lshl_add_u64 v[156:157], s[20:21], 0, v[208:209]
	s_mov_b32 m0, s34
	s_nop 0
	global_load_lds_dwordx4 v[156:157], off
	s_waitcnt vmcnt(8)
	s_waitcnt lgkmcnt(0)
	s_barrier
	s_waitcnt lgkmcnt(0)
	v_mfma_f32_16x16x32_bf16 v[156:159], v[96:99], v[140:143], v[184:187]
	v_mfma_f32_16x16x32_bf16 v[184:187], v[100:103], v[144:147], v[156:159]
	v_mfma_f32_16x16x32_bf16 v[156:159], v[96:99], v[148:151], v[180:183]
	v_mfma_f32_16x16x32_bf16 v[180:183], v[100:103], v[152:155], v[156:159]
	v_mfma_f32_16x16x32_bf16 v[156:159], v[96:99], v[160:163], v[176:179]
	v_mfma_f32_16x16x32_bf16 v[92:95], v[104:107], v[140:143], v[92:95]
	v_mfma_f32_16x16x32_bf16 v[88:91], v[104:107], v[148:151], v[88:91]
	v_mfma_f32_16x16x32_bf16 v[176:179], v[100:103], v[168:171], v[156:159]
	v_mfma_f32_16x16x32_bf16 v[84:87], v[104:107], v[160:163], v[84:87]
	v_mfma_f32_16x16x32_bf16 v[156:159], v[96:99], v[188:191], v[172:175]
	v_mfma_f32_16x16x32_bf16 v[80:83], v[104:107], v[188:191], v[80:83]
	v_mfma_f32_16x16x32_bf16 v[92:95], v[108:111], v[144:147], v[92:95]
	v_mfma_f32_16x16x32_bf16 v[88:91], v[108:111], v[152:155], v[88:91]
	v_mfma_f32_16x16x32_bf16 v[84:87], v[108:111], v[168:171], v[84:87]
	v_mfma_f32_16x16x32_bf16 v[172:175], v[100:103], v[226:229], v[156:159]
	v_mfma_f32_16x16x32_bf16 v[80:83], v[108:111], v[226:229], v[80:83]
	v_mfma_f32_16x16x32_bf16 v[156:159], v[112:115], v[140:143], v[164:167]
	v_mfma_f32_16x16x32_bf16 v[128:131], v[112:115], v[148:151], v[128:131]
	v_mfma_f32_16x16x32_bf16 v[164:167], v[116:119], v[144:147], v[156:159]
	v_mfma_f32_16x16x32_bf16 v[156:159], v[116:119], v[152:155], v[128:131]
	v_mfma_f32_16x16x32_bf16 v[128:131], v[112:115], v[160:163], v[132:135]
	v_mfma_f32_16x16x32_bf16 v[76:79], v[120:123], v[140:143], v[76:79]
	v_mfma_f32_16x16x32_bf16 v[72:75], v[120:123], v[148:151], v[72:75]
	v_mfma_f32_16x16x32_bf16 v[148:151], v[116:119], v[168:171], v[128:131]
	v_mfma_f32_16x16x32_bf16 v[68:71], v[120:123], v[160:163], v[68:71]
	v_mfma_f32_16x16x32_bf16 v[128:131], v[112:115], v[188:191], v[136:139]
	v_mfma_f32_16x16x32_bf16 v[64:67], v[120:123], v[188:191], v[64:67]
	v_mfma_f32_16x16x32_bf16 v[76:79], v[124:127], v[144:147], v[76:79]
	v_mfma_f32_16x16x32_bf16 v[72:75], v[124:127], v[152:155], v[72:75]
	v_mfma_f32_16x16x32_bf16 v[68:71], v[124:127], v[168:171], v[68:71]
	v_mfma_f32_16x16x32_bf16 v[140:143], v[116:119], v[226:229], v[128:131]
	v_mfma_f32_16x16x32_bf16 v[64:67], v[124:127], v[226:229], v[64:67]
	s_barrier
; #define PG8_STAGE(bufoff, gbase, voff) do { _Pragma("unroll") for (int _i = 0; _i < 2; ++_i) \
;         __builtin_amdgcn_global_load_lds((const unsigned*)((const char*)(gbase) + (voff)[_i]), (LAS unsigned*)(lds + (bufoff) + ldsw + _i * 8192), 16, 0, 0); } while (0)
; #define PG8_LDA(dst, b, h) do { _Pragma("unroll") for (int m = 0; m < 4; ++m) _Pragma("unroll") for (int k = 0; k < 2; ++k) dst[m][k] = *(const LAS bf16x8*)(lds + PG8_SA(b, h) + aoff + m * 2048 + k * 1024); } while (0)
; #define PG8_LDB(dst, b, h) do { _Pragma("unroll") for (int n = 0; n < 2; ++n) _Pragma("unroll") for (int k = 0; k < 2; ++k) dst[n][k] = *(const LAS bf16x8*)(lds + PG8_SB(b, h) + boff + n * 2048 + k * 1024); } while (0)
; #define PG8_WAIT_V(n) asm volatile("s_waitcnt vmcnt(" #n ")" ::: "memory")
; #define PG8_WAIT_L(n) asm volatile("s_waitcnt lgkmcnt(" #n ")" ::: "memory")
; #define PG8_BAR __builtin_amdgcn_s_barrier()
; #define PG8_SCHED __builtin_amdgcn_sched_barrier(0)
; template <class Epi, bool PERMA = false, bool DUAL = false, bool ALIGN_EPI = true, bool SP2 = true>
; __device__ __forceinline__ void gemm_phase(LAS unsigned char* lds, const Gemm g, const StaticOrder& S, const Epi& E) {
;     ...
;             PG8_LDB(B0, 1, 0); PG8_LDB(B1, 1, 1); PG8_SCHED; PG8_LDA(At, 1, 0); PG8_STAGE(PG8_SA(0, 1), a2 + hstepA, voffA);
;             PG8_WAIT_V(8); PG8_WAIT_L(0); PG8_BAR; PG8_MMA(0, 0, At, B0); PG8_MMA(0, 1, At, B1); PG8_BAR; PG8_SCHED;
;             PG8_LDA(At, 1, 1); PG8_STAGE(PG8_SB(1, 0), b3, voffB); PG8_STAGE(PG8_SB(1, 1), b3 + hstepB, voffB); PG8_STAGE(PG8_SA(1, 0), a3, voffA);
;             PG8_WAIT_V(8); PG8_WAIT_L(0); PG8_BAR; PG8_MMA(1, 0, At, B0); PG8_MMA(1, 1, At, B1); PG8_BAR; PG8_SCHED;
;     __device__ __forceinline__ void operator()(const f32x4 (&acc)[2][2][4][2], const Unit& u, int wr, int wc, int fr, int fq) const {
;     ...
;         f32x4 wgt[2][8];
; #pragma unroll
;         for (int n = 0; n < 2; ++n) { const float* wp = cw + ch0 + 4 * n;
;             wgt[n][0] = *(const f32x4*)wp; wgt[n][1] = *(const f32x4*)(wp + 2 * DFF); wgt[n][2] = *(const f32x4*)(wp + 4 * DFF); wgt[n][3] = *(const f32x4*)(cb + ch0 + 4 * n);
;             wgt[n][4] = *(const f32x4*)(wp + DFF); wgt[n][5] = *(const f32x4*)(wp + 3 * DFF); wgt[n][6] = *(const f32x4*)(wp + 5 * DFF); wgt[n][7] = *(const f32x4*)(cb + DFF + ch0 + 4 * n); }
	s_add_i32 s20, s52, s28
	v_lshl_add_u64 v[220:221], v[220:221], 0, s[56:57]
	s_mov_b32 m0, s20
	ds_read_b128 v[128:131], v224 offset:49152
	ds_read_b128 v[132:135], v224 offset:50176
	ds_read_b128 v[136:139], v224 offset:51200
	ds_read_b128 v[144:147], v224 offset:52224
	ds_read_b128 v[152:155], v224 offset:53248
	ds_read_b128 v[160:163], v224 offset:54272
	ds_read_b128 v[168:171], v224 offset:55296
	ds_read_b128 v[188:191], v224 offset:56320
	global_load_lds_dwordx4 v[220:221], off
	s_add_i32 m0, s20, 0x2000
	s_add_u32 s20, s24, 0x80080
	v_lshl_add_u64 v[220:221], v[238:239], 0, s[56:57]
	s_addc_u32 s21, s25, 0
	s_add_i32 s24, s53, s28
	global_load_lds_dwordx4 v[220:221], off
	v_lshl_add_u64 v[220:221], s[20:21], 0, v[210:211]
	s_mov_b32 m0, s24
	s_nop 0
	global_load_lds_dwordx4 v[220:221], off
	v_lshl_add_u64 v[220:221], s[20:21], 0, v[206:207]
	s_add_i32 m0, s24, 0x2000
	s_nop 0
	global_load_lds_dwordx4 v[220:221], off
	v_lshl_add_u64 v[220:221], v[240:241], 0, s[56:57]
	s_mov_b32 m0, s35
	s_nop 0
	global_load_lds_dwordx4 v[220:221], off
	v_lshl_add_u64 v[220:221], v[242:243], 0, s[56:57]
	s_mov_b32 m0, s36
	s_nop 0
	global_load_lds_dwordx4 v[220:221], off
	s_waitcnt vmcnt(8)
	s_waitcnt lgkmcnt(0)
	s_barrier
	s_waitcnt lgkmcnt(0)
	v_mfma_f32_16x16x32_bf16 v[60:63], v[96:99], v[128:131], v[60:63]
	v_mfma_f32_16x16x32_bf16 v[28:31], v[104:107], v[128:131], v[28:31]
	v_mfma_f32_16x16x32_bf16 v[56:59], v[96:99], v[136:139], v[56:59]
	v_mfma_f32_16x16x32_bf16 v[24:27], v[104:107], v[136:139], v[24:27]
	v_mfma_f32_16x16x32_bf16 v[52:55], v[96:99], v[152:155], v[52:55]
	v_mfma_f32_16x16x32_bf16 v[20:23], v[104:107], v[152:155], v[20:23]
	v_mfma_f32_16x16x32_bf16 v[48:51], v[96:99], v[168:171], v[48:51]
	v_mfma_f32_16x16x32_bf16 v[16:19], v[104:107], v[168:171], v[16:19]
	v_mfma_f32_16x16x32_bf16 v[60:63], v[100:103], v[132:135], v[60:63]
	v_mfma_f32_16x16x32_bf16 v[28:31], v[108:111], v[132:135], v[28:31]
	v_mfma_f32_16x16x32_bf16 v[56:59], v[100:103], v[144:147], v[56:59]
	v_mfma_f32_16x16x32_bf16 v[24:27], v[108:111], v[144:147], v[24:27]
	v_mfma_f32_16x16x32_bf16 v[52:55], v[100:103], v[160:163], v[52:55]
	v_mfma_f32_16x16x32_bf16 v[20:23], v[108:111], v[160:163], v[20:23]
	v_mfma_f32_16x16x32_bf16 v[48:51], v[100:103], v[188:191], v[48:51]
	v_mfma_f32_16x16x32_bf16 v[16:19], v[108:111], v[188:191], v[16:19]
	v_mfma_f32_16x16x32_bf16 v[44:47], v[112:115], v[128:131], v[44:47]
	v_mfma_f32_16x16x32_bf16 v[12:15], v[120:123], v[128:131], v[12:15]
	v_mfma_f32_16x16x32_bf16 v[40:43], v[112:115], v[136:139], v[40:43]
	v_mfma_f32_16x16x32_bf16 v[8:11], v[120:123], v[136:139], v[8:11]
	v_mfma_f32_16x16x32_bf16 v[36:39], v[112:115], v[152:155], v[36:39]
	v_mfma_f32_16x16x32_bf16 v[4:7], v[120:123], v[152:155], v[4:7]
	v_mfma_f32_16x16x32_bf16 v[32:35], v[112:115], v[168:171], v[32:35]
	v_mfma_f32_16x16x32_bf16 v[0:3], v[120:123], v[168:171], v[0:3]
	v_mfma_f32_16x16x32_bf16 v[44:47], v[116:119], v[132:135], v[44:47]
	v_mfma_f32_16x16x32_bf16 v[12:15], v[124:127], v[132:135], v[12:15]
	v_mfma_f32_16x16x32_bf16 v[40:43], v[116:119], v[144:147], v[40:43]
	v_mfma_f32_16x16x32_bf16 v[8:11], v[124:127], v[144:147], v[8:11]
	v_mfma_f32_16x16x32_bf16 v[36:39], v[116:119], v[160:163], v[36:39]
	v_mfma_f32_16x16x32_bf16 v[4:7], v[124:127], v[160:163], v[4:7]
	v_mfma_f32_16x16x32_bf16 v[32:35], v[116:119], v[188:191], v[32:35]
	v_mfma_f32_16x16x32_bf16 v[0:3], v[124:127], v[188:191], v[0:3]
	s_barrier
	s_add_i32 s51, s51, 2
	s_add_u32 s49, s49, 0x100
	s_addc_u32 s50, s50, 0
	s_cmp_gt_u32 s51, 29
	s_mov_b64 s[20:21], s[22:23]
	s_cbranch_scc0 .LBB0_528
	v_lshl_or_b32 v220, s38, 7, v214
	v_ashrrev_i32_e32 v221, 31, v220
	v_lshlrev_b64 v[96:97], 2, v[220:221]
	v_lshl_add_u64 v[112:113], s[2:3], 0, v[96:97]
	v_add_co_u32_e32 v102, vcc, s72, v112
	s_mov_b64 s[20:21], 0xb000
	s_nop 0
	v_addc_co_u32_e32 v103, vcc, 0, v113, vcc
	s_mov_b32 s13, 0x16000
	v_lshl_add_u64 v[100:101], v[112:113], 0, s[20:21]
	s_mov_b64 s[20:21], 0x16000
	v_add_co_u32_e32 v106, vcc, s13, v112
	s_nop 0
	v_lshl_add_u64 v[104:105], v[112:113], 0, s[20:21]
	v_addc_co_u32_e32 v107, vcc, 0, v113, vcc
	v_lshl_add_u64 v[114:115], s[6:7], 0, v[96:97]
	v_lshl_add_u64 v[188:189], s[10:11], 0, v[96:97]
	global_load_dwordx4 v[96:99], v[112:113], off offset:16
	global_load_dwordx4 v[128:131], v[112:113], off
	global_load_dwordx4 v[132:135], v[102:103], off
	s_nop 0
	global_load_dwordx4 v[100:103], v[100:101], off offset:16
	s_nop 0
	global_load_dwordx4 v[136:139], v[106:107], off
	s_nop 0
	global_load_dwordx4 v[104:107], v[104:105], off offset:16
	s_nop 0
	global_load_dwordx4 v[108:111], v[114:115], off offset:16
	global_load_dwordx4 v[144:147], v[114:115], off
	s_movk_i32 s13, 0x5000
	v_add_co_u32_e32 v116, vcc, s13, v112
	s_mov_b64 s[20:21], 0x5800
	s_nop 0
	v_addc_co_u32_e32 v117, vcc, 0, v113, vcc
	s_mov_b32 s13, 0x10000
	v_lshl_add_u64 v[114:115], v[112:113], 0, s[20:21]
	s_mov_b64 s[20:21], 0x10800
	v_add_co_u32_e32 v120, vcc, s13, v112
	global_load_dwordx4 v[160:163], v[116:117], off offset:2048
	s_nop 0
	global_load_dwordx4 v[116:119], v[114:115], off offset:16
	v_lshl_add_u64 v[114:115], v[112:113], 0, s[20:21]
	v_addc_co_u32_e32 v121, vcc, 0, v113, vcc
	s_mov_b64 s[20:21], 0x1b800
	s_mov_b32 s13, 0x1b000
	global_load_dwordx4 v[168:171], v[120:121], off offset:2048
	s_nop 0
	global_load_dwordx4 v[120:123], v[114:115], off offset:16
	v_lshl_add_u64 v[114:115], v[112:113], 0, s[20:21]
	v_add_co_u32_e32 v112, vcc, s13, v112
	s_nop 0
	v_addc_co_u32_e32 v113, vcc, 0, v113, vcc
	global_load_dwordx4 v[152:155], v[112:113], off offset:2048
	s_nop 0
	global_load_dwordx4 v[112:115], v[114:115], off offset:16
	s_nop 0
	global_load_dwordx4 v[124:127], v[188:189], off offset:16
	s_nop 0
	global_load_dwordx4 v[188:191], v[188:189], off
	s_and_b64 vcc, exec, s[4:5]
	s_cbranch_vccz .LBB0_531
	s_barrier

; #define PG8_STAGE(bufoff, gbase, voff) do { _Pragma("unroll") for (int _i = 0; _i < 2; ++_i) \
;         __builtin_amdgcn_global_load_lds((const unsigned*)((const char*)(gbase) + (voff)[_i]), (LAS unsigned*)(lds + (bufoff) + ldsw + _i * 8192), 16, 0, 0); } while (0)
; #define PG8_LDA(dst, b, h) do { _Pragma("unroll") for (int m = 0; m < 4; ++m) _Pragma("unroll") for (int k = 0; k < 2; ++k) dst[m][k] = *(const LAS bf16x8*)(lds + PG8_SA(b, h) + aoff + m * 2048 + k * 1024); } while (0)
; #define PG8_LDB(dst, b, h) do { _Pragma("unroll") for (int n = 0; n < 2; ++n) _Pragma("unroll") for (int k = 0; k < 2; ++k) dst[n][k] = *(const LAS bf16x8*)(lds + PG8_SB(b, h) + boff + n * 2048 + k * 1024); } while (0)
; #define PG8_MMA(ai, bj, At, Bt) do { __builtin_amdgcn_s_setprio(1); _Pragma("unroll") for (int m = 0; m < 4; ++m) _Pragma("unroll") for (int n = 0; n < 2; ++n) _Pragma("unroll") for (int k = 0; k < 2; ++k) \
;         acc[ai][bj][m][n] = __builtin_amdgcn_mfma_f32_16x16x32_bf16(Bt[n][k], At[m][k], acc[ai][bj][m][n], 0, 0, 0); __builtin_amdgcn_s_setprio(0); } while (0)
; #define PG8_WAIT_V(n) asm volatile("s_waitcnt vmcnt(" #n ")" ::: "memory")
; #define PG8_WAIT_L(n) asm volatile("s_waitcnt lgkmcnt(" #n ")" ::: "memory")
; template <class Epi, bool PERMA = false, bool DUAL = false, bool ALIGN_EPI = true, bool SP2 = true>
; __device__ __forceinline__ void gemm_phase(LAS unsigned char* lds, const Gemm g, const StaticOrder& S, const Epi& E) {
;     ...
;         for (int t = 0; t < nt; t += 2) {
;             const bool last = (t == nt - 2);
;             const char* a1 = cA + (size_t)(t + 1) * kstep;
;             const char* a2 = last ? nA : cA + (size_t)(t + 2) * kstep; const char* b2 = last ? nB : cB + (size_t)(t + 2) * kstep;
;             const char* a3 = a2 + kstep; const char* b3 = b2 + kstep;
;             if constexpr (SP2) {
;             PG8_LDB(B0, 0, 0); PG8_LDB(B1, 0, 1); PG8_SCHED; PG8_LDA(At, 0, 0); PG8_STAGE(PG8_SA(1, 1), a1 + hstepA, voffA);
;             PG8_WAIT_V(8); PG8_WAIT_L(0); PG8_BAR; PG8_MMA(0, 0, At, B0); PG8_MMA(0, 1, At, B1); PG8_BAR; PG8_SCHED;
;             PG8_LDA(At, 0, 1); PG8_STAGE(PG8_SB(0, 0), b2, voffB); PG8_STAGE(PG8_SB(0, 1), b2 + hstepB, voffB); PG8_STAGE(PG8_SA(0, 0), a2, voffA);
;             PG8_WAIT_V(8); PG8_WAIT_L(0); PG8_BAR; PG8_MMA(1, 0, At, B0); PG8_MMA(1, 1, At, B1); PG8_BAR; PG8_SCHED;
.LBB0_675:
	s_add_u32 s14, s12, 0x100
	s_addc_u32 s15, s13, 0
	s_add_i32 s36, 0, 0x10000
	s_cmpk_eq_i32 s33, 0x54
	s_cselect_b32 s19, s1, s15
	s_cselect_b32 s18, s0, s14
	s_cselect_b32 s17, s7, s11
	s_cselect_b32 s16, s6, s9
	s_add_i32 s37, 0, 0x14000
	v_add_u32_e32 v116, s36, v193
	v_add_u32_e32 v156, s37, v193
	ds_read_b128 v[104:107], v116
	ds_read_b128 v[108:111], v116 offset:1024
	ds_read_b128 v[112:115], v116 offset:2048
	ds_read_b128 v[116:119], v116 offset:3072
	ds_read_b128 v[144:147], v156
	ds_read_b128 v[148:151], v156 offset:1024
	ds_read_b128 v[152:155], v156 offset:2048
	ds_read_b128 v[156:159], v156 offset:3072
	v_lshl_add_u64 v[206:207], s[12:13], 0, v[180:181]
	s_add_i32 m0, s21, 0xc000
	ds_read_b128 v[184:187], v212
	ds_read_b128 v[188:191], v212 offset:1024
	ds_read_b128 v[214:217], v212 offset:2048
	ds_read_b128 v[218:221], v212 offset:3072
	ds_read_b128 v[222:225], v212 offset:4096
	ds_read_b128 v[226:229], v212 offset:5120
	ds_read_b128 v[238:241], v212 offset:6144
	ds_read_b128 v[242:245], v212 offset:7168
	global_load_lds_dwordx4 v[206:207], off
	v_lshl_add_u64 v[206:207], s[12:13], 0, v[182:183]
	s_add_i32 m0, s21, 0xe000
	s_nop 0
	global_load_lds_dwordx4 v[206:207], off
	s_waitcnt vmcnt(8)
	s_waitcnt lgkmcnt(0)
	s_barrier
	s_waitcnt lgkmcnt(0)
	v_mfma_f32_16x16x32_bf16 v[140:143], v[104:107], v[184:187], v[140:143]
	v_mfma_f32_16x16x32_bf16 v[136:139], v[112:115], v[184:187], v[136:139]
	v_mfma_f32_16x16x32_bf16 v[124:127], v[104:107], v[214:217], v[124:127]
	v_mfma_f32_16x16x32_bf16 v[120:123], v[112:115], v[214:217], v[120:123]
	v_mfma_f32_16x16x32_bf16 v[92:95], v[104:107], v[222:225], v[92:95]
	v_mfma_f32_16x16x32_bf16 v[88:91], v[112:115], v[222:225], v[88:91]
	v_mfma_f32_16x16x32_bf16 v[76:79], v[104:107], v[238:241], v[76:79]
	v_mfma_f32_16x16x32_bf16 v[72:75], v[112:115], v[238:241], v[72:75]
	v_mfma_f32_16x16x32_bf16 v[140:143], v[108:111], v[188:191], v[140:143]
	v_mfma_f32_16x16x32_bf16 v[136:139], v[116:119], v[188:191], v[136:139]
	v_mfma_f32_16x16x32_bf16 v[124:127], v[108:111], v[218:221], v[124:127]
	v_mfma_f32_16x16x32_bf16 v[120:123], v[116:119], v[218:221], v[120:123]
	v_mfma_f32_16x16x32_bf16 v[92:95], v[108:111], v[226:229], v[92:95]
	v_mfma_f32_16x16x32_bf16 v[88:91], v[116:119], v[226:229], v[88:91]
	v_mfma_f32_16x16x32_bf16 v[76:79], v[108:111], v[242:245], v[76:79]
	v_mfma_f32_16x16x32_bf16 v[72:75], v[116:119], v[242:245], v[72:75]
	v_mfma_f32_16x16x32_bf16 v[132:135], v[144:147], v[184:187], v[132:135]
	v_mfma_f32_16x16x32_bf16 v[128:131], v[152:155], v[184:187], v[128:131]
	v_mfma_f32_16x16x32_bf16 v[100:103], v[144:147], v[214:217], v[100:103]
	v_mfma_f32_16x16x32_bf16 v[96:99], v[152:155], v[214:217], v[96:99]
	v_mfma_f32_16x16x32_bf16 v[84:87], v[144:147], v[222:225], v[84:87]
	v_mfma_f32_16x16x32_bf16 v[80:83], v[152:155], v[222:225], v[80:83]
	v_mfma_f32_16x16x32_bf16 v[68:71], v[144:147], v[238:241], v[68:71]
	v_mfma_f32_16x16x32_bf16 v[64:67], v[152:155], v[238:241], v[64:67]
	v_mfma_f32_16x16x32_bf16 v[132:135], v[148:151], v[188:191], v[132:135]
	v_mfma_f32_16x16x32_bf16 v[128:131], v[156:159], v[188:191], v[128:131]
	v_mfma_f32_16x16x32_bf16 v[100:103], v[148:151], v[218:221], v[100:103]
	v_mfma_f32_16x16x32_bf16 v[96:99], v[156:159], v[218:221], v[96:99]
	v_mfma_f32_16x16x32_bf16 v[84:87], v[148:151], v[226:229], v[84:87]
	v_mfma_f32_16x16x32_bf16 v[80:83], v[156:159], v[226:229], v[80:83]
	v_mfma_f32_16x16x32_bf16 v[68:71], v[148:151], v[242:245], v[68:71]
	v_mfma_f32_16x16x32_bf16 v[64:67], v[156:159], v[242:245], v[64:67]
	s_barrier
	s_add_i32 s12, s36, s20
	v_lshl_add_u64 v[206:207], s[16:17], 0, v[164:165]
	s_mov_b32 m0, s12
	ds_read_b128 v[184:187], v212 offset:16384
	ds_read_b128 v[188:191], v212 offset:17408
	ds_read_b128 v[214:217], v212 offset:18432
	ds_read_b128 v[218:221], v212 offset:19456
	ds_read_b128 v[222:225], v212 offset:20480
	ds_read_b128 v[226:229], v212 offset:21504
	ds_read_b128 v[238:241], v212 offset:22528
	ds_read_b128 v[242:245], v212 offset:23552
	global_load_lds_dwordx4 v[206:207], off
	s_add_i32 m0, s12, 0x2000
	s_add_u32 s12, s16, 0x160000
	v_lshl_add_u64 v[246:247], s[16:17], 0, v[160:161]
	s_addc_u32 s13, s17, 0
	s_add_i32 s36, s37, s20
	global_load_lds_dwordx4 v[246:247], off
	v_lshl_add_u64 v[248:249], s[12:13], 0, v[164:165]
	s_mov_b32 m0, s36
	v_lshl_add_u64 v[194:195], s[18:19], 0, v[162:163]
	global_load_lds_dwordx4 v[248:249], off
	v_lshl_add_u64 v[248:249], s[12:13], 0, v[160:161]
	s_add_i32 m0, s36, 0x2000
	s_nop 0
	global_load_lds_dwordx4 v[248:249], off
	v_lshl_add_u64 v[248:249], s[18:19], 0, v[166:167]
	s_mov_b32 m0, s21
	s_nop 0
	global_load_lds_dwordx4 v[248:249], off
	s_mov_b32 m0, s22
	s_nop 0
	global_load_lds_dwordx4 v[194:195], off
	s_waitcnt vmcnt(8)
	s_waitcnt lgkmcnt(0)
	s_barrier
; #define PG8_STAGE(bufoff, gbase, voff) do { _Pragma("unroll") for (int _i = 0; _i < 2; ++_i) \
;         __builtin_amdgcn_global_load_lds((const unsigned*)((const char*)(gbase) + (voff)[_i]), (LAS unsigned*)(lds + (bufoff) + ldsw + _i * 8192), 16, 0, 0); } while (0)
; #define PG8_LDA(dst, b, h) do { _Pragma("unroll") for (int m = 0; m < 4; ++m) _Pragma("unroll") for (int k = 0; k < 2; ++k) dst[m][k] = *(const LAS bf16x8*)(lds + PG8_SA(b, h) + aoff + m * 2048 + k * 1024); } while (0)
; #define PG8_LDB(dst, b, h) do { _Pragma("unroll") for (int n = 0; n < 2; ++n) _Pragma("unroll") for (int k = 0; k < 2; ++k) dst[n][k] = *(const LAS bf16x8*)(lds + PG8_SB(b, h) + boff + n * 2048 + k * 1024); } while (0)
; #define PG8_MMA(ai, bj, At, Bt) do { __builtin_amdgcn_s_setprio(1); _Pragma("unroll") for (int m = 0; m < 4; ++m) _Pragma("unroll") for (int n = 0; n < 2; ++n) _Pragma("unroll") for (int k = 0; k < 2; ++k) \
;         acc[ai][bj][m][n] = __builtin_amdgcn_mfma_f32_16x16x32_bf16(Bt[n][k], At[m][k], acc[ai][bj][m][n], 0, 0, 0); __builtin_amdgcn_s_setprio(0); } while (0)
; #define PG8_WAIT_V(n) asm volatile("s_waitcnt vmcnt(" #n ")" ::: "memory")
; #define PG8_WAIT_L(n) asm volatile("s_waitcnt lgkmcnt(" #n ")" ::: "memory")
; template <class Epi, bool PERMA = false, bool DUAL = false, bool ALIGN_EPI = true, bool SP2 = true>
; __device__ __forceinline__ void gemm_phase(LAS unsigned char* lds, const Gemm g, const StaticOrder& S, const Epi& E) {
;     ...
;             PG8_WAIT_V(8); PG8_WAIT_L(0); PG8_BAR; PG8_MMA(0, 0, At, B0); PG8_MMA(0, 1, At, B1); PG8_BAR; PG8_SCHED;
;             PG8_LDA(At, 0, 1); PG8_STAGE(PG8_SB(0, 0), b2, voffB); PG8_STAGE(PG8_SB(0, 1), b2 + hstepB, voffB); PG8_STAGE(PG8_SA(0, 0), a2, voffA);
;             PG8_WAIT_V(8); PG8_WAIT_L(0); PG8_BAR; PG8_MMA(1, 0, At, B0); PG8_MMA(1, 1, At, B1); PG8_BAR; PG8_SCHED;
;             PG8_LDB(B0, 1, 0); PG8_LDB(B1, 1, 1); PG8_SCHED; PG8_LDA(At, 1, 0); PG8_STAGE(PG8_SA(0, 1), a2 + hstepA, voffA);
;             PG8_WAIT_V(8); PG8_WAIT_L(0); PG8_BAR; PG8_MMA(0, 0, At, B0); PG8_MMA(0, 1, At, B1); PG8_BAR; PG8_SCHED;
;             PG8_LDA(At, 1, 1); PG8_STAGE(PG8_SB(1, 0), b3, voffB); PG8_STAGE(PG8_SB(1, 1), b3 + hstepB, voffB); PG8_STAGE(PG8_SA(1, 0), a3, voffA);
;             PG8_WAIT_V(8); PG8_WAIT_L(0); PG8_BAR; PG8_MMA(1, 0, At, B0); PG8_MMA(1, 1, At, B1); PG8_BAR; PG8_SCHED;
	s_waitcnt lgkmcnt(0)
	v_mfma_f32_16x16x32_bf16 v[60:63], v[104:107], v[184:187], v[60:63]
	v_mfma_f32_16x16x32_bf16 v[56:59], v[112:115], v[184:187], v[56:59]
	v_mfma_f32_16x16x32_bf16 v[44:47], v[104:107], v[214:217], v[44:47]
	v_mfma_f32_16x16x32_bf16 v[40:43], v[112:115], v[214:217], v[40:43]
	v_mfma_f32_16x16x32_bf16 v[28:31], v[104:107], v[222:225], v[28:31]
	v_mfma_f32_16x16x32_bf16 v[24:27], v[112:115], v[222:225], v[24:27]
	v_mfma_f32_16x16x32_bf16 v[12:15], v[104:107], v[238:241], v[12:15]
	v_mfma_f32_16x16x32_bf16 v[8:11], v[112:115], v[238:241], v[8:11]
	v_mfma_f32_16x16x32_bf16 v[60:63], v[108:111], v[188:191], v[60:63]
	v_mfma_f32_16x16x32_bf16 v[56:59], v[116:119], v[188:191], v[56:59]
	v_mfma_f32_16x16x32_bf16 v[44:47], v[108:111], v[218:221], v[44:47]
	v_mfma_f32_16x16x32_bf16 v[40:43], v[116:119], v[218:221], v[40:43]
	v_mfma_f32_16x16x32_bf16 v[28:31], v[108:111], v[226:229], v[28:31]
	v_mfma_f32_16x16x32_bf16 v[24:27], v[116:119], v[226:229], v[24:27]
	v_mfma_f32_16x16x32_bf16 v[12:15], v[108:111], v[242:245], v[12:15]
	v_mfma_f32_16x16x32_bf16 v[8:11], v[116:119], v[242:245], v[8:11]
	v_mfma_f32_16x16x32_bf16 v[52:55], v[144:147], v[184:187], v[52:55]
	v_mfma_f32_16x16x32_bf16 v[48:51], v[152:155], v[184:187], v[48:51]
	v_mfma_f32_16x16x32_bf16 v[36:39], v[144:147], v[214:217], v[36:39]
	v_mfma_f32_16x16x32_bf16 v[32:35], v[152:155], v[214:217], v[32:35]
	v_mfma_f32_16x16x32_bf16 v[20:23], v[144:147], v[222:225], v[20:23]
	v_mfma_f32_16x16x32_bf16 v[16:19], v[152:155], v[222:225], v[16:19]
	v_mfma_f32_16x16x32_bf16 v[4:7], v[144:147], v[238:241], v[4:7]
	v_mfma_f32_16x16x32_bf16 v[0:3], v[152:155], v[238:241], v[0:3]
	v_mfma_f32_16x16x32_bf16 v[52:55], v[148:151], v[188:191], v[52:55]
	v_mfma_f32_16x16x32_bf16 v[48:51], v[156:159], v[188:191], v[48:51]
	v_mfma_f32_16x16x32_bf16 v[36:39], v[148:151], v[218:221], v[36:39]
	v_mfma_f32_16x16x32_bf16 v[32:35], v[156:159], v[218:221], v[32:35]
	v_mfma_f32_16x16x32_bf16 v[20:23], v[148:151], v[226:229], v[20:23]
	v_mfma_f32_16x16x32_bf16 v[16:19], v[156:159], v[226:229], v[16:19]
	v_mfma_f32_16x16x32_bf16 v[4:7], v[148:151], v[242:245], v[4:7]
	v_mfma_f32_16x16x32_bf16 v[0:3], v[156:159], v[242:245], v[0:3]
	s_barrier
	s_add_i32 s36, 0, 0x18000
	s_add_i32 s37, 0, 0x1c000
	v_add_u32_e32 v116, s36, v193
	v_add_u32_e32 v156, s37, v193
	ds_read_b128 v[104:107], v116
	ds_read_b128 v[108:111], v116 offset:1024
	ds_read_b128 v[112:115], v116 offset:2048
	ds_read_b128 v[116:119], v116 offset:3072
	ds_read_b128 v[144:147], v156
	ds_read_b128 v[148:151], v156 offset:1024
	ds_read_b128 v[152:155], v156 offset:2048
	ds_read_b128 v[156:159], v156 offset:3072
	s_add_u32 s12, s18, 0x160000
	s_addc_u32 s13, s19, 0
	s_mov_b32 m0, s23
	v_lshl_add_u64 v[196:197], s[12:13], 0, v[166:167]
	ds_read_b128 v[184:187], v212 offset:32768
	ds_read_b128 v[188:191], v212 offset:33792
	ds_read_b128 v[214:217], v212 offset:34816
	ds_read_b128 v[218:221], v212 offset:35840
	ds_read_b128 v[222:225], v212 offset:36864
	ds_read_b128 v[226:229], v212 offset:37888
	ds_read_b128 v[238:241], v212 offset:38912
	ds_read_b128 v[242:245], v212 offset:39936
	global_load_lds_dwordx4 v[196:197], off
	v_lshl_add_u64 v[196:197], s[12:13], 0, v[162:163]
	s_mov_b32 m0, s24
	s_nop 0
	global_load_lds_dwordx4 v[196:197], off
	s_waitcnt vmcnt(8)
	s_waitcnt lgkmcnt(0)
	s_barrier
	s_waitcnt lgkmcnt(0)
	v_mfma_f32_16x16x32_bf16 v[140:143], v[104:107], v[184:187], v[140:143]
	v_mfma_f32_16x16x32_bf16 v[136:139], v[112:115], v[184:187], v[136:139]
	v_mfma_f32_16x16x32_bf16 v[124:127], v[104:107], v[214:217], v[124:127]
	v_mfma_f32_16x16x32_bf16 v[120:123], v[112:115], v[214:217], v[120:123]
	v_mfma_f32_16x16x32_bf16 v[92:95], v[104:107], v[222:225], v[92:95]
	v_mfma_f32_16x16x32_bf16 v[88:91], v[112:115], v[222:225], v[88:91]
	v_mfma_f32_16x16x32_bf16 v[76:79], v[104:107], v[238:241], v[76:79]
	v_mfma_f32_16x16x32_bf16 v[72:75], v[112:115], v[238:241], v[72:75]
	v_mfma_f32_16x16x32_bf16 v[140:143], v[108:111], v[188:191], v[140:143]
	v_mfma_f32_16x16x32_bf16 v[136:139], v[116:119], v[188:191], v[136:139]
	v_mfma_f32_16x16x32_bf16 v[124:127], v[108:111], v[218:221], v[124:127]
	v_mfma_f32_16x16x32_bf16 v[120:123], v[116:119], v[218:221], v[120:123]
	v_mfma_f32_16x16x32_bf16 v[92:95], v[108:111], v[226:229], v[92:95]
	v_mfma_f32_16x16x32_bf16 v[88:91], v[116:119], v[226:229], v[88:91]
	v_mfma_f32_16x16x32_bf16 v[76:79], v[108:111], v[242:245], v[76:79]
	v_mfma_f32_16x16x32_bf16 v[72:75], v[116:119], v[242:245], v[72:75]
	v_mfma_f32_16x16x32_bf16 v[132:135], v[144:147], v[184:187], v[132:135]
	v_mfma_f32_16x16x32_bf16 v[128:131], v[152:155], v[184:187], v[128:131]
	v_mfma_f32_16x16x32_bf16 v[100:103], v[144:147], v[214:217], v[100:103]
	v_mfma_f32_16x16x32_bf16 v[96:99], v[152:155], v[214:217], v[96:99]
	v_mfma_f32_16x16x32_bf16 v[84:87], v[144:147], v[222:225], v[84:87]
	v_mfma_f32_16x16x32_bf16 v[80:83], v[152:155], v[222:225], v[80:83]
	v_mfma_f32_16x16x32_bf16 v[68:71], v[144:147], v[238:241], v[68:71]
	v_mfma_f32_16x16x32_bf16 v[64:67], v[152:155], v[238:241], v[64:67]
	v_mfma_f32_16x16x32_bf16 v[132:135], v[148:151], v[188:191], v[132:135]
	v_mfma_f32_16x16x32_bf16 v[128:131], v[156:159], v[188:191], v[128:131]
	v_mfma_f32_16x16x32_bf16 v[100:103], v[148:151], v[218:221], v[100:103]
	v_mfma_f32_16x16x32_bf16 v[96:99], v[156:159], v[218:221], v[96:99]
	v_mfma_f32_16x16x32_bf16 v[84:87], v[148:151], v[226:229], v[84:87]
	v_mfma_f32_16x16x32_bf16 v[80:83], v[156:159], v[226:229], v[80:83]
	v_mfma_f32_16x16x32_bf16 v[68:71], v[148:151], v[242:245], v[68:71]
	v_mfma_f32_16x16x32_bf16 v[64:67], v[156:159], v[242:245], v[64:67]
	s_barrier
; #define PG8_STAGE(bufoff, gbase, voff) do { _Pragma("unroll") for (int _i = 0; _i < 2; ++_i) \
;         __builtin_amdgcn_global_load_lds((const unsigned*)((const char*)(gbase) + (voff)[_i]), (LAS unsigned*)(lds + (bufoff) + ldsw + _i * 8192), 16, 0, 0); } while (0)
; #define PG8_LDA(dst, b, h) do { _Pragma("unroll") for (int m = 0; m < 4; ++m) _Pragma("unroll") for (int k = 0; k < 2; ++k) dst[m][k] = *(const LAS bf16x8*)(lds + PG8_SA(b, h) + aoff + m * 2048 + k * 1024); } while (0)
; #define PG8_LDB(dst, b, h) do { _Pragma("unroll") for (int n = 0; n < 2; ++n) _Pragma("unroll") for (int k = 0; k < 2; ++k) dst[n][k] = *(const LAS bf16x8*)(lds + PG8_SB(b, h) + boff + n * 2048 + k * 1024); } while (0)
; #define PG8_MMA(ai, bj, At, Bt) do { __builtin_amdgcn_s_setprio(1); _Pragma("unroll") for (int m = 0; m < 4; ++m) _Pragma("unroll") for (int n = 0; n < 2; ++n) _Pragma("unroll") for (int k = 0; k < 2; ++k) \
;         acc[ai][bj][m][n] = __builtin_amdgcn_mfma_f32_16x16x32_bf16(Bt[n][k], At[m][k], acc[ai][bj][m][n], 0, 0, 0); __builtin_amdgcn_s_setprio(0); } while (0)
; #define PG8_WAIT_V(n) asm volatile("s_waitcnt vmcnt(" #n ")" ::: "memory")
; #define PG8_WAIT_L(n) asm volatile("s_waitcnt lgkmcnt(" #n ")" ::: "memory")
; #define PG8_BAR __builtin_amdgcn_s_barrier()
; #define PG8_SCHED __builtin_amdgcn_sched_barrier(0)
; template <class Epi, bool PERMA = false, bool DUAL = false, bool ALIGN_EPI = true, bool SP2 = true>
; __device__ __forceinline__ void gemm_phase(LAS unsigned char* lds, const Gemm g, const StaticOrder& S, const Epi& E) {
;     ...
;             PG8_LDB(B0, 1, 0); PG8_LDB(B1, 1, 1); PG8_SCHED; PG8_LDA(At, 1, 0); PG8_STAGE(PG8_SA(0, 1), a2 + hstepA, voffA);
;             PG8_WAIT_V(8); PG8_WAIT_L(0); PG8_BAR; PG8_MMA(0, 0, At, B0); PG8_MMA(0, 1, At, B1); PG8_BAR; PG8_SCHED;
;             PG8_LDA(At, 1, 1); PG8_STAGE(PG8_SB(1, 0), b3, voffB); PG8_STAGE(PG8_SB(1, 1), b3 + hstepB, voffB); PG8_STAGE(PG8_SA(1, 0), a3, voffA);
;             PG8_WAIT_V(8); PG8_WAIT_L(0); PG8_BAR; PG8_MMA(1, 0, At, B0); PG8_MMA(1, 1, At, B1); PG8_BAR; PG8_SCHED;
	s_add_i32 s12, s36, s20
	v_lshl_add_u64 v[196:197], v[206:207], 0, s[38:39]
	s_mov_b32 m0, s12
	ds_read_b128 v[184:187], v212 offset:49152
	ds_read_b128 v[188:191], v212 offset:50176
	ds_read_b128 v[214:217], v212 offset:51200
	ds_read_b128 v[218:221], v212 offset:52224
	ds_read_b128 v[222:225], v212 offset:53248
	ds_read_b128 v[226:229], v212 offset:54272
	ds_read_b128 v[238:241], v212 offset:55296
	ds_read_b128 v[242:245], v212 offset:56320
	global_load_lds_dwordx4 v[196:197], off
	s_add_i32 m0, s12, 0x2000
	s_add_u32 s12, s16, 0x160080
	v_lshl_add_u64 v[196:197], v[246:247], 0, s[38:39]
	s_addc_u32 s13, s17, 0
	s_add_i32 s16, s37, s20
	global_load_lds_dwordx4 v[196:197], off
	v_lshl_add_u64 v[196:197], s[12:13], 0, v[164:165]
	s_mov_b32 m0, s16
	v_lshl_add_u64 v[194:195], v[194:195], 0, s[38:39]
	global_load_lds_dwordx4 v[196:197], off
	v_lshl_add_u64 v[196:197], s[12:13], 0, v[160:161]
	s_add_i32 m0, s16, 0x2000
	s_nop 0
	global_load_lds_dwordx4 v[196:197], off
	v_lshl_add_u64 v[196:197], v[248:249], 0, s[38:39]
	s_mov_b32 m0, s29
	s_nop 0
	global_load_lds_dwordx4 v[196:197], off
	s_mov_b32 m0, s30
	s_nop 0
	global_load_lds_dwordx4 v[194:195], off
	s_waitcnt vmcnt(8)
	s_waitcnt lgkmcnt(0)
	s_barrier
	s_waitcnt lgkmcnt(0)
	v_mfma_f32_16x16x32_bf16 v[60:63], v[104:107], v[184:187], v[60:63]
	v_mfma_f32_16x16x32_bf16 v[56:59], v[112:115], v[184:187], v[56:59]
	v_mfma_f32_16x16x32_bf16 v[44:47], v[104:107], v[214:217], v[44:47]
	v_mfma_f32_16x16x32_bf16 v[40:43], v[112:115], v[214:217], v[40:43]
	v_mfma_f32_16x16x32_bf16 v[28:31], v[104:107], v[222:225], v[28:31]
	v_mfma_f32_16x16x32_bf16 v[24:27], v[112:115], v[222:225], v[24:27]
	v_mfma_f32_16x16x32_bf16 v[12:15], v[104:107], v[238:241], v[12:15]
	v_mfma_f32_16x16x32_bf16 v[8:11], v[112:115], v[238:241], v[8:11]
	v_mfma_f32_16x16x32_bf16 v[60:63], v[108:111], v[188:191], v[60:63]
	v_mfma_f32_16x16x32_bf16 v[56:59], v[116:119], v[188:191], v[56:59]
	v_mfma_f32_16x16x32_bf16 v[44:47], v[108:111], v[218:221], v[44:47]
	v_mfma_f32_16x16x32_bf16 v[40:43], v[116:119], v[218:221], v[40:43]
	v_mfma_f32_16x16x32_bf16 v[28:31], v[108:111], v[226:229], v[28:31]
	v_mfma_f32_16x16x32_bf16 v[24:27], v[116:119], v[226:229], v[24:27]
	v_mfma_f32_16x16x32_bf16 v[12:15], v[108:111], v[242:245], v[12:15]
	v_mfma_f32_16x16x32_bf16 v[8:11], v[116:119], v[242:245], v[8:11]
	v_mfma_f32_16x16x32_bf16 v[52:55], v[144:147], v[184:187], v[52:55]
	v_mfma_f32_16x16x32_bf16 v[48:51], v[152:155], v[184:187], v[48:51]
	v_mfma_f32_16x16x32_bf16 v[36:39], v[144:147], v[214:217], v[36:39]
	v_mfma_f32_16x16x32_bf16 v[32:35], v[152:155], v[214:217], v[32:35]
	v_mfma_f32_16x16x32_bf16 v[20:23], v[144:147], v[222:225], v[20:23]
	v_mfma_f32_16x16x32_bf16 v[16:19], v[152:155], v[222:225], v[16:19]
	v_mfma_f32_16x16x32_bf16 v[4:7], v[144:147], v[238:241], v[4:7]
	v_mfma_f32_16x16x32_bf16 v[0:3], v[152:155], v[238:241], v[0:3]
	v_mfma_f32_16x16x32_bf16 v[52:55], v[148:151], v[188:191], v[52:55]
	v_mfma_f32_16x16x32_bf16 v[48:51], v[156:159], v[188:191], v[48:51]
	v_mfma_f32_16x16x32_bf16 v[36:39], v[148:151], v[218:221], v[36:39]
	v_mfma_f32_16x16x32_bf16 v[32:35], v[156:159], v[218:221], v[32:35]
	v_mfma_f32_16x16x32_bf16 v[20:23], v[148:151], v[226:229], v[20:23]
	v_mfma_f32_16x16x32_bf16 v[16:19], v[156:159], v[226:229], v[16:19]
	v_mfma_f32_16x16x32_bf16 v[4:7], v[148:151], v[242:245], v[4:7]
	v_mfma_f32_16x16x32_bf16 v[0:3], v[156:159], v[242:245], v[0:3]
	s_barrier
	s_add_i32 s33, s33, 2
	s_add_u32 s9, s9, 0x100
	s_addc_u32 s11, s11, 0
	s_cmpk_gt_u32 s33, 0x55
	s_mov_b64 s[12:13], s[14:15]
	s_cbranch_scc0 .LBB0_675
	s_and_b64 vcc, exec, s[4:5]
	s_cbranch_vccz .LBB0_678
	s_barrier

; #define PG8_STAGE(bufoff, gbase, voff) do { _Pragma("unroll") for (int _i = 0; _i < 2; ++_i) \
;         __builtin_amdgcn_global_load_lds((const unsigned*)((const char*)(gbase) + (voff)[_i]), (LAS unsigned*)(lds + (bufoff) + ldsw + _i * 8192), 16, 0, 0); } while (0)
; #define PG8_LDA(dst, b, h) do { _Pragma("unroll") for (int m = 0; m < 4; ++m) _Pragma("unroll") for (int k = 0; k < 2; ++k) dst[m][k] = *(const LAS bf16x8*)(lds + PG8_SA(b, h) + aoff + m * 2048 + k * 1024); } while (0)
; #define PG8_LDB(dst, b, h) do { _Pragma("unroll") for (int n = 0; n < 2; ++n) _Pragma("unroll") for (int k = 0; k < 2; ++k) dst[n][k] = *(const LAS bf16x8*)(lds + PG8_SB(b, h) + boff + n * 2048 + k * 1024); } while (0)
; #define PG8_WAIT_V(n) asm volatile("s_waitcnt vmcnt(" #n ")" ::: "memory")
; #define PG8_BAR __builtin_amdgcn_s_barrier()
; template <class Epi, bool PERMA = false, bool DUAL = false, bool ALIGN_EPI = true, bool SP2 = true>
; __device__ __forceinline__ void gemm_phase(LAS unsigned char* lds, const Gemm g, const StaticOrder& S, const Epi& E) {
;     ...
;     for (;;) {
;         const int nw_ = DUAL ? ((ui + 1) & 1) : 0;
;         const bool has_next = DUAL ? S.next((ui + 1) >> 1, nxt) : S.next(ui + 1, nxt);
;         const bf16_t* gA_ = (DUAL && nw_) ? g.A2 : g.A; const bf16_t* gB_ = (DUAL && nw_) ? g.Bt2 : g.Bt;
;         const char* nA = has_next ? (const char*)gA_ + (size_t)nxt.pm * tstepA : cA; const char* nB = has_next ? (const char*)gB_ + (size_t)nxt.pn * tstepB : cB;
;         for (int t = 0; t < nt; t += 2) {
;             const bool last = (t == nt - 2);
;             const char* a1 = cA + (size_t)(t + 1) * kstep;
;             const char* a2 = last ? nA : cA + (size_t)(t + 2) * kstep; const char* b2 = last ? nB : cB + (size_t)(t + 2) * kstep;
;             const char* a3 = a2 + kstep; const char* b3 = b2 + kstep;
;             if constexpr (SP2) {
;             PG8_LDB(B0, 0, 0); PG8_LDB(B1, 0, 1); PG8_SCHED; PG8_LDA(At, 0, 0); PG8_STAGE(PG8_SA(1, 1), a1 + hstepA, voffA);
;             PG8_WAIT_V(8); PG8_WAIT_L(0); PG8_BAR; PG8_MMA(0, 0, At, B0); PG8_MMA(0, 1, At, B1); PG8_BAR; PG8_SCHED;
;             PG8_LDA(At, 0, 1); PG8_STAGE(PG8_SB(0, 0), b2, voffB); PG8_STAGE(PG8_SB(0, 1), b2 + hstepB, voffB); PG8_STAGE(PG8_SA(0, 0), a2, voffA);
;             PG8_WAIT_V(8); PG8_WAIT_L(0); PG8_BAR; PG8_MMA(1, 0, At, B0); PG8_MMA(1, 1, At, B1); PG8_BAR; PG8_SCHED;
.LBB0_770:
	s_add_u32 s23, s14, s22
	s_addc_u32 s28, s15, 0
	s_add_u32 s26, s23, 0x100
	s_addc_u32 s27, s28, 0
	s_and_b64 s[24:25], s[20:21], exec
	s_cselect_b32 s25, s9, s27
	s_cselect_b32 s24, s47, s26
	s_add_u32 s22, s16, s22
	s_addc_u32 s26, s17, 0
	s_add_u32 s22, s22, 0x100
	s_addc_u32 s26, s26, 0
	s_add_i32 s57, 0, 0x10000
	s_and_b64 s[20:21], s[20:21], exec
	s_cselect_b32 s27, s7, s26
	s_cselect_b32 s26, s48, s22
	s_add_i32 s21, 0, 0x14000
	s_add_u32 s30, s23, 0x10080
	s_addc_u32 s31, s28, 0
	s_add_i32 s56, s57, s35
	s_add_i32 m0, s36, 0xc000
	s_add_i32 s59, s36, 0xe000
	s_add_i32 s53, s56, 0x2000
	v_add_u32_e32 v138, s57, v140
	s_add_u32 s28, s26, 0x10000
	ds_read_b128 v[142:145], v138
	ds_read_b128 v[146:149], v138 offset:1024
	ds_read_b128 v[150:153], v138 offset:2048
	ds_read_b128 v[154:157], v138 offset:3072
	v_add_u32_e32 v138, s21, v140
	s_addc_u32 s29, s27, 0
	s_add_i32 s55, s21, s35
	ds_read_b128 v[158:161], v138
	ds_read_b128 v[162:165], v138 offset:1024
	ds_read_b128 v[166:169], v138 offset:2048
	ds_read_b128 v[170:173], v138 offset:3072
	s_add_i32 s54, s55, 0x2000
	s_add_i32 s52, 0, 0x18000
	s_add_i32 s51, 0, 0x1c000
	s_add_u32 s22, s24, 0x10000
	s_addc_u32 s23, s25, 0
	s_add_i32 s50, s52, s35
	s_add_i32 s49, s50, 0x2000
	s_add_u32 s20, s26, 0x10080
	s_addc_u32 s21, s27, 0
	s_add_i32 s58, s51, s35
	s_add_i32 s57, s58, 0x2000
	v_lshl_add_u64 v[138:139], s[30:31], 0, v[134:135]
	ds_read_b128 v[174:177], v141
	ds_read_b128 v[178:181], v141 offset:1024
	ds_read_b128 v[182:185], v141 offset:2048
	ds_read_b128 v[186:189], v141 offset:3072
	ds_read_b128 v[206:209], v141 offset:4096
	ds_read_b128 v[210:213], v141 offset:5120
	ds_read_b128 v[214:217], v141 offset:6144
	ds_read_b128 v[218:221], v141 offset:7168
	global_load_lds_dwordx4 v[138:139], off
	v_lshl_add_u64 v[138:139], s[30:31], 0, v[130:131]
	s_mov_b32 m0, s59
	s_nop 0
	global_load_lds_dwordx4 v[138:139], off
	s_waitcnt vmcnt(8)
	s_waitcnt lgkmcnt(0)
	s_barrier
	s_waitcnt lgkmcnt(0)
	v_mfma_f32_16x16x32_bf16 v[124:127], v[142:145], v[174:177], v[124:127]
	v_mfma_f32_16x16x32_bf16 v[120:123], v[150:153], v[174:177], v[120:123]
	v_mfma_f32_16x16x32_bf16 v[116:119], v[142:145], v[182:185], v[116:119]
	v_mfma_f32_16x16x32_bf16 v[108:111], v[150:153], v[182:185], v[108:111]
	v_mfma_f32_16x16x32_bf16 v[100:103], v[142:145], v[206:209], v[100:103]
	v_mfma_f32_16x16x32_bf16 v[92:95], v[150:153], v[206:209], v[92:95]
	v_mfma_f32_16x16x32_bf16 v[84:87], v[142:145], v[214:217], v[84:87]
	v_mfma_f32_16x16x32_bf16 v[76:79], v[150:153], v[214:217], v[76:79]
	v_mfma_f32_16x16x32_bf16 v[124:127], v[146:149], v[178:181], v[124:127]
	v_mfma_f32_16x16x32_bf16 v[120:123], v[154:157], v[178:181], v[120:123]
	v_mfma_f32_16x16x32_bf16 v[116:119], v[146:149], v[186:189], v[116:119]
	v_mfma_f32_16x16x32_bf16 v[108:111], v[154:157], v[186:189], v[108:111]
	v_mfma_f32_16x16x32_bf16 v[100:103], v[146:149], v[210:213], v[100:103]
	v_mfma_f32_16x16x32_bf16 v[92:95], v[154:157], v[210:213], v[92:95]
	v_mfma_f32_16x16x32_bf16 v[84:87], v[146:149], v[218:221], v[84:87]
	v_mfma_f32_16x16x32_bf16 v[76:79], v[154:157], v[218:221], v[76:79]
	v_mfma_f32_16x16x32_bf16 v[112:115], v[158:161], v[174:177], v[112:115]
	v_mfma_f32_16x16x32_bf16 v[104:107], v[166:169], v[174:177], v[104:107]
	v_mfma_f32_16x16x32_bf16 v[96:99], v[158:161], v[182:185], v[96:99]
	v_mfma_f32_16x16x32_bf16 v[88:91], v[166:169], v[182:185], v[88:91]
	v_mfma_f32_16x16x32_bf16 v[80:83], v[158:161], v[206:209], v[80:83]
	v_mfma_f32_16x16x32_bf16 v[72:75], v[166:169], v[206:209], v[72:75]
	v_mfma_f32_16x16x32_bf16 v[68:71], v[158:161], v[214:217], v[68:71]
	v_mfma_f32_16x16x32_bf16 v[64:67], v[166:169], v[214:217], v[64:67]
	v_mfma_f32_16x16x32_bf16 v[112:115], v[162:165], v[178:181], v[112:115]
	v_mfma_f32_16x16x32_bf16 v[104:107], v[170:173], v[178:181], v[104:107]
	v_mfma_f32_16x16x32_bf16 v[96:99], v[162:165], v[186:189], v[96:99]
	v_mfma_f32_16x16x32_bf16 v[88:91], v[170:173], v[186:189], v[88:91]
	v_mfma_f32_16x16x32_bf16 v[80:83], v[162:165], v[210:213], v[80:83]
	v_mfma_f32_16x16x32_bf16 v[72:75], v[170:173], v[210:213], v[72:75]
	v_mfma_f32_16x16x32_bf16 v[68:71], v[162:165], v[218:221], v[68:71]
	v_mfma_f32_16x16x32_bf16 v[64:67], v[170:173], v[218:221], v[64:67]
	s_barrier
	s_mov_b32 m0, s56
	v_lshl_add_u64 v[138:139], s[26:27], 0, v[132:133]
	ds_read_b128 v[174:177], v141 offset:16384
	ds_read_b128 v[178:181], v141 offset:17408
	ds_read_b128 v[182:185], v141 offset:18432
	ds_read_b128 v[186:189], v141 offset:19456
	ds_read_b128 v[206:209], v141 offset:20480
	ds_read_b128 v[210:213], v141 offset:21504
	ds_read_b128 v[214:217], v141 offset:22528
	ds_read_b128 v[218:221], v141 offset:23552
	global_load_lds_dwordx4 v[138:139], off
	v_lshl_add_u64 v[190:191], s[26:27], 0, v[128:129]
	s_mov_b32 m0, s53
	v_lshl_add_u64 v[194:195], s[28:29], 0, v[132:133]
	global_load_lds_dwordx4 v[190:191], off
	s_mov_b32 m0, s55
	v_lshl_add_u64 v[196:197], s[24:25], 0, v[130:131]
	global_load_lds_dwordx4 v[194:195], off
	v_lshl_add_u64 v[194:195], s[28:29], 0, v[128:129]
	s_mov_b32 m0, s54
	s_nop 0
	global_load_lds_dwordx4 v[194:195], off
	v_lshl_add_u64 v[194:195], s[24:25], 0, v[134:135]
	s_mov_b32 m0, s36
	s_nop 0
	global_load_lds_dwordx4 v[194:195], off
	s_mov_b32 m0, s37
	s_nop 0
	global_load_lds_dwordx4 v[196:197], off
	s_waitcnt vmcnt(8)
	s_waitcnt lgkmcnt(0)
	s_barrier
; #define PG8_STAGE(bufoff, gbase, voff) do { _Pragma("unroll") for (int _i = 0; _i < 2; ++_i) \
;         __builtin_amdgcn_global_load_lds((const unsigned*)((const char*)(gbase) + (voff)[_i]), (LAS unsigned*)(lds + (bufoff) + ldsw + _i * 8192), 16, 0, 0); } while (0)
; #define PG8_LDA(dst, b, h) do { _Pragma("unroll") for (int m = 0; m < 4; ++m) _Pragma("unroll") for (int k = 0; k < 2; ++k) dst[m][k] = *(const LAS bf16x8*)(lds + PG8_SA(b, h) + aoff + m * 2048 + k * 1024); } while (0)
; #define PG8_LDB(dst, b, h) do { _Pragma("unroll") for (int n = 0; n < 2; ++n) _Pragma("unroll") for (int k = 0; k < 2; ++k) dst[n][k] = *(const LAS bf16x8*)(lds + PG8_SB(b, h) + boff + n * 2048 + k * 1024); } while (0)
; #define PG8_MMA(ai, bj, At, Bt) do { __builtin_amdgcn_s_setprio(1); _Pragma("unroll") for (int m = 0; m < 4; ++m) _Pragma("unroll") for (int n = 0; n < 2; ++n) _Pragma("unroll") for (int k = 0; k < 2; ++k) \
;         acc[ai][bj][m][n] = __builtin_amdgcn_mfma_f32_16x16x32_bf16(Bt[n][k], At[m][k], acc[ai][bj][m][n], 0, 0, 0); __builtin_amdgcn_s_setprio(0); } while (0)
; #define PG8_WAIT_V(n) asm volatile("s_waitcnt vmcnt(" #n ")" ::: "memory")
; #define PG8_WAIT_L(n) asm volatile("s_waitcnt lgkmcnt(" #n ")" ::: "memory")
; #define PG8_BAR __builtin_amdgcn_s_barrier()
; #define PG8_SCHED __builtin_amdgcn_sched_barrier(0)
; template <class Epi, bool PERMA = false, bool DUAL = false, bool ALIGN_EPI = true, bool SP2 = true>
; __device__ __forceinline__ void gemm_phase(LAS unsigned char* lds, const Gemm g, const StaticOrder& S, const Epi& E) {
;     ...
;             PG8_WAIT_V(8); PG8_WAIT_L(0); PG8_BAR; PG8_MMA(1, 0, At, B0); PG8_MMA(1, 1, At, B1); PG8_BAR; PG8_SCHED;
;             PG8_LDB(B0, 1, 0); PG8_LDB(B1, 1, 1); PG8_SCHED; PG8_LDA(At, 1, 0); PG8_STAGE(PG8_SA(0, 1), a2 + hstepA, voffA);
;             PG8_WAIT_V(8); PG8_WAIT_L(0); PG8_BAR; PG8_MMA(0, 0, At, B0); PG8_MMA(0, 1, At, B1); PG8_BAR; PG8_SCHED;
	s_waitcnt lgkmcnt(0)
	v_mfma_f32_16x16x32_bf16 v[60:63], v[142:145], v[174:177], v[60:63]
	v_mfma_f32_16x16x32_bf16 v[56:59], v[150:153], v[174:177], v[56:59]
	v_mfma_f32_16x16x32_bf16 v[52:55], v[142:145], v[182:185], v[52:55]
	v_mfma_f32_16x16x32_bf16 v[44:47], v[150:153], v[182:185], v[44:47]
	v_mfma_f32_16x16x32_bf16 v[36:39], v[142:145], v[206:209], v[36:39]
	v_mfma_f32_16x16x32_bf16 v[28:31], v[150:153], v[206:209], v[28:31]
	v_mfma_f32_16x16x32_bf16 v[20:23], v[142:145], v[214:217], v[20:23]
	v_mfma_f32_16x16x32_bf16 v[12:15], v[150:153], v[214:217], v[12:15]
	v_mfma_f32_16x16x32_bf16 v[60:63], v[146:149], v[178:181], v[60:63]
	v_mfma_f32_16x16x32_bf16 v[56:59], v[154:157], v[178:181], v[56:59]
	v_mfma_f32_16x16x32_bf16 v[52:55], v[146:149], v[186:189], v[52:55]
	v_mfma_f32_16x16x32_bf16 v[44:47], v[154:157], v[186:189], v[44:47]
	v_mfma_f32_16x16x32_bf16 v[36:39], v[146:149], v[210:213], v[36:39]
	v_mfma_f32_16x16x32_bf16 v[28:31], v[154:157], v[210:213], v[28:31]
	v_mfma_f32_16x16x32_bf16 v[20:23], v[146:149], v[218:221], v[20:23]
	v_mfma_f32_16x16x32_bf16 v[12:15], v[154:157], v[218:221], v[12:15]
	v_mfma_f32_16x16x32_bf16 v[48:51], v[158:161], v[174:177], v[48:51]
	v_mfma_f32_16x16x32_bf16 v[40:43], v[166:169], v[174:177], v[40:43]
	v_mfma_f32_16x16x32_bf16 v[32:35], v[158:161], v[182:185], v[32:35]
	v_mfma_f32_16x16x32_bf16 v[24:27], v[166:169], v[182:185], v[24:27]
	v_mfma_f32_16x16x32_bf16 v[16:19], v[158:161], v[206:209], v[16:19]
	v_mfma_f32_16x16x32_bf16 v[8:11], v[166:169], v[206:209], v[8:11]
	v_mfma_f32_16x16x32_bf16 v[4:7], v[158:161], v[214:217], v[4:7]
	v_mfma_f32_16x16x32_bf16 v[0:3], v[166:169], v[214:217], v[0:3]
	v_mfma_f32_16x16x32_bf16 v[48:51], v[162:165], v[178:181], v[48:51]
	v_mfma_f32_16x16x32_bf16 v[40:43], v[170:173], v[178:181], v[40:43]
	v_mfma_f32_16x16x32_bf16 v[32:35], v[162:165], v[186:189], v[32:35]
	v_mfma_f32_16x16x32_bf16 v[24:27], v[170:173], v[186:189], v[24:27]
	v_mfma_f32_16x16x32_bf16 v[16:19], v[162:165], v[210:213], v[16:19]
	v_mfma_f32_16x16x32_bf16 v[8:11], v[170:173], v[210:213], v[8:11]
	v_mfma_f32_16x16x32_bf16 v[4:7], v[162:165], v[218:221], v[4:7]
	v_mfma_f32_16x16x32_bf16 v[0:3], v[170:173], v[218:221], v[0:3]
	s_barrier
	v_add_u32_e32 v154, s52, v140
	v_add_u32_e32 v170, s51, v140
	ds_read_b128 v[142:145], v154
	ds_read_b128 v[146:149], v154 offset:1024
	ds_read_b128 v[150:153], v154 offset:2048
	ds_read_b128 v[154:157], v154 offset:3072
	ds_read_b128 v[158:161], v170
	ds_read_b128 v[162:165], v170 offset:1024
	ds_read_b128 v[166:169], v170 offset:2048
	ds_read_b128 v[170:173], v170 offset:3072
	s_mov_b32 m0, s38
	v_lshl_add_u64 v[222:223], s[22:23], 0, v[134:135]
	ds_read_b128 v[174:177], v141 offset:32768
	ds_read_b128 v[178:181], v141 offset:33792
	ds_read_b128 v[182:185], v141 offset:34816
	ds_read_b128 v[186:189], v141 offset:35840
	ds_read_b128 v[206:209], v141 offset:36864
	ds_read_b128 v[210:213], v141 offset:37888
	ds_read_b128 v[214:217], v141 offset:38912
	ds_read_b128 v[218:221], v141 offset:39936
	global_load_lds_dwordx4 v[222:223], off
	v_lshl_add_u64 v[222:223], s[22:23], 0, v[130:131]
	s_mov_b32 m0, s39
	s_nop 0
	global_load_lds_dwordx4 v[222:223], off
	s_waitcnt vmcnt(8)
	s_waitcnt lgkmcnt(0)
	s_barrier
	s_waitcnt lgkmcnt(0)
	v_mfma_f32_16x16x32_bf16 v[124:127], v[142:145], v[174:177], v[124:127]
	v_mfma_f32_16x16x32_bf16 v[120:123], v[150:153], v[174:177], v[120:123]
	v_mfma_f32_16x16x32_bf16 v[116:119], v[142:145], v[182:185], v[116:119]
	v_mfma_f32_16x16x32_bf16 v[108:111], v[150:153], v[182:185], v[108:111]
	v_mfma_f32_16x16x32_bf16 v[100:103], v[142:145], v[206:209], v[100:103]
	v_mfma_f32_16x16x32_bf16 v[92:95], v[150:153], v[206:209], v[92:95]
	v_mfma_f32_16x16x32_bf16 v[84:87], v[142:145], v[214:217], v[84:87]
	v_mfma_f32_16x16x32_bf16 v[76:79], v[150:153], v[214:217], v[76:79]
	v_mfma_f32_16x16x32_bf16 v[124:127], v[146:149], v[178:181], v[124:127]
	v_mfma_f32_16x16x32_bf16 v[120:123], v[154:157], v[178:181], v[120:123]
	v_mfma_f32_16x16x32_bf16 v[116:119], v[146:149], v[186:189], v[116:119]
	v_mfma_f32_16x16x32_bf16 v[108:111], v[154:157], v[186:189], v[108:111]
	v_mfma_f32_16x16x32_bf16 v[100:103], v[146:149], v[210:213], v[100:103]
	v_mfma_f32_16x16x32_bf16 v[92:95], v[154:157], v[210:213], v[92:95]
	v_mfma_f32_16x16x32_bf16 v[84:87], v[146:149], v[218:221], v[84:87]
	v_mfma_f32_16x16x32_bf16 v[76:79], v[154:157], v[218:221], v[76:79]
	v_mfma_f32_16x16x32_bf16 v[112:115], v[158:161], v[174:177], v[112:115]
	v_mfma_f32_16x16x32_bf16 v[104:107], v[166:169], v[174:177], v[104:107]
	v_mfma_f32_16x16x32_bf16 v[96:99], v[158:161], v[182:185], v[96:99]
	v_mfma_f32_16x16x32_bf16 v[88:91], v[166:169], v[182:185], v[88:91]
	v_mfma_f32_16x16x32_bf16 v[80:83], v[158:161], v[206:209], v[80:83]
	v_mfma_f32_16x16x32_bf16 v[72:75], v[166:169], v[206:209], v[72:75]
	v_mfma_f32_16x16x32_bf16 v[68:71], v[158:161], v[214:217], v[68:71]
	v_mfma_f32_16x16x32_bf16 v[64:67], v[166:169], v[214:217], v[64:67]
	v_mfma_f32_16x16x32_bf16 v[112:115], v[162:165], v[178:181], v[112:115]
	v_mfma_f32_16x16x32_bf16 v[104:107], v[170:173], v[178:181], v[104:107]
	v_mfma_f32_16x16x32_bf16 v[96:99], v[162:165], v[186:189], v[96:99]
	v_mfma_f32_16x16x32_bf16 v[88:91], v[170:173], v[186:189], v[88:91]
	v_mfma_f32_16x16x32_bf16 v[80:83], v[162:165], v[210:213], v[80:83]
	v_mfma_f32_16x16x32_bf16 v[72:75], v[170:173], v[210:213], v[72:75]
	v_mfma_f32_16x16x32_bf16 v[68:71], v[162:165], v[218:221], v[68:71]
	v_mfma_f32_16x16x32_bf16 v[64:67], v[170:173], v[218:221], v[64:67]
	s_barrier
; #define PG8_STAGE(bufoff, gbase, voff) do { _Pragma("unroll") for (int _i = 0; _i < 2; ++_i) \
;         __builtin_amdgcn_global_load_lds((const unsigned*)((const char*)(gbase) + (voff)[_i]), (LAS unsigned*)(lds + (bufoff) + ldsw + _i * 8192), 16, 0, 0); } while (0)
; #define PG8_LDA(dst, b, h) do { _Pragma("unroll") for (int m = 0; m < 4; ++m) _Pragma("unroll") for (int k = 0; k < 2; ++k) dst[m][k] = *(const LAS bf16x8*)(lds + PG8_SA(b, h) + aoff + m * 2048 + k * 1024); } while (0)
; #define PG8_MMA(ai, bj, At, Bt) do { __builtin_amdgcn_s_setprio(1); _Pragma("unroll") for (int m = 0; m < 4; ++m) _Pragma("unroll") for (int n = 0; n < 2; ++n) _Pragma("unroll") for (int k = 0; k < 2; ++k) \
;         acc[ai][bj][m][n] = __builtin_amdgcn_mfma_f32_16x16x32_bf16(Bt[n][k], At[m][k], acc[ai][bj][m][n], 0, 0, 0); __builtin_amdgcn_s_setprio(0); } while (0)
; #define PG8_WAIT_V(n) asm volatile("s_waitcnt vmcnt(" #n ")" ::: "memory")
; #define PG8_WAIT_L(n) asm volatile("s_waitcnt lgkmcnt(" #n ")" ::: "memory")
; #define PG8_BAR __builtin_amdgcn_s_barrier()
; #define PG8_SCHED __builtin_amdgcn_sched_barrier(0)
; template <class Epi, bool PERMA = false, bool DUAL = false, bool ALIGN_EPI = true, bool SP2 = true>
; __device__ __forceinline__ void gemm_phase(LAS unsigned char* lds, const Gemm g, const StaticOrder& S, const Epi& E) {
;     ...
;             PG8_LDA(At, 1, 1); PG8_STAGE(PG8_SB(1, 0), b3, voffB); PG8_STAGE(PG8_SB(1, 1), b3 + hstepB, voffB); PG8_STAGE(PG8_SA(1, 0), a3, voffA);
;             PG8_WAIT_V(8); PG8_WAIT_L(0); PG8_BAR; PG8_MMA(1, 0, At, B0); PG8_MMA(1, 1, At, B1); PG8_BAR; PG8_SCHED;
;     ...
;         if constexpr (ALIGN_EPI) { if (wr == 0) PG8_BAR; }
	s_mov_b32 m0, s50
	v_lshl_add_u64 v[138:139], v[138:139], 0, s[68:69]
	ds_read_b128 v[174:177], v141 offset:49152
	ds_read_b128 v[178:181], v141 offset:50176
	ds_read_b128 v[182:185], v141 offset:51200
	ds_read_b128 v[186:189], v141 offset:52224
	ds_read_b128 v[206:209], v141 offset:53248
	ds_read_b128 v[210:213], v141 offset:54272
	ds_read_b128 v[214:217], v141 offset:55296
	ds_read_b128 v[218:221], v141 offset:56320
	global_load_lds_dwordx4 v[138:139], off
	v_lshl_add_u64 v[138:139], v[190:191], 0, s[68:69]
	s_mov_b32 m0, s49
	s_nop 0
	global_load_lds_dwordx4 v[138:139], off
	v_lshl_add_u64 v[138:139], s[20:21], 0, v[132:133]
	s_mov_b32 m0, s58
	s_nop 0
	global_load_lds_dwordx4 v[138:139], off
	v_lshl_add_u64 v[138:139], s[20:21], 0, v[128:129]
	s_mov_b32 m0, s57
	s_nop 0
	global_load_lds_dwordx4 v[138:139], off
	v_lshl_add_u64 v[138:139], v[194:195], 0, s[68:69]
	s_mov_b32 m0, s42
	s_nop 0
	global_load_lds_dwordx4 v[138:139], off
	v_lshl_add_u64 v[138:139], v[196:197], 0, s[68:69]
	s_mov_b32 m0, s43
	s_nop 0
	global_load_lds_dwordx4 v[138:139], off
	s_waitcnt vmcnt(8)
	s_waitcnt lgkmcnt(0)
	s_barrier
	s_waitcnt lgkmcnt(0)
	v_mfma_f32_16x16x32_bf16 v[60:63], v[142:145], v[174:177], v[60:63]
	v_mfma_f32_16x16x32_bf16 v[56:59], v[150:153], v[174:177], v[56:59]
	v_mfma_f32_16x16x32_bf16 v[52:55], v[142:145], v[182:185], v[52:55]
	v_mfma_f32_16x16x32_bf16 v[44:47], v[150:153], v[182:185], v[44:47]
	v_mfma_f32_16x16x32_bf16 v[36:39], v[142:145], v[206:209], v[36:39]
	v_mfma_f32_16x16x32_bf16 v[28:31], v[150:153], v[206:209], v[28:31]
	v_mfma_f32_16x16x32_bf16 v[20:23], v[142:145], v[214:217], v[20:23]
	v_mfma_f32_16x16x32_bf16 v[12:15], v[150:153], v[214:217], v[12:15]
	v_mfma_f32_16x16x32_bf16 v[60:63], v[146:149], v[178:181], v[60:63]
	v_mfma_f32_16x16x32_bf16 v[56:59], v[154:157], v[178:181], v[56:59]
	v_mfma_f32_16x16x32_bf16 v[52:55], v[146:149], v[186:189], v[52:55]
	v_mfma_f32_16x16x32_bf16 v[44:47], v[154:157], v[186:189], v[44:47]
	v_mfma_f32_16x16x32_bf16 v[36:39], v[146:149], v[210:213], v[36:39]
	v_mfma_f32_16x16x32_bf16 v[28:31], v[154:157], v[210:213], v[28:31]
	v_mfma_f32_16x16x32_bf16 v[20:23], v[146:149], v[218:221], v[20:23]
	v_mfma_f32_16x16x32_bf16 v[12:15], v[154:157], v[218:221], v[12:15]
	v_mfma_f32_16x16x32_bf16 v[48:51], v[158:161], v[174:177], v[48:51]
	v_mfma_f32_16x16x32_bf16 v[40:43], v[166:169], v[174:177], v[40:43]
	v_mfma_f32_16x16x32_bf16 v[32:35], v[158:161], v[182:185], v[32:35]
	v_mfma_f32_16x16x32_bf16 v[24:27], v[166:169], v[182:185], v[24:27]
	v_mfma_f32_16x16x32_bf16 v[16:19], v[158:161], v[206:209], v[16:19]
	v_mfma_f32_16x16x32_bf16 v[8:11], v[166:169], v[206:209], v[8:11]
	v_mfma_f32_16x16x32_bf16 v[4:7], v[158:161], v[214:217], v[4:7]
	v_mfma_f32_16x16x32_bf16 v[0:3], v[166:169], v[214:217], v[0:3]
	v_mfma_f32_16x16x32_bf16 v[48:51], v[162:165], v[178:181], v[48:51]
	v_mfma_f32_16x16x32_bf16 v[40:43], v[170:173], v[178:181], v[40:43]
	v_mfma_f32_16x16x32_bf16 v[32:35], v[162:165], v[186:189], v[32:35]
	v_mfma_f32_16x16x32_bf16 v[24:27], v[170:173], v[186:189], v[24:27]
	v_mfma_f32_16x16x32_bf16 v[16:19], v[162:165], v[210:213], v[16:19]
	v_mfma_f32_16x16x32_bf16 v[8:11], v[170:173], v[210:213], v[8:11]
	v_mfma_f32_16x16x32_bf16 v[4:7], v[162:165], v[218:221], v[4:7]
	v_mfma_f32_16x16x32_bf16 v[0:3], v[170:173], v[218:221], v[0:3]
	s_barrier
	s_movk_i32 s22, 0x100
	s_andn2_b64 vcc, exec, s[18:19]
	s_mov_b64 s[20:21], -1
	s_mov_b64 s[18:19], 0
	s_cbranch_vccz .LBB0_770
	s_and_b64 vcc, exec, s[4:5]
	s_cbranch_vccz .LBB0_773
	s_barrier

; #define PG8_STAGE(bufoff, gbase, voff) do { _Pragma("unroll") for (int _i = 0; _i < 2; ++_i) \
;         __builtin_amdgcn_global_load_lds((const unsigned*)((const char*)(gbase) + (voff)[_i]), (LAS unsigned*)(lds + (bufoff) + ldsw + _i * 8192), 16, 0, 0); } while (0)
; #define PG8_LDA(dst, b, h) do { _Pragma("unroll") for (int m = 0; m < 4; ++m) _Pragma("unroll") for (int k = 0; k < 2; ++k) dst[m][k] = *(const LAS bf16x8*)(lds + PG8_SA(b, h) + aoff + m * 2048 + k * 1024); } while (0)
; #define PG8_LDB(dst, b, h) do { _Pragma("unroll") for (int n = 0; n < 2; ++n) _Pragma("unroll") for (int k = 0; k < 2; ++k) dst[n][k] = *(const LAS bf16x8*)(lds + PG8_SB(b, h) + boff + n * 2048 + k * 1024); } while (0)
; #define PG8_MMA(ai, bj, At, Bt) do { __builtin_amdgcn_s_setprio(1); _Pragma("unroll") for (int m = 0; m < 4; ++m) _Pragma("unroll") for (int n = 0; n < 2; ++n) _Pragma("unroll") for (int k = 0; k < 2; ++k) \
;         acc[ai][bj][m][n] = __builtin_amdgcn_mfma_f32_16x16x32_bf16(Bt[n][k], At[m][k], acc[ai][bj][m][n], 0, 0, 0); __builtin_amdgcn_s_setprio(0); } while (0)
; #define PG8_WAIT_V(n) asm volatile("s_waitcnt vmcnt(" #n ")" ::: "memory")
; #define PG8_WAIT_L(n) asm volatile("s_waitcnt lgkmcnt(" #n ")" ::: "memory")
; #define PG8_BAR __builtin_amdgcn_s_barrier()
; #define PG8_SCHED __builtin_amdgcn_sched_barrier(0)
; template <class Epi, bool PERMA = false, bool DUAL = false, bool ALIGN_EPI = true, bool SP2 = true>
; __device__ __forceinline__ void gemm_phase(LAS unsigned char* lds, const Gemm g, const StaticOrder& S, const Epi& E) {
;     ...
;             const bool last = (t == nt - 2);
;             const char* a1 = cA + (size_t)(t + 1) * kstep;
;             const char* a2 = last ? nA : cA + (size_t)(t + 2) * kstep; const char* b2 = last ? nB : cB + (size_t)(t + 2) * kstep;
;             const char* a3 = a2 + kstep; const char* b3 = b2 + kstep;
;             if constexpr (SP2) {
;             PG8_LDB(B0, 0, 0); PG8_LDB(B1, 0, 1); PG8_SCHED; PG8_LDA(At, 0, 0); PG8_STAGE(PG8_SA(1, 1), a1 + hstepA, voffA);
;             PG8_WAIT_V(8); PG8_WAIT_L(0); PG8_BAR; PG8_MMA(0, 0, At, B0); PG8_MMA(0, 1, At, B1); PG8_BAR; PG8_SCHED;
;             PG8_LDA(At, 0, 1); PG8_STAGE(PG8_SB(0, 0), b2, voffB); PG8_STAGE(PG8_SB(0, 1), b2 + hstepB, voffB); PG8_STAGE(PG8_SA(0, 0), a2, voffA);
.LBB0_790:
	s_add_u32 s14, s12, 0xfff80080
	s_addc_u32 s15, s13, -1
	s_add_i32 s36, 0, 0x10000
	s_cmp_eq_u32 s35, 28
	s_cselect_b32 s17, s7, s15
	s_cselect_b32 s16, s30, s14
	s_cselect_b32 s15, s5, s34
	s_cselect_b32 s14, s31, s33
	s_add_i32 s40, 0, 0x14000
	v_add_u32_e32 v140, s36, v190
	v_add_u32_e32 v156, s40, v190
	ds_read_b128 v[120:123], v140
	ds_read_b128 v[128:131], v140 offset:1024
	ds_read_b128 v[132:135], v140 offset:2048
	ds_read_b128 v[140:143], v140 offset:3072
	ds_read_b128 v[144:147], v156
	ds_read_b128 v[148:151], v156 offset:1024
	ds_read_b128 v[152:155], v156 offset:2048
	ds_read_b128 v[156:159], v156 offset:3072
	v_lshl_add_u64 v[194:195], s[12:13], 0, v[174:175]
	s_add_i32 m0, s19, 0xc000
	ds_read_b128 v[178:181], v191
	ds_read_b128 v[182:185], v191 offset:1024
	ds_read_b128 v[186:189], v191 offset:2048
	ds_read_b128 v[206:209], v191 offset:3072
	ds_read_b128 v[210:213], v191 offset:4096
	ds_read_b128 v[214:217], v191 offset:5120
	ds_read_b128 v[218:221], v191 offset:6144
	ds_read_b128 v[222:225], v191 offset:7168
	global_load_lds_dwordx4 v[194:195], off
	v_lshl_add_u64 v[194:195], s[12:13], 0, v[176:177]
	s_add_i32 m0, s19, 0xe000
	s_nop 0
	global_load_lds_dwordx4 v[194:195], off
	s_waitcnt vmcnt(8)
	s_waitcnt lgkmcnt(0)
	s_barrier
	s_waitcnt lgkmcnt(0)
	v_mfma_f32_16x16x32_bf16 v[136:139], v[120:123], v[178:181], v[136:139]
	v_mfma_f32_16x16x32_bf16 v[124:127], v[132:135], v[178:181], v[124:127]
	v_mfma_f32_16x16x32_bf16 v[108:111], v[120:123], v[186:189], v[108:111]
	v_mfma_f32_16x16x32_bf16 v[104:107], v[132:135], v[186:189], v[104:107]
	v_mfma_f32_16x16x32_bf16 v[92:95], v[120:123], v[210:213], v[92:95]
	v_mfma_f32_16x16x32_bf16 v[88:91], v[132:135], v[210:213], v[88:91]
	v_mfma_f32_16x16x32_bf16 v[76:79], v[120:123], v[218:221], v[76:79]
	v_mfma_f32_16x16x32_bf16 v[72:75], v[132:135], v[218:221], v[72:75]
	v_mfma_f32_16x16x32_bf16 v[136:139], v[128:131], v[182:185], v[136:139]
	v_mfma_f32_16x16x32_bf16 v[124:127], v[140:143], v[182:185], v[124:127]
	v_mfma_f32_16x16x32_bf16 v[108:111], v[128:131], v[206:209], v[108:111]
	v_mfma_f32_16x16x32_bf16 v[104:107], v[140:143], v[206:209], v[104:107]
	v_mfma_f32_16x16x32_bf16 v[92:95], v[128:131], v[214:217], v[92:95]
	v_mfma_f32_16x16x32_bf16 v[88:91], v[140:143], v[214:217], v[88:91]
	v_mfma_f32_16x16x32_bf16 v[76:79], v[128:131], v[222:225], v[76:79]
	v_mfma_f32_16x16x32_bf16 v[72:75], v[140:143], v[222:225], v[72:75]
	v_mfma_f32_16x16x32_bf16 v[116:119], v[144:147], v[178:181], v[116:119]
	v_mfma_f32_16x16x32_bf16 v[112:115], v[152:155], v[178:181], v[112:115]
	v_mfma_f32_16x16x32_bf16 v[100:103], v[144:147], v[186:189], v[100:103]
	v_mfma_f32_16x16x32_bf16 v[96:99], v[152:155], v[186:189], v[96:99]
	v_mfma_f32_16x16x32_bf16 v[84:87], v[144:147], v[210:213], v[84:87]
	v_mfma_f32_16x16x32_bf16 v[80:83], v[152:155], v[210:213], v[80:83]
	v_mfma_f32_16x16x32_bf16 v[68:71], v[144:147], v[218:221], v[68:71]
	v_mfma_f32_16x16x32_bf16 v[64:67], v[152:155], v[218:221], v[64:67]
	v_mfma_f32_16x16x32_bf16 v[116:119], v[148:151], v[182:185], v[116:119]
	v_mfma_f32_16x16x32_bf16 v[112:115], v[156:159], v[182:185], v[112:115]
	v_mfma_f32_16x16x32_bf16 v[100:103], v[148:151], v[206:209], v[100:103]
	v_mfma_f32_16x16x32_bf16 v[96:99], v[156:159], v[206:209], v[96:99]
	v_mfma_f32_16x16x32_bf16 v[84:87], v[148:151], v[214:217], v[84:87]
	v_mfma_f32_16x16x32_bf16 v[80:83], v[156:159], v[214:217], v[80:83]
	v_mfma_f32_16x16x32_bf16 v[68:71], v[148:151], v[222:225], v[68:71]
	v_mfma_f32_16x16x32_bf16 v[64:67], v[156:159], v[222:225], v[64:67]
	s_barrier
	s_add_i32 s36, s36, s18
	v_lshl_add_u64 v[194:195], s[14:15], 0, v[164:165]
	s_mov_b32 m0, s36
	ds_read_b128 v[178:181], v191 offset:16384
	ds_read_b128 v[182:185], v191 offset:17408
	ds_read_b128 v[186:189], v191 offset:18432
	ds_read_b128 v[206:209], v191 offset:19456
	ds_read_b128 v[210:213], v191 offset:20480
	ds_read_b128 v[214:217], v191 offset:21504
	ds_read_b128 v[218:221], v191 offset:22528
	ds_read_b128 v[222:225], v191 offset:23552
	global_load_lds_dwordx4 v[194:195], off
	s_add_i32 m0, s36, 0x2000
	s_add_u32 s36, s14, 0x80000
	v_lshl_add_u64 v[196:197], s[14:15], 0, v[160:161]
	s_addc_u32 s37, s15, 0
	s_add_i32 s40, s40, s18
	global_load_lds_dwordx4 v[196:197], off
	v_lshl_add_u64 v[226:227], s[36:37], 0, v[164:165]
	s_mov_b32 m0, s40
	v_lshl_add_u64 v[228:229], s[16:17], 0, v[162:163]
	global_load_lds_dwordx4 v[226:227], off
	v_lshl_add_u64 v[226:227], s[36:37], 0, v[160:161]
	s_add_i32 m0, s40, 0x2000
	s_nop 0
	global_load_lds_dwordx4 v[226:227], off
	v_lshl_add_u64 v[226:227], s[16:17], 0, v[166:167]
	s_mov_b32 m0, s19
	s_nop 0
	global_load_lds_dwordx4 v[226:227], off
	s_mov_b32 m0, s20
	s_nop 0
	global_load_lds_dwordx4 v[228:229], off
	s_waitcnt vmcnt(8)
	s_waitcnt lgkmcnt(0)
	s_barrier
; #define PG8_STAGE(bufoff, gbase, voff) do { _Pragma("unroll") for (int _i = 0; _i < 2; ++_i) \
;         __builtin_amdgcn_global_load_lds((const unsigned*)((const char*)(gbase) + (voff)[_i]), (LAS unsigned*)(lds + (bufoff) + ldsw + _i * 8192), 16, 0, 0); } while (0)
; #define PG8_LDA(dst, b, h) do { _Pragma("unroll") for (int m = 0; m < 4; ++m) _Pragma("unroll") for (int k = 0; k < 2; ++k) dst[m][k] = *(const LAS bf16x8*)(lds + PG8_SA(b, h) + aoff + m * 2048 + k * 1024); } while (0)
; #define PG8_LDB(dst, b, h) do { _Pragma("unroll") for (int n = 0; n < 2; ++n) _Pragma("unroll") for (int k = 0; k < 2; ++k) dst[n][k] = *(const LAS bf16x8*)(lds + PG8_SB(b, h) + boff + n * 2048 + k * 1024); } while (0)
; #define PG8_MMA(ai, bj, At, Bt) do { __builtin_amdgcn_s_setprio(1); _Pragma("unroll") for (int m = 0; m < 4; ++m) _Pragma("unroll") for (int n = 0; n < 2; ++n) _Pragma("unroll") for (int k = 0; k < 2; ++k) \
;         acc[ai][bj][m][n] = __builtin_amdgcn_mfma_f32_16x16x32_bf16(Bt[n][k], At[m][k], acc[ai][bj][m][n], 0, 0, 0); __builtin_amdgcn_s_setprio(0); } while (0)
; #define PG8_WAIT_V(n) asm volatile("s_waitcnt vmcnt(" #n ")" ::: "memory")
; #define PG8_WAIT_L(n) asm volatile("s_waitcnt lgkmcnt(" #n ")" ::: "memory")
; #define PG8_BAR __builtin_amdgcn_s_barrier()
; #define PG8_SCHED __builtin_amdgcn_sched_barrier(0)
; template <class Epi, bool PERMA = false, bool DUAL = false, bool ALIGN_EPI = true, bool SP2 = true>
; __device__ __forceinline__ void gemm_phase(LAS unsigned char* lds, const Gemm g, const StaticOrder& S, const Epi& E) {
;     ...
;             PG8_WAIT_V(8); PG8_WAIT_L(0); PG8_BAR; PG8_MMA(1, 0, At, B0); PG8_MMA(1, 1, At, B1); PG8_BAR; PG8_SCHED;
;             PG8_LDB(B0, 1, 0); PG8_LDB(B1, 1, 1); PG8_SCHED; PG8_LDA(At, 1, 0); PG8_STAGE(PG8_SA(0, 1), a2 + hstepA, voffA);
;             PG8_WAIT_V(8); PG8_WAIT_L(0); PG8_BAR; PG8_MMA(0, 0, At, B0); PG8_MMA(0, 1, At, B1); PG8_BAR; PG8_SCHED;
	s_waitcnt lgkmcnt(0)
	v_mfma_f32_16x16x32_bf16 v[60:63], v[120:123], v[178:181], v[60:63]
	v_mfma_f32_16x16x32_bf16 v[56:59], v[132:135], v[178:181], v[56:59]
	v_mfma_f32_16x16x32_bf16 v[44:47], v[120:123], v[186:189], v[44:47]
	v_mfma_f32_16x16x32_bf16 v[40:43], v[132:135], v[186:189], v[40:43]
	v_mfma_f32_16x16x32_bf16 v[28:31], v[120:123], v[210:213], v[28:31]
	v_mfma_f32_16x16x32_bf16 v[24:27], v[132:135], v[210:213], v[24:27]
	v_mfma_f32_16x16x32_bf16 v[12:15], v[120:123], v[218:221], v[12:15]
	v_mfma_f32_16x16x32_bf16 v[8:11], v[132:135], v[218:221], v[8:11]
	v_mfma_f32_16x16x32_bf16 v[60:63], v[128:131], v[182:185], v[60:63]
	v_mfma_f32_16x16x32_bf16 v[56:59], v[140:143], v[182:185], v[56:59]
	v_mfma_f32_16x16x32_bf16 v[44:47], v[128:131], v[206:209], v[44:47]
	v_mfma_f32_16x16x32_bf16 v[40:43], v[140:143], v[206:209], v[40:43]
	v_mfma_f32_16x16x32_bf16 v[28:31], v[128:131], v[214:217], v[28:31]
	v_mfma_f32_16x16x32_bf16 v[24:27], v[140:143], v[214:217], v[24:27]
	v_mfma_f32_16x16x32_bf16 v[12:15], v[128:131], v[222:225], v[12:15]
	v_mfma_f32_16x16x32_bf16 v[8:11], v[140:143], v[222:225], v[8:11]
	v_mfma_f32_16x16x32_bf16 v[52:55], v[144:147], v[178:181], v[52:55]
	v_mfma_f32_16x16x32_bf16 v[48:51], v[152:155], v[178:181], v[48:51]
	v_mfma_f32_16x16x32_bf16 v[36:39], v[144:147], v[186:189], v[36:39]
	v_mfma_f32_16x16x32_bf16 v[32:35], v[152:155], v[186:189], v[32:35]
	v_mfma_f32_16x16x32_bf16 v[20:23], v[144:147], v[210:213], v[20:23]
	v_mfma_f32_16x16x32_bf16 v[16:19], v[152:155], v[210:213], v[16:19]
	v_mfma_f32_16x16x32_bf16 v[0:3], v[144:147], v[218:221], v[0:3]
	v_mfma_f32_16x16x32_bf16 v[4:7], v[152:155], v[218:221], v[4:7]
	v_mfma_f32_16x16x32_bf16 v[52:55], v[148:151], v[182:185], v[52:55]
	v_mfma_f32_16x16x32_bf16 v[48:51], v[156:159], v[182:185], v[48:51]
	v_mfma_f32_16x16x32_bf16 v[36:39], v[148:151], v[206:209], v[36:39]
	v_mfma_f32_16x16x32_bf16 v[32:35], v[156:159], v[206:209], v[32:35]
	v_mfma_f32_16x16x32_bf16 v[20:23], v[148:151], v[214:217], v[20:23]
	v_mfma_f32_16x16x32_bf16 v[16:19], v[156:159], v[214:217], v[16:19]
	v_mfma_f32_16x16x32_bf16 v[0:3], v[148:151], v[222:225], v[0:3]
	v_mfma_f32_16x16x32_bf16 v[4:7], v[156:159], v[222:225], v[4:7]
	s_barrier
	s_add_i32 s36, 0, 0x18000
	s_add_i32 s37, 0, 0x1c000
	v_add_u32_e32 v140, s36, v190
	v_add_u32_e32 v156, s37, v190
	ds_read_b128 v[120:123], v140
	ds_read_b128 v[128:131], v140 offset:1024
	ds_read_b128 v[132:135], v140 offset:2048
	ds_read_b128 v[140:143], v140 offset:3072
	ds_read_b128 v[144:147], v156
	ds_read_b128 v[148:151], v156 offset:1024
	ds_read_b128 v[152:155], v156 offset:2048
	ds_read_b128 v[156:159], v156 offset:3072
	s_add_u32 s16, s16, 0x80000
	s_addc_u32 s17, s17, 0
	s_mov_b32 m0, s21
	v_lshl_add_u64 v[238:239], s[16:17], 0, v[166:167]
	ds_read_b128 v[178:181], v191 offset:32768
	ds_read_b128 v[182:185], v191 offset:33792
	ds_read_b128 v[186:189], v191 offset:34816
	ds_read_b128 v[206:209], v191 offset:35840
	ds_read_b128 v[210:213], v191 offset:36864
	ds_read_b128 v[214:217], v191 offset:37888
	ds_read_b128 v[218:221], v191 offset:38912
	ds_read_b128 v[222:225], v191 offset:39936
	global_load_lds_dwordx4 v[238:239], off
	v_lshl_add_u64 v[238:239], s[16:17], 0, v[162:163]
	s_mov_b32 m0, s22
	s_nop 0
	global_load_lds_dwordx4 v[238:239], off
	s_waitcnt vmcnt(8)
	s_waitcnt lgkmcnt(0)
	s_barrier
	s_waitcnt lgkmcnt(0)
	v_mfma_f32_16x16x32_bf16 v[136:139], v[120:123], v[178:181], v[136:139]
	v_mfma_f32_16x16x32_bf16 v[124:127], v[132:135], v[178:181], v[124:127]
	v_mfma_f32_16x16x32_bf16 v[108:111], v[120:123], v[186:189], v[108:111]
	v_mfma_f32_16x16x32_bf16 v[104:107], v[132:135], v[186:189], v[104:107]
	v_mfma_f32_16x16x32_bf16 v[92:95], v[120:123], v[210:213], v[92:95]
	v_mfma_f32_16x16x32_bf16 v[88:91], v[132:135], v[210:213], v[88:91]
	v_mfma_f32_16x16x32_bf16 v[76:79], v[120:123], v[218:221], v[76:79]
	v_mfma_f32_16x16x32_bf16 v[72:75], v[132:135], v[218:221], v[72:75]
	v_mfma_f32_16x16x32_bf16 v[136:139], v[128:131], v[182:185], v[136:139]
	v_mfma_f32_16x16x32_bf16 v[124:127], v[140:143], v[182:185], v[124:127]
	v_mfma_f32_16x16x32_bf16 v[108:111], v[128:131], v[206:209], v[108:111]
	v_mfma_f32_16x16x32_bf16 v[104:107], v[140:143], v[206:209], v[104:107]
	v_mfma_f32_16x16x32_bf16 v[92:95], v[128:131], v[214:217], v[92:95]
	v_mfma_f32_16x16x32_bf16 v[88:91], v[140:143], v[214:217], v[88:91]
	v_mfma_f32_16x16x32_bf16 v[76:79], v[128:131], v[222:225], v[76:79]
	v_mfma_f32_16x16x32_bf16 v[72:75], v[140:143], v[222:225], v[72:75]
	v_mfma_f32_16x16x32_bf16 v[116:119], v[144:147], v[178:181], v[116:119]
	v_mfma_f32_16x16x32_bf16 v[112:115], v[152:155], v[178:181], v[112:115]
	v_mfma_f32_16x16x32_bf16 v[100:103], v[144:147], v[186:189], v[100:103]
	v_mfma_f32_16x16x32_bf16 v[96:99], v[152:155], v[186:189], v[96:99]
	v_mfma_f32_16x16x32_bf16 v[84:87], v[144:147], v[210:213], v[84:87]
	v_mfma_f32_16x16x32_bf16 v[80:83], v[152:155], v[210:213], v[80:83]
	v_mfma_f32_16x16x32_bf16 v[68:71], v[144:147], v[218:221], v[68:71]
	v_mfma_f32_16x16x32_bf16 v[64:67], v[152:155], v[218:221], v[64:67]
	v_mfma_f32_16x16x32_bf16 v[116:119], v[148:151], v[182:185], v[116:119]
	v_mfma_f32_16x16x32_bf16 v[112:115], v[156:159], v[182:185], v[112:115]
	v_mfma_f32_16x16x32_bf16 v[100:103], v[148:151], v[206:209], v[100:103]
	v_mfma_f32_16x16x32_bf16 v[96:99], v[156:159], v[206:209], v[96:99]
	v_mfma_f32_16x16x32_bf16 v[84:87], v[148:151], v[214:217], v[84:87]
	v_mfma_f32_16x16x32_bf16 v[80:83], v[156:159], v[214:217], v[80:83]
	v_mfma_f32_16x16x32_bf16 v[68:71], v[148:151], v[222:225], v[68:71]
	v_mfma_f32_16x16x32_bf16 v[64:67], v[156:159], v[222:225], v[64:67]
	s_barrier
; #define PG8_STAGE(bufoff, gbase, voff) do { _Pragma("unroll") for (int _i = 0; _i < 2; ++_i) \
;         __builtin_amdgcn_global_load_lds((const unsigned*)((const char*)(gbase) + (voff)[_i]), (LAS unsigned*)(lds + (bufoff) + ldsw + _i * 8192), 16, 0, 0); } while (0)
; #define PG8_LDA(dst, b, h) do { _Pragma("unroll") for (int m = 0; m < 4; ++m) _Pragma("unroll") for (int k = 0; k < 2; ++k) dst[m][k] = *(const LAS bf16x8*)(lds + PG8_SA(b, h) + aoff + m * 2048 + k * 1024); } while (0)
; #define PG8_MMA(ai, bj, At, Bt) do { __builtin_amdgcn_s_setprio(1); _Pragma("unroll") for (int m = 0; m < 4; ++m) _Pragma("unroll") for (int n = 0; n < 2; ++n) _Pragma("unroll") for (int k = 0; k < 2; ++k) \
;         acc[ai][bj][m][n] = __builtin_amdgcn_mfma_f32_16x16x32_bf16(Bt[n][k], At[m][k], acc[ai][bj][m][n], 0, 0, 0); __builtin_amdgcn_s_setprio(0); } while (0)
; #define PG8_WAIT_V(n) asm volatile("s_waitcnt vmcnt(" #n ")" ::: "memory")
; #define PG8_WAIT_L(n) asm volatile("s_waitcnt lgkmcnt(" #n ")" ::: "memory")
; #define PG8_BAR __builtin_amdgcn_s_barrier()
; #define PG8_SCHED __builtin_amdgcn_sched_barrier(0)
; template <class Epi, bool PERMA = false, bool DUAL = false, bool ALIGN_EPI = true, bool SP2 = true>
; __device__ __forceinline__ void gemm_phase(LAS unsigned char* lds, const Gemm g, const StaticOrder& S, const Epi& E) {
;     ...
;             PG8_LDA(At, 1, 1); PG8_STAGE(PG8_SB(1, 0), b3, voffB); PG8_STAGE(PG8_SB(1, 1), b3 + hstepB, voffB); PG8_STAGE(PG8_SA(1, 0), a3, voffA);
;             PG8_WAIT_V(8); PG8_WAIT_L(0); PG8_BAR; PG8_MMA(1, 0, At, B0); PG8_MMA(1, 1, At, B1); PG8_BAR; PG8_SCHED;
;     ...
;         if constexpr (ALIGN_EPI) { if (wr == 0) PG8_BAR; }
	s_add_i32 s16, s36, s18
	v_lshl_add_u64 v[194:195], v[194:195], 0, s[46:47]
	s_mov_b32 m0, s16
	ds_read_b128 v[178:181], v191 offset:49152
	ds_read_b128 v[182:185], v191 offset:50176
	ds_read_b128 v[186:189], v191 offset:51200
	ds_read_b128 v[206:209], v191 offset:52224
	ds_read_b128 v[210:213], v191 offset:53248
	ds_read_b128 v[214:217], v191 offset:54272
	ds_read_b128 v[218:221], v191 offset:55296
	ds_read_b128 v[222:225], v191 offset:56320
	global_load_lds_dwordx4 v[194:195], off
	s_add_i32 m0, s16, 0x2000
	s_add_u32 s14, s14, 0x80080
	v_lshl_add_u64 v[194:195], v[196:197], 0, s[46:47]
	s_addc_u32 s15, s15, 0
	s_add_i32 s16, s37, s18
	global_load_lds_dwordx4 v[194:195], off
	v_lshl_add_u64 v[194:195], s[14:15], 0, v[164:165]
	s_mov_b32 m0, s16
	s_nop 0
	global_load_lds_dwordx4 v[194:195], off
	v_lshl_add_u64 v[194:195], s[14:15], 0, v[160:161]
	s_add_i32 m0, s16, 0x2000
	s_nop 0
	global_load_lds_dwordx4 v[194:195], off
	v_lshl_add_u64 v[194:195], v[226:227], 0, s[46:47]
	s_mov_b32 m0, s25
	s_nop 0
	global_load_lds_dwordx4 v[194:195], off
	v_lshl_add_u64 v[194:195], v[228:229], 0, s[46:47]
	s_mov_b32 m0, s26
	s_nop 0
	global_load_lds_dwordx4 v[194:195], off
	s_waitcnt vmcnt(8)
	s_waitcnt lgkmcnt(0)
	s_barrier
	s_waitcnt lgkmcnt(0)
	v_mfma_f32_16x16x32_bf16 v[60:63], v[120:123], v[178:181], v[60:63]
	v_mfma_f32_16x16x32_bf16 v[56:59], v[132:135], v[178:181], v[56:59]
	v_mfma_f32_16x16x32_bf16 v[44:47], v[120:123], v[186:189], v[44:47]
	v_mfma_f32_16x16x32_bf16 v[40:43], v[132:135], v[186:189], v[40:43]
	v_mfma_f32_16x16x32_bf16 v[28:31], v[120:123], v[210:213], v[28:31]
	v_mfma_f32_16x16x32_bf16 v[24:27], v[132:135], v[210:213], v[24:27]
	v_mfma_f32_16x16x32_bf16 v[12:15], v[120:123], v[218:221], v[12:15]
	v_mfma_f32_16x16x32_bf16 v[8:11], v[132:135], v[218:221], v[8:11]
	v_mfma_f32_16x16x32_bf16 v[60:63], v[128:131], v[182:185], v[60:63]
	v_mfma_f32_16x16x32_bf16 v[56:59], v[140:143], v[182:185], v[56:59]
	v_mfma_f32_16x16x32_bf16 v[44:47], v[128:131], v[206:209], v[44:47]
	v_mfma_f32_16x16x32_bf16 v[40:43], v[140:143], v[206:209], v[40:43]
	v_mfma_f32_16x16x32_bf16 v[28:31], v[128:131], v[214:217], v[28:31]
	v_mfma_f32_16x16x32_bf16 v[24:27], v[140:143], v[214:217], v[24:27]
	v_mfma_f32_16x16x32_bf16 v[12:15], v[128:131], v[222:225], v[12:15]
	v_mfma_f32_16x16x32_bf16 v[8:11], v[140:143], v[222:225], v[8:11]
	v_mfma_f32_16x16x32_bf16 v[52:55], v[144:147], v[178:181], v[52:55]
	v_mfma_f32_16x16x32_bf16 v[48:51], v[152:155], v[178:181], v[48:51]
	v_mfma_f32_16x16x32_bf16 v[36:39], v[144:147], v[186:189], v[36:39]
	v_mfma_f32_16x16x32_bf16 v[32:35], v[152:155], v[186:189], v[32:35]
	v_mfma_f32_16x16x32_bf16 v[20:23], v[144:147], v[210:213], v[20:23]
	v_mfma_f32_16x16x32_bf16 v[16:19], v[152:155], v[210:213], v[16:19]
	v_mfma_f32_16x16x32_bf16 v[0:3], v[144:147], v[218:221], v[0:3]
	v_mfma_f32_16x16x32_bf16 v[4:7], v[152:155], v[218:221], v[4:7]
	v_mfma_f32_16x16x32_bf16 v[52:55], v[148:151], v[182:185], v[52:55]
	v_mfma_f32_16x16x32_bf16 v[48:51], v[156:159], v[182:185], v[48:51]
	v_mfma_f32_16x16x32_bf16 v[36:39], v[148:151], v[206:209], v[36:39]
	v_mfma_f32_16x16x32_bf16 v[32:35], v[156:159], v[206:209], v[32:35]
	v_mfma_f32_16x16x32_bf16 v[20:23], v[148:151], v[214:217], v[20:23]
	v_mfma_f32_16x16x32_bf16 v[16:19], v[156:159], v[214:217], v[16:19]
	v_mfma_f32_16x16x32_bf16 v[0:3], v[148:151], v[222:225], v[0:3]
	v_mfma_f32_16x16x32_bf16 v[4:7], v[156:159], v[222:225], v[4:7]
	s_barrier
	s_add_i32 s35, s35, 2
	s_add_u32 s12, s12, 0x100
	s_addc_u32 s13, s13, 0
	s_add_u32 s33, s33, 0x100
	s_addc_u32 s34, s34, 0
	s_cmp_gt_u32 s35, 29
	s_cbranch_scc0 .LBB0_790
	s_and_b64 vcc, exec, s[2:3]
	s_cbranch_vccz .LBB0_793
	s_barrier
